# GEMM mainloops: one static s_setprio 1 for the wave half that enters one barrier late (wr==1), per-MFMA-segment priority toggling removed, priority reset at GEMM exit
# speedup vs baseline: 1.0158x; 1.0136x over previous
.LBB0_101:
	v_ashrrev_i32_e32 v0, 31, v158
	v_lshrrev_b32_e32 v0, 26, v0
	v_add_u32_e32 v0, v158, v0
	s_waitcnt vmcnt(0)
	v_ashrrev_i32_e32 v10, 6, v0
	v_bfe_i32 v0, v158, 27, 1
	v_lshlrev_b32_e32 v2, 4, v158
	v_lshrrev_b32_e32 v0, 22, v0
	v_add_u32_e32 v0, v2, v0
	v_and_b32_e32 v0, 0xfffffc00, v0
	v_sub_u32_e32 v0, v2, v0
	v_lshrrev_b32_e32 v3, 4, v0
	v_bitop3_b32 v3, v3, v0, 32 bitop3:0x6c
	v_ashrrev_i32_e32 v0, 31, v0
	v_lshrrev_b32_e32 v0, 26, v0
	v_lshlrev_b32_e32 v4, 3, v10
	v_add_u32_e32 v0, v3, v0
	v_and_b32_e32 v4, -16, v4
	v_ashrrev_i32_e32 v11, 6, v0
	s_waitcnt lgkmcnt(0)
	s_add_u32 s25, s2, 0xb580000
	v_add_u32_e32 v0, v11, v4
	v_lshlrev_b32_e32 v4, 5, v10
	s_addc_u32 s26, s3, 0
	s_mul_i32 s13, s44, 0x580000
	v_and_b32_e32 v12, 32, v4
	v_mul_i32_i24_e32 v4, 64, v11
	s_mul_hi_i32 s11, s44, 0x580000
	s_add_u32 s27, s8, s13
	v_sub_u32_e32 v3, v3, v4
	s_addc_u32 s28, s9, s11
	v_ashrrev_i16_sdwa v3, v207, sext(v3) dst_sel:DWORD dst_unused:UNUSED_PAD src0_sel:DWORD src1_sel:BYTE_0
	v_lshlrev_b32_e32 v4, 1, v0
	v_lshrrev_b32_e32 v5, 2, v0
	v_and_b32_e32 v6, 3, v11
	s_mov_b32 s9, 0xffffe0
	v_bfe_i32 v13, v3, 0, 16
	v_and_b32_e32 v4, 24, v4
	v_and_b32_e32 v5, 4, v5
	v_and_or_b32 v6, v0, s9, v6
	v_add_u32_e32 v3, v12, v13
	v_or3_b32 v4, v6, v5, v4
	v_mul_lo_u32 v0, v0, s71
	v_add_lshl_u32 v130, v3, v0, 1
	v_mul_u32_u24_e32 v0, 0xb00, v4
	v_add_u32_e32 v2, 0x2000, v2
	v_add_lshl_u32 v0, v0, v3, 1
	v_ashrrev_i32_e32 v3, 31, v2
	v_lshrrev_b32_e32 v3, 22, v3
	s_add_i32 s10, s12, s10
	v_add_u32_e32 v3, v2, v3
	s_ashr_i32 s11, s10, 31
	v_ashrrev_i32_e32 v14, 10, v3
	s_lshr_b32 s11, s11, 27
	v_mul_i32_i24_e32 v3, 0x400, v14
	s_add_i32 s11, s10, s11
	v_sub_u32_e32 v2, v2, v3
	s_ashr_i32 s12, s11, 5
	s_and_b32 s11, s11, 0xffe0
	v_lshrrev_b32_e32 v3, 4, v2
	s_sub_i32 s11, s10, s11
	v_bitop3_b32 v2, v3, v2, 32 bitop3:0x6c
	s_bfe_i32 s10, s11, 0x80000
	v_ashrrev_i32_e32 v4, 31, v2
	s_bfe_u32 s10, s10, 0x3000c
	v_lshrrev_b32_e32 v4, 26, v4
	s_add_i32 s13, s11, s10
	v_lshlrev_b32_e32 v3, 3, v14
	v_add_u32_e32 v4, v2, v4
	s_bfe_i32 s10, s13, 0x80000
	s_and_b32 s13, s13, 0xf8
	v_and_b32_e32 v3, -16, v3
	v_ashrrev_i32_e32 v15, 6, v4
	s_sext_i32_i16 s14, s10
	s_sub_i32 s11, s11, s13
	s_ashr_i32 s8, s1, 6
	v_add_u32_e32 v3, v15, v3
	v_and_b32_e32 v4, 0xc0, v4
	v_and_b32_e32 v6, 3, v15
	s_lshl_b32 s12, s12, 3
	s_sext_i32_i8 s11, s11
	s_ashr_i32 s13, s14, 3
	v_lshlrev_b32_e32 v5, 5, v14
	v_sub_u32_e32 v2, v2, v4
	v_and_or_b32 v6, v3, s9, v6
	s_ashr_i32 s9, s1, 8
	s_lshl_b32 s29, s8, 10
	s_lshr_b32 s10, s14, 3
	s_add_i32 s46, s12, s11
	s_mul_hi_i32 s15, s13, 0x160000
	s_mul_i32 s13, s13, 0x160000
	v_and_b32_e32 v16, 32, v5
	v_ashrrev_i16_sdwa v2, v207, sext(v2) dst_sel:DWORD dst_unused:UNUSED_PAD src0_sel:DWORD src1_sel:BYTE_0
	v_lshlrev_b32_e32 v4, 1, v3
	v_lshrrev_b32_e32 v5, 2, v3
	s_add_u32 s14, s27, s13
	v_bfe_i32 v17, v2, 0, 16
	v_and_b32_e32 v4, 24, v4
	v_and_b32_e32 v5, 4, v5
	s_addc_u32 s15, s28, s15
	s_add_i32 s30, s29, 0
	v_add_u32_e32 v2, v16, v17
	v_or3_b32 v4, v6, v5, v4
	v_mul_lo_u32 v3, v3, s71
	s_add_i32 m0, s30, 0x10000
	v_add_lshl_u32 v132, v2, v3, 1
	v_mul_u32_u24_e32 v3, 0xb00, v4
	s_mul_i32 s12, s46, 0x160000
	global_load_lds_dwordx4 v0, s[14:15]
	s_add_i32 m0, s30, 0x12000
	v_add_lshl_u32 v134, v3, v2, 1
	s_mul_hi_i32 s11, s46, 0x160000
	s_add_u32 s12, s25, s12
	global_load_lds_dwordx4 v134, s[14:15]
	s_addc_u32 s13, s26, s11
	s_mov_b32 m0, s30
	s_add_i32 s31, s30, 0x2000
	global_load_lds_dwordx4 v130, s[12:13]
	s_mov_b32 m0, s31
	s_add_u32 s18, s14, 0xb0000
	global_load_lds_dwordx4 v132, s[12:13]
	s_addc_u32 s19, s15, 0
	s_add_i32 m0, s30, 0x14000
	v_mov_b32_e32 v135, v1
	global_load_lds_dwordx4 v0, s[18:19]
	s_add_i32 m0, s30, 0x16000
	v_mov_b32_e32 v131, v1
	global_load_lds_dwordx4 v134, s[18:19]
	s_add_u32 s18, s12, 0xb0000
	s_addc_u32 s19, s13, 0
	s_add_i32 s34, s30, 0x4000
	s_mov_b32 m0, s34
	s_add_i32 s35, s30, 0x6000
	global_load_lds_dwordx4 v130, s[18:19]
	s_mov_b32 m0, s35
	v_mov_b32_e32 v133, v1
	global_load_lds_dwordx4 v132, s[18:19]
	s_mov_b32 s60, s44
	v_lshl_add_u64 v[8:9], s[14:15], 0, v[0:1]
	v_lshl_add_u64 v[6:7], s[14:15], 0, v[134:135]
	v_lshl_add_u64 v[4:5], s[12:13], 0, v[130:131]
	s_cmp_lg_u32 s9, 1
	v_lshl_add_u64 v[2:3], s[12:13], 0, v[132:133]
	s_cbranch_scc1 .LBB0_103
	s_barrier
	s_setprio 1

.LBB0_115:
	s_add_u32 s14, s12, 0x100
	s_addc_u32 s15, s13, 0
	s_add_i32 s45, 0, 0x10000
	v_add_u32_e32 v148, s45, v141
	ds_read_b128 v[144:147], v148
	ds_read_b128 v[160:163], v148 offset:1024
	ds_read_b128 v[164:167], v148 offset:2048
	ds_read_b128 v[168:171], v148 offset:3072
	s_cmp_eq_u32 s44, 40
	s_cselect_b32 s23, s9, s15
	s_cselect_b32 s22, s8, s14
	s_cselect_b32 s19, s11, s43
	s_cselect_b32 s18, s10, s42
	v_lshl_add_u64 v[148:149], s[12:13], 0, v[138:139]
	s_add_i32 m0, s30, 0xc000
	ds_read_b128 v[172:175], v143
	ds_read_b128 v[176:179], v143 offset:1024
	ds_read_b128 v[180:183], v143 offset:2048
	ds_read_b128 v[184:187], v143 offset:3072
	ds_read_b128 v[188:191], v143 offset:4096
	ds_read_b128 v[192:195], v143 offset:5120
	ds_read_b128 v[196:199], v143 offset:6144
	ds_read_b128 v[200:203], v143 offset:7168
	global_load_lds_dwordx4 v[148:149], off
	v_lshl_add_u64 v[148:149], s[12:13], 0, v[136:137]
	s_add_i32 m0, s30, 0xe000
	s_nop 0
	global_load_lds_dwordx4 v[148:149], off
	s_waitcnt lgkmcnt(8)
	s_barrier
	s_waitcnt lgkmcnt(0)
	s_waitcnt lgkmcnt(0)
	v_mfma_f32_16x16x32_bf16 v[126:129], v[144:147], v[172:175], v[126:129]
	v_mfma_f32_16x16x32_bf16 v[122:125], v[164:167], v[172:175], v[122:125]
	v_mfma_f32_16x16x32_bf16 v[118:121], v[144:147], v[180:183], v[118:121]
	v_mfma_f32_16x16x32_bf16 v[114:117], v[164:167], v[180:183], v[114:117]
	v_mfma_f32_16x16x32_bf16 v[102:105], v[144:147], v[188:191], v[102:105]
	v_mfma_f32_16x16x32_bf16 v[98:101], v[164:167], v[188:191], v[98:101]
	v_mfma_f32_16x16x32_bf16 v[86:89], v[144:147], v[196:199], v[86:89]
	v_mfma_f32_16x16x32_bf16 v[82:85], v[164:167], v[196:199], v[82:85]
	v_mfma_f32_16x16x32_bf16 v[126:129], v[160:163], v[176:179], v[126:129]
	v_mfma_f32_16x16x32_bf16 v[122:125], v[168:171], v[176:179], v[122:125]
	v_mfma_f32_16x16x32_bf16 v[118:121], v[160:163], v[184:187], v[118:121]
	v_mfma_f32_16x16x32_bf16 v[114:117], v[168:171], v[184:187], v[114:117]
	v_mfma_f32_16x16x32_bf16 v[102:105], v[160:163], v[192:195], v[102:105]
	v_mfma_f32_16x16x32_bf16 v[98:101], v[168:171], v[192:195], v[98:101]
	v_mfma_f32_16x16x32_bf16 v[86:89], v[160:163], v[200:203], v[86:89]
	v_mfma_f32_16x16x32_bf16 v[82:85], v[168:171], v[200:203], v[82:85]
	s_barrier
	s_add_i32 s52, 0, 0x14000
	v_add_u32_e32 v148, s52, v141
	s_add_i32 s12, s45, s29
	ds_read_b128 v[234:237], v148
	ds_read_b128 v[238:241], v148 offset:1024
	ds_read_b128 v[242:245], v148 offset:2048
	ds_read_b128 v[246:249], v148 offset:3072
	v_lshl_add_u64 v[148:149], s[18:19], 0, v[0:1]
	s_mov_b32 m0, s12
	v_lshl_add_u64 v[204:205], s[18:19], 0, v[134:135]
	global_load_lds_dwordx4 v[148:149], off
	s_add_i32 m0, s12, 0x2000
	s_nop 0
	global_load_lds_dwordx4 v[204:205], off
	s_barrier
	s_waitcnt lgkmcnt(0)
	s_waitcnt lgkmcnt(0)
	v_mfma_f32_16x16x32_bf16 v[110:113], v[234:237], v[172:175], v[110:113]
	v_mfma_f32_16x16x32_bf16 v[106:109], v[242:245], v[172:175], v[106:109]
	v_mfma_f32_16x16x32_bf16 v[94:97], v[234:237], v[180:183], v[94:97]
	v_mfma_f32_16x16x32_bf16 v[90:93], v[242:245], v[180:183], v[90:93]
	v_mfma_f32_16x16x32_bf16 v[78:81], v[234:237], v[188:191], v[78:81]
	v_mfma_f32_16x16x32_bf16 v[74:77], v[242:245], v[188:191], v[74:77]
	v_mfma_f32_16x16x32_bf16 v[70:73], v[234:237], v[196:199], v[70:73]
	v_mfma_f32_16x16x32_bf16 v[66:69], v[242:245], v[196:199], v[66:69]
	v_mfma_f32_16x16x32_bf16 v[110:113], v[238:241], v[176:179], v[110:113]
	v_mfma_f32_16x16x32_bf16 v[106:109], v[246:249], v[176:179], v[106:109]
	v_mfma_f32_16x16x32_bf16 v[94:97], v[238:241], v[184:187], v[94:97]
	v_mfma_f32_16x16x32_bf16 v[90:93], v[246:249], v[184:187], v[90:93]
	v_mfma_f32_16x16x32_bf16 v[78:81], v[238:241], v[192:195], v[78:81]
	v_mfma_f32_16x16x32_bf16 v[74:77], v[246:249], v[192:195], v[74:77]
	v_mfma_f32_16x16x32_bf16 v[70:73], v[238:241], v[200:203], v[70:73]
	v_mfma_f32_16x16x32_bf16 v[66:69], v[246:249], v[200:203], v[66:69]
	s_mov_b32 m0, s30
	v_lshl_add_u64 v[250:251], s[22:23], 0, v[130:131]
	s_barrier
	ds_read_b128 v[172:175], v143 offset:16384
	ds_read_b128 v[176:179], v143 offset:17408
	ds_read_b128 v[180:183], v143 offset:18432
	ds_read_b128 v[184:187], v143 offset:19456
	ds_read_b128 v[188:191], v143 offset:20480
	ds_read_b128 v[192:195], v143 offset:21504
	ds_read_b128 v[196:199], v143 offset:22528
	ds_read_b128 v[200:203], v143 offset:23552
	global_load_lds_dwordx4 v[250:251], off
	v_lshl_add_u64 v[252:253], s[22:23], 0, v[132:133]
	s_mov_b32 m0, s31
	s_nop 0
	global_load_lds_dwordx4 v[252:253], off
	s_barrier
	s_waitcnt lgkmcnt(0)
	s_waitcnt lgkmcnt(0)
	v_mfma_f32_16x16x32_bf16 v[62:65], v[144:147], v[172:175], v[62:65]
	v_mfma_f32_16x16x32_bf16 v[58:61], v[164:167], v[172:175], v[58:61]
	v_mfma_f32_16x16x32_bf16 v[54:57], v[144:147], v[180:183], v[54:57]
	v_mfma_f32_16x16x32_bf16 v[50:53], v[164:167], v[180:183], v[50:53]
	v_mfma_f32_16x16x32_bf16 v[38:41], v[144:147], v[188:191], v[38:41]
	v_mfma_f32_16x16x32_bf16 v[34:37], v[164:167], v[188:191], v[34:37]
	v_mfma_f32_16x16x32_bf16 v[22:25], v[144:147], v[196:199], v[22:25]
	v_mfma_f32_16x16x32_bf16 v[18:21], v[164:167], v[196:199], v[18:21]
	v_mfma_f32_16x16x32_bf16 v[62:65], v[160:163], v[176:179], v[62:65]
	v_mfma_f32_16x16x32_bf16 v[58:61], v[168:171], v[176:179], v[58:61]
	v_mfma_f32_16x16x32_bf16 v[54:57], v[160:163], v[184:187], v[54:57]
	v_mfma_f32_16x16x32_bf16 v[50:53], v[168:171], v[184:187], v[50:53]
	v_mfma_f32_16x16x32_bf16 v[38:41], v[160:163], v[192:195], v[38:41]
	v_mfma_f32_16x16x32_bf16 v[34:37], v[168:171], v[192:195], v[34:37]
	v_mfma_f32_16x16x32_bf16 v[22:25], v[160:163], v[200:203], v[22:25]
	v_mfma_f32_16x16x32_bf16 v[18:21], v[168:171], v[200:203], v[18:21]
	s_barrier
	s_add_u32 s12, s18, 0xb0000
	s_addc_u32 s13, s19, 0
	s_add_i32 s45, s52, s29
	v_lshl_add_u64 v[144:145], s[12:13], 0, v[0:1]
	s_mov_b32 m0, s45
	s_nop 0
	global_load_lds_dwordx4 v[144:145], off
	v_lshl_add_u64 v[144:145], s[12:13], 0, v[134:135]
	s_add_i32 m0, s45, 0x2000
	s_nop 0
	global_load_lds_dwordx4 v[144:145], off
	s_waitcnt vmcnt(6)
	s_barrier
	v_mfma_f32_16x16x32_bf16 v[46:49], v[234:237], v[172:175], v[46:49]
	v_mfma_f32_16x16x32_bf16 v[42:45], v[242:245], v[172:175], v[42:45]
	v_mfma_f32_16x16x32_bf16 v[30:33], v[234:237], v[180:183], v[30:33]
	v_mfma_f32_16x16x32_bf16 v[26:29], v[242:245], v[180:183], v[26:29]
	v_mfma_f32_16x16x32_bf16 v[14:17], v[234:237], v[188:191], v[14:17]
	v_mfma_f32_16x16x32_bf16 v[10:13], v[242:245], v[188:191], v[10:13]
	v_mfma_f32_16x16x32_bf16 v[6:9], v[234:237], v[196:199], v[6:9]
	v_mfma_f32_16x16x32_bf16 v[2:5], v[242:245], v[196:199], v[2:5]
	v_mfma_f32_16x16x32_bf16 v[46:49], v[238:241], v[176:179], v[46:49]
	v_mfma_f32_16x16x32_bf16 v[42:45], v[246:249], v[176:179], v[42:45]
	v_mfma_f32_16x16x32_bf16 v[30:33], v[238:241], v[184:187], v[30:33]
	v_mfma_f32_16x16x32_bf16 v[26:29], v[246:249], v[184:187], v[26:29]
	v_mfma_f32_16x16x32_bf16 v[14:17], v[238:241], v[192:195], v[14:17]
	v_mfma_f32_16x16x32_bf16 v[10:13], v[246:249], v[192:195], v[10:13]
	v_mfma_f32_16x16x32_bf16 v[6:9], v[238:241], v[200:203], v[6:9]
	v_mfma_f32_16x16x32_bf16 v[2:5], v[246:249], v[200:203], v[2:5]
	s_add_i32 s45, 0, 0x18000
	v_add_u32_e32 v159, s45, v141
	s_barrier
	ds_read_b128 v[144:147], v159
	ds_read_b128 v[160:163], v159 offset:1024
	ds_read_b128 v[164:167], v159 offset:2048
	ds_read_b128 v[168:171], v159 offset:3072
	s_add_u32 s12, s22, 0xb0000
	s_addc_u32 s13, s23, 0
	s_mov_b32 m0, s34
	v_lshl_add_u64 v[234:235], s[12:13], 0, v[130:131]
	ds_read_b128 v[172:175], v143 offset:32768
	ds_read_b128 v[176:179], v143 offset:33792
	ds_read_b128 v[180:183], v143 offset:34816
	ds_read_b128 v[184:187], v143 offset:35840
	ds_read_b128 v[188:191], v143 offset:36864
	ds_read_b128 v[192:195], v143 offset:37888
	ds_read_b128 v[196:199], v143 offset:38912
	ds_read_b128 v[200:203], v143 offset:39936
	global_load_lds_dwordx4 v[234:235], off
	v_lshl_add_u64 v[234:235], s[12:13], 0, v[132:133]
	s_mov_b32 m0, s35
	s_nop 0
	global_load_lds_dwordx4 v[234:235], off
	s_waitcnt lgkmcnt(8)
	s_barrier
	s_waitcnt lgkmcnt(0)
	s_waitcnt lgkmcnt(0)
	v_mfma_f32_16x16x32_bf16 v[126:129], v[144:147], v[172:175], v[126:129]
	v_mfma_f32_16x16x32_bf16 v[122:125], v[164:167], v[172:175], v[122:125]
	v_mfma_f32_16x16x32_bf16 v[118:121], v[144:147], v[180:183], v[118:121]
	v_mfma_f32_16x16x32_bf16 v[114:117], v[164:167], v[180:183], v[114:117]
	v_mfma_f32_16x16x32_bf16 v[102:105], v[144:147], v[188:191], v[102:105]
	v_mfma_f32_16x16x32_bf16 v[98:101], v[164:167], v[188:191], v[98:101]
	v_mfma_f32_16x16x32_bf16 v[86:89], v[144:147], v[196:199], v[86:89]
	v_mfma_f32_16x16x32_bf16 v[82:85], v[164:167], v[196:199], v[82:85]
	v_mfma_f32_16x16x32_bf16 v[126:129], v[160:163], v[176:179], v[126:129]
	v_mfma_f32_16x16x32_bf16 v[122:125], v[168:171], v[176:179], v[122:125]
	v_mfma_f32_16x16x32_bf16 v[118:121], v[160:163], v[184:187], v[118:121]
	v_mfma_f32_16x16x32_bf16 v[114:117], v[168:171], v[184:187], v[114:117]
	v_mfma_f32_16x16x32_bf16 v[102:105], v[160:163], v[192:195], v[102:105]
	v_mfma_f32_16x16x32_bf16 v[98:101], v[168:171], v[192:195], v[98:101]
	v_mfma_f32_16x16x32_bf16 v[86:89], v[160:163], v[200:203], v[86:89]
	v_mfma_f32_16x16x32_bf16 v[82:85], v[168:171], v[200:203], v[82:85]
	s_barrier
	s_add_i32 s22, 0, 0x1c000
	s_add_i32 s12, s45, s29
	v_add_u32_e32 v159, s22, v141
	v_lshl_add_u64 v[148:149], v[148:149], 0, s[20:21]
	s_mov_b32 m0, s12
	ds_read_b128 v[234:237], v159
	ds_read_b128 v[238:241], v159 offset:1024
	ds_read_b128 v[242:245], v159 offset:2048
	ds_read_b128 v[246:249], v159 offset:3072
	global_load_lds_dwordx4 v[148:149], off
	v_lshl_add_u64 v[148:149], v[204:205], 0, s[20:21]
	s_add_i32 m0, s12, 0x2000
	s_nop 0
	global_load_lds_dwordx4 v[148:149], off
	s_barrier
	s_waitcnt lgkmcnt(0)
	s_waitcnt lgkmcnt(0)
	v_mfma_f32_16x16x32_bf16 v[110:113], v[234:237], v[172:175], v[110:113]
	v_mfma_f32_16x16x32_bf16 v[106:109], v[242:245], v[172:175], v[106:109]
	v_mfma_f32_16x16x32_bf16 v[94:97], v[234:237], v[180:183], v[94:97]
	v_mfma_f32_16x16x32_bf16 v[90:93], v[242:245], v[180:183], v[90:93]
	v_mfma_f32_16x16x32_bf16 v[78:81], v[234:237], v[188:191], v[78:81]
	v_mfma_f32_16x16x32_bf16 v[74:77], v[242:245], v[188:191], v[74:77]
	v_mfma_f32_16x16x32_bf16 v[70:73], v[234:237], v[196:199], v[70:73]
	v_mfma_f32_16x16x32_bf16 v[66:69], v[242:245], v[196:199], v[66:69]
	v_mfma_f32_16x16x32_bf16 v[110:113], v[238:241], v[176:179], v[110:113]
	v_mfma_f32_16x16x32_bf16 v[106:109], v[246:249], v[176:179], v[106:109]
	v_mfma_f32_16x16x32_bf16 v[94:97], v[238:241], v[184:187], v[94:97]
	v_mfma_f32_16x16x32_bf16 v[90:93], v[246:249], v[184:187], v[90:93]
	v_mfma_f32_16x16x32_bf16 v[78:81], v[238:241], v[192:195], v[78:81]
	v_mfma_f32_16x16x32_bf16 v[74:77], v[246:249], v[192:195], v[74:77]
	v_mfma_f32_16x16x32_bf16 v[70:73], v[238:241], v[200:203], v[70:73]
	v_mfma_f32_16x16x32_bf16 v[66:69], v[246:249], v[200:203], v[66:69]
	s_mov_b32 m0, s38
	v_lshl_add_u64 v[148:149], v[250:251], 0, s[20:21]
	s_barrier
	ds_read_b128 v[172:175], v143 offset:49152
	ds_read_b128 v[176:179], v143 offset:50176
	ds_read_b128 v[180:183], v143 offset:51200
	ds_read_b128 v[184:187], v143 offset:52224
	ds_read_b128 v[188:191], v143 offset:53248
	ds_read_b128 v[192:195], v143 offset:54272
	ds_read_b128 v[196:199], v143 offset:55296
	ds_read_b128 v[200:203], v143 offset:56320
	global_load_lds_dwordx4 v[148:149], off
	v_lshl_add_u64 v[148:149], v[252:253], 0, s[20:21]
	s_mov_b32 m0, s39
	s_nop 0
	global_load_lds_dwordx4 v[148:149], off
	s_barrier
	s_waitcnt lgkmcnt(0)
	s_waitcnt lgkmcnt(0)
	v_mfma_f32_16x16x32_bf16 v[62:65], v[144:147], v[172:175], v[62:65]
	v_mfma_f32_16x16x32_bf16 v[58:61], v[164:167], v[172:175], v[58:61]
	v_mfma_f32_16x16x32_bf16 v[54:57], v[144:147], v[180:183], v[54:57]
	v_mfma_f32_16x16x32_bf16 v[50:53], v[164:167], v[180:183], v[50:53]
	v_mfma_f32_16x16x32_bf16 v[38:41], v[144:147], v[188:191], v[38:41]
	v_mfma_f32_16x16x32_bf16 v[34:37], v[164:167], v[188:191], v[34:37]
	v_mfma_f32_16x16x32_bf16 v[22:25], v[144:147], v[196:199], v[22:25]
	v_mfma_f32_16x16x32_bf16 v[18:21], v[164:167], v[196:199], v[18:21]
	v_mfma_f32_16x16x32_bf16 v[62:65], v[160:163], v[176:179], v[62:65]
	v_mfma_f32_16x16x32_bf16 v[58:61], v[168:171], v[176:179], v[58:61]
	v_mfma_f32_16x16x32_bf16 v[54:57], v[160:163], v[184:187], v[54:57]
	v_mfma_f32_16x16x32_bf16 v[50:53], v[168:171], v[184:187], v[50:53]
	v_mfma_f32_16x16x32_bf16 v[38:41], v[160:163], v[192:195], v[38:41]
	v_mfma_f32_16x16x32_bf16 v[34:37], v[168:171], v[192:195], v[34:37]
	v_mfma_f32_16x16x32_bf16 v[22:25], v[160:163], v[200:203], v[22:25]
	v_mfma_f32_16x16x32_bf16 v[18:21], v[168:171], v[200:203], v[18:21]
	s_barrier
	s_add_u32 s12, s18, 0xb0080
	s_addc_u32 s13, s19, 0
	s_add_i32 s18, s22, s29
	v_lshl_add_u64 v[144:145], s[12:13], 0, v[0:1]
	s_mov_b32 m0, s18
	s_nop 0
	global_load_lds_dwordx4 v[144:145], off
	v_lshl_add_u64 v[144:145], s[12:13], 0, v[134:135]
	s_add_i32 m0, s18, 0x2000
	s_nop 0
	global_load_lds_dwordx4 v[144:145], off
	s_waitcnt vmcnt(6)
	s_barrier
	v_mfma_f32_16x16x32_bf16 v[46:49], v[234:237], v[172:175], v[46:49]
	v_mfma_f32_16x16x32_bf16 v[42:45], v[242:245], v[172:175], v[42:45]
	v_mfma_f32_16x16x32_bf16 v[30:33], v[234:237], v[180:183], v[30:33]
	v_mfma_f32_16x16x32_bf16 v[26:29], v[242:245], v[180:183], v[26:29]
	v_mfma_f32_16x16x32_bf16 v[14:17], v[234:237], v[188:191], v[14:17]
	v_mfma_f32_16x16x32_bf16 v[10:13], v[242:245], v[188:191], v[10:13]
	v_mfma_f32_16x16x32_bf16 v[6:9], v[234:237], v[196:199], v[6:9]
	v_mfma_f32_16x16x32_bf16 v[2:5], v[242:245], v[196:199], v[2:5]
	v_mfma_f32_16x16x32_bf16 v[46:49], v[238:241], v[176:179], v[46:49]
	v_mfma_f32_16x16x32_bf16 v[42:45], v[246:249], v[176:179], v[42:45]
	v_mfma_f32_16x16x32_bf16 v[30:33], v[238:241], v[184:187], v[30:33]
	v_mfma_f32_16x16x32_bf16 v[26:29], v[246:249], v[184:187], v[26:29]
	v_mfma_f32_16x16x32_bf16 v[14:17], v[238:241], v[192:195], v[14:17]
	v_mfma_f32_16x16x32_bf16 v[10:13], v[246:249], v[192:195], v[10:13]
	v_mfma_f32_16x16x32_bf16 v[6:9], v[238:241], v[200:203], v[6:9]
	v_mfma_f32_16x16x32_bf16 v[2:5], v[246:249], v[200:203], v[2:5]
	s_add_i32 s44, s44, 2
	s_add_u32 s42, s42, 0x100
	s_addc_u32 s43, s43, 0
	s_cmp_gt_u32 s44, 41
	s_mov_b64 s[12:13], s[14:15]
	s_barrier
	s_cbranch_scc0 .LBB0_115
	v_lshl_add_u32 v144, s46, 8, v140
	v_lshl_or_b32 v146, s49, 8, v142
	v_ashrrev_i32_e32 v147, 31, v146
	v_ashrrev_i32_e32 v145, 31, v144
	v_lshl_add_u64 v[146:147], v[146:147], 1, s[2:3]
	v_lshlrev_b64 v[148:149], 11, v[144:145]
	v_lshl_add_u64 v[148:149], v[146:147], 0, v[148:149]
	s_mov_b64 s[12:13], 0x40000
	v_cvt_pk_bf16_f32 v62, v62, v63
	v_cvt_pk_bf16_f32 v63, v64, v65
	v_cvt_pk_bf16_f32 v64, v58, v59
	v_add_co_u32_e32 v58, vcc, s79, v148
	v_cvt_pk_bf16_f32 v70, v70, v71
	v_cvt_pk_bf16_f32 v71, v72, v73
	v_cvt_pk_bf16_f32 v72, v66, v67
	v_lshl_add_u64 v[66:67], v[148:149], 0, s[12:13]
	v_addc_co_u32_e32 v59, vcc, 0, v149, vcc
	v_cvt_pk_bf16_f32 v46, v46, v47
	v_cvt_pk_bf16_f32 v47, v48, v49
	v_cvt_pk_bf16_f32 v48, v42, v43
	v_cvt_pk_bf16_f32 v49, v44, v45
	global_store_dwordx4 v[66:67], v[46:49], off offset:256
	s_mov_b64 s[12:13], 0x48000
	v_cvt_pk_bf16_f32 v110, v110, v111
	v_add_co_u32_e32 v48, vcc, s91, v148
	v_cvt_pk_bf16_f32 v111, v112, v113
	v_cvt_pk_bf16_f32 v112, v106, v107
	v_or_b32_e32 v106, 16, v144
	v_lshl_add_u64 v[46:47], v[148:149], 0, s[12:13]
	v_addc_co_u32_e32 v49, vcc, 0, v149, vcc
	v_cvt_pk_bf16_f32 v30, v30, v31
	v_cvt_pk_bf16_f32 v31, v32, v33
	v_cvt_pk_bf16_f32 v32, v26, v27
	v_cvt_pk_bf16_f32 v33, v28, v29
	v_ashrrev_i32_e32 v107, 31, v106
	v_cvt_pk_bf16_f32 v94, v94, v95
	v_cvt_pk_bf16_f32 v95, v96, v97
	v_cvt_pk_bf16_f32 v96, v90, v91
	v_or_b32_e32 v90, 32, v144
	global_store_dwordx4 v[46:47], v[30:33], off offset:256
	s_mov_b64 s[12:13], 0x50000
	v_cvt_pk_bf16_f32 v113, v108, v109
	v_add_co_u32_e32 v32, vcc, s92, v148
	v_lshlrev_b64 v[106:107], 11, v[106:107]
	v_ashrrev_i32_e32 v91, 31, v90
	v_cvt_pk_bf16_f32 v78, v78, v79
	v_cvt_pk_bf16_f32 v79, v80, v81
	v_cvt_pk_bf16_f32 v80, v74, v75
	v_or_b32_e32 v74, 48, v144
	v_lshl_add_u64 v[30:31], v[148:149], 0, s[12:13]
	v_addc_co_u32_e32 v33, vcc, 0, v149, vcc
	v_cvt_pk_bf16_f32 v14, v14, v15
	v_cvt_pk_bf16_f32 v15, v16, v17
	v_cvt_pk_bf16_f32 v16, v10, v11
	v_cvt_pk_bf16_f32 v17, v12, v13
	global_store_dwordx4 v[148:149], v[110:113], off offset:256
	v_cvt_pk_bf16_f32 v97, v92, v93
	v_lshlrev_b64 v[90:91], 11, v[90:91]
	v_lshl_add_u64 v[110:111], v[146:147], 0, v[106:107]
	v_ashrrev_i32_e32 v75, 31, v74
	global_store_dwordx4 v[30:31], v[14:17], off offset:256
	global_store_dwordx4 v[110:111], v[94:97], off offset:256
	v_cvt_pk_bf16_f32 v81, v76, v77
	v_add_co_u32_e32 v16, vcc, 0x58000, v148
	v_lshl_add_u64 v[94:95], v[146:147], 0, v[90:91]
	v_lshlrev_b64 v[74:75], 11, v[74:75]
	s_mov_b64 s[12:13], 0x58000
	v_addc_co_u32_e32 v17, vcc, 0, v149, vcc
	v_cvt_pk_bf16_f32 v126, v126, v127
	v_cvt_pk_bf16_f32 v127, v128, v129
	v_cvt_pk_bf16_f32 v128, v122, v123
	v_cvt_pk_bf16_f32 v129, v124, v125
	v_cvt_pk_bf16_f32 v106, v118, v119
	v_cvt_pk_bf16_f32 v107, v120, v121
	v_cvt_pk_bf16_f32 v108, v114, v115
	v_cvt_pk_bf16_f32 v109, v116, v117
	v_cvt_pk_bf16_f32 v90, v102, v103
	v_cvt_pk_bf16_f32 v91, v104, v105
	v_cvt_pk_bf16_f32 v92, v98, v99
	v_cvt_pk_bf16_f32 v93, v100, v101
	global_store_dwordx4 v[94:95], v[78:81], off offset:256
	v_cvt_pk_bf16_f32 v76, v82, v83
	v_cvt_pk_bf16_f32 v77, v84, v85
	v_lshl_add_u64 v[78:79], v[146:147], 0, v[74:75]
	v_cvt_pk_bf16_f32 v74, v86, v87
	v_cvt_pk_bf16_f32 v75, v88, v89
	v_cvt_pk_bf16_f32 v73, v68, v69
	v_cvt_pk_bf16_f32 v65, v60, v61
	v_cvt_pk_bf16_f32 v42, v54, v55
	v_cvt_pk_bf16_f32 v43, v56, v57
	v_cvt_pk_bf16_f32 v44, v50, v51
	v_cvt_pk_bf16_f32 v45, v52, v53
	v_cvt_pk_bf16_f32 v26, v38, v39
	v_cvt_pk_bf16_f32 v27, v40, v41
	v_cvt_pk_bf16_f32 v28, v34, v35
	v_cvt_pk_bf16_f32 v29, v36, v37
	v_lshl_add_u64 v[14:15], v[148:149], 0, s[12:13]
	v_cvt_pk_bf16_f32 v10, v22, v23
	v_cvt_pk_bf16_f32 v11, v24, v25
	v_cvt_pk_bf16_f32 v12, v18, v19
	v_cvt_pk_bf16_f32 v13, v20, v21
	v_cvt_pk_bf16_f32 v6, v6, v7
	v_cvt_pk_bf16_f32 v7, v8, v9
	v_cvt_pk_bf16_f32 v8, v2, v3
	v_cvt_pk_bf16_f32 v9, v4, v5
	s_and_b64 vcc, exec, s[40:41]
	s_mov_b32 s49, s50
	s_mov_b32 s46, s51
	s_mov_b64 s[14:15], s[10:11]
	s_mov_b64 s[12:13], s[8:9]
	global_store_dwordx4 v[148:149], v[126:129], off
	global_store_dwordx4 v[110:111], v[106:109], off
	global_store_dwordx4 v[94:95], v[90:93], off
	global_store_dwordx4 v[78:79], v[74:77], off
	global_store_dwordx4 v[78:79], v[70:73], off offset:256
	global_store_dwordx4 v[58:59], v[62:65], off
	global_store_dwordx4 v[48:49], v[42:45], off
	global_store_dwordx4 v[32:33], v[26:29], off
	global_store_dwordx4 v[16:17], v[10:13], off
	global_store_dwordx4 v[14:15], v[6:9], off offset:256
	s_cbranch_vccz .LBB0_104
	s_waitcnt vmcnt(0)
	s_setprio 0
	s_cmpk_gt_u32 s1, 0xff
	s_cbranch_scc1 .LBB0_119
	s_barrier

.LBB0_168:
	s_cmp_lt_i32 s57, 7
	s_mov_b64 s[2:3], -1
	s_mov_b32 s66, s56
	s_cbranch_scc1 .LBB0_270
	s_cmp_gt_i32 s57, 7
	s_cbranch_scc0 .LBB0_183
	s_add_i32 s1, s86, -13
	s_cmp_lt_u32 s1, 12
	s_cselect_b32 s1, 0x80, s17
	s_mul_i32 s76, s1, 22
	s_cmp_ge_i32 s0, s76
	v_readfirstlane_b32 s26, v158
	s_cbranch_scc1 .LBB0_182
	v_lshlrev_b32_e32 v0, 4, v158
	s_waitcnt vmcnt(0)
	v_add_u32_e32 v2, 0x2000, v0
	v_ashrrev_i32_e32 v3, 31, v2
	v_lshrrev_b32_e32 v3, 22, v3
	v_add_u32_e32 v3, v2, v3
	v_ashrrev_i32_e32 v10, 10, v3
	v_mul_i32_i24_e32 v3, 0x400, v10
	v_sub_u32_e32 v2, v2, v3
	v_lshrrev_b32_e32 v3, 4, v2
	v_bitop3_b32 v2, v3, v2, 32 bitop3:0x6c
	s_load_dwordx2 s[2:3], s[54:55], 0x118
	v_ashrrev_i32_e32 v3, 31, v2
	v_lshrrev_b32_e32 v3, 26, v3
	v_add_u32_e32 v3, v2, v3
	v_lshlrev_b32_e32 v4, 3, v10
	s_mov_b32 s10, s44
	v_ashrrev_i32_e32 v11, 6, v3
	v_and_b32_e32 v4, -16, v4
	s_mul_i32 s9, s10, 0xb00000
	v_add_u32_e32 v4, v11, v4
	s_load_dwordx4 s[44:47], s[54:55], 0x158
	s_waitcnt lgkmcnt(0)
	s_add_u32 s27, s2, s9
	v_and_b32_e32 v5, 3, v11
	s_mov_b32 s2, 0x1fffe0
	v_lshrrev_b32_e32 v6, 2, v4
	v_lshlrev_b32_e32 v7, 1, v4
	v_and_b32_e32 v3, 0xc0, v3
	v_and_or_b32 v5, v4, s2, v5
	v_and_b32_e32 v6, 4, v6
	v_and_b32_e32 v7, 24, v7
	v_sub_u32_e32 v2, v2, v3
	v_or3_b32 v5, v5, v6, v7
	v_lshlrev_b32_e32 v6, 5, v10
	v_ashrrev_i16_sdwa v2, v207, sext(v2) dst_sel:DWORD dst_unused:UNUSED_PAD src0_sel:DWORD src1_sel:BYTE_0
	v_and_b32_e32 v6, 32, v6
	v_bfe_i32 v12, v2, 0, 16
	v_add_lshl_u32 v2, v6, v12, 1
	v_lshl_add_u32 v130, v5, 11, v2
	v_lshl_add_u32 v132, v4, 11, v2
	v_bfe_i32 v2, v158, 27, 1
	v_lshrrev_b32_e32 v2, 22, v2
	v_add_u32_e32 v2, v0, v2
	v_and_b32_e32 v2, 0xfffffc00, v2
	v_sub_u32_e32 v0, v0, v2
	v_lshrrev_b32_e32 v2, 4, v0
	v_bitop3_b32 v2, v2, v0, 32 bitop3:0x6c
	v_ashrrev_i32_e32 v0, 31, v0
	v_lshrrev_b32_e32 v0, 26, v0
	v_add_u32_e32 v0, v2, v0
	v_ashrrev_i32_e32 v13, 6, v0
	v_ashrrev_i32_e32 v0, 31, v158
	v_lshrrev_b32_e32 v0, 26, v0
	v_add_u32_e32 v0, v158, v0
	v_ashrrev_i32_e32 v14, 6, v0
	v_lshlrev_b32_e32 v0, 3, v14
	s_mul_hi_i32 s8, s10, 0xb00000
	v_and_b32_e32 v0, -16, v0
	s_addc_u32 s28, s3, s8
	v_add_u32_e32 v3, v13, v0
	v_and_b32_e32 v0, 3, v13
	s_ashr_i32 s31, s0, 31
	v_and_or_b32 v0, v3, s2, v0
	s_lshr_b32 s2, s31, 29
	s_add_i32 s2, s0, s2
	s_ashr_i32 s9, s26, 6
	s_lshr_b32 s30, s76, 3
	s_ashr_i32 s3, s2, 3
	s_and_b32 s2, s2, -8
	s_mov_b32 s62, s10
	s_ashr_i32 s10, s26, 8
	s_lshl_b32 s29, s9, 10
	s_sub_i32 s2, s0, s2
	s_add_i32 s34, s30, 1
	s_cmp_lt_i32 s2, 0
	s_cselect_b32 s8, s34, s30
	s_mul_i32 s2, s8, s2
	s_add_i32 s2, s2, s3
	s_mul_hi_i32 s3, s2, 0x2e8ba2e9
	v_lshrrev_b32_e32 v4, 2, v3
	v_lshlrev_b32_e32 v5, 1, v3
	s_lshr_b32 s8, s3, 31
	s_ashr_i32 s3, s3, 5
	v_and_b32_e32 v4, 4, v4
	v_and_b32_e32 v5, 24, v5
	s_add_i32 s3, s3, s8
	v_or3_b32 v0, v0, v4, v5
	v_mul_i32_i24_e32 v5, 64, v13
	s_lshl_b32 s11, s3, 3
	v_sub_u32_e32 v2, v2, v5
	s_sub_i32 s8, s1, s11
	v_lshlrev_b32_e32 v4, 5, v14
	v_ashrrev_i16_sdwa v2, v207, sext(v2) dst_sel:DWORD dst_unused:UNUSED_PAD src0_sel:DWORD src1_sel:BYTE_0
	s_min_u32 s12, s8, 8
	s_mulk_i32 s3, 0xb0
	v_and_b32_e32 v4, 32, v4
	v_bfe_i32 v15, v2, 0, 16
	s_sub_i32 s13, s2, s3
	v_cvt_f32_ubyte0_e32 v5, s12
	v_add_lshl_u32 v2, v4, v15, 1
	v_cvt_f32_i32_e32 v4, s13
	v_rcp_iflag_f32_e32 v6, v5
	v_lshl_add_u32 v0, v0, 11, v2
	v_lshl_add_u32 v134, v3, 11, v2
	s_ashr_i32 s2, s13, 30
	v_mul_f32_e32 v2, v4, v6
	v_trunc_f32_e32 v2, v2
	v_fma_f32 v3, -v2, v5, v4
	v_cvt_i32_f32_e32 v2, v2
	s_or_b32 s8, s2, 1
	v_cmp_ge_f32_e64 s[2:3], |v3|, v5
	s_and_b64 s[2:3], s[2:3], exec
	s_cselect_b32 s2, s8, 0
	v_readfirstlane_b32 s3, v2
	s_add_i32 s8, s3, s2
	s_mul_i32 s2, s8, s12
	s_sub_i32 s2, s13, s2
	s_sext_i32_i16 s2, s2
	s_add_i32 s2, s11, s2
	s_ashr_i32 s3, s2, 31
	s_bfe_i64 s[14:15], s[8:9], 0x100000
	s_lshl_b64 s[12:13], s[2:3], 19
	s_lshl_b64 s[14:15], s[14:15], 19
	s_add_u32 s18, s27, s14
	s_addc_u32 s19, s28, s15
	s_add_i32 s3, s29, 0
	s_add_i32 m0, s3, 0x10000
	v_mov_b32_e32 v131, v1
	global_load_lds_dwordx4 v0, s[18:19]
	s_add_i32 m0, s3, 0x12000
	s_add_u32 s22, s44, s12
	global_load_lds_dwordx4 v130, s[18:19]
	s_addc_u32 s23, s45, s13
	s_mov_b32 m0, s3
	s_add_i32 s35, s3, 0x2000
	global_load_lds_dwordx4 v134, s[22:23]
	s_mov_b32 m0, s35
	s_add_u32 s12, s18, 0x40000
	global_load_lds_dwordx4 v132, s[22:23]
	s_addc_u32 s13, s19, 0
	s_add_i32 m0, s3, 0x14000
	v_mov_b32_e32 v135, v1
	global_load_lds_dwordx4 v0, s[12:13]
	s_add_i32 m0, s3, 0x16000
	v_mov_b32_e32 v133, v1
	global_load_lds_dwordx4 v130, s[12:13]
	s_add_u32 s12, s22, 0x40000
	s_addc_u32 s13, s23, 0
	s_add_i32 s38, s3, 0x4000
	s_mov_b32 m0, s38
	s_add_i32 s39, s3, 0x6000
	global_load_lds_dwordx4 v134, s[12:13]
	s_mov_b32 m0, s39
	s_mov_b32 s60, s57
	global_load_lds_dwordx4 v132, s[12:13]
	v_lshl_add_u64 v[8:9], s[18:19], 0, v[0:1]
	v_lshl_add_u64 v[6:7], s[18:19], 0, v[130:131]
	v_lshl_add_u64 v[4:5], s[22:23], 0, v[134:135]
	s_cmp_lg_u32 s10, 1
	v_lshl_add_u64 v[2:3], s[22:23], 0, v[132:133]
	s_cbranch_scc1 .LBB0_173
	s_barrier
	s_setprio 1

.LBB0_177:
	s_add_u32 s22, s18, 0xfffc0080
	s_addc_u32 s23, s19, -1
	s_add_i32 s56, 0, 0x10000
	v_add_u32_e32 v148, s56, v141
	ds_read_b128 v[144:147], v148
	ds_read_b128 v[160:163], v148 offset:1024
	ds_read_b128 v[164:167], v148 offset:2048
	ds_read_b128 v[168:171], v148 offset:3072
	s_cmp_eq_u32 s55, 12
	s_cselect_b32 s25, s11, s23
	s_cselect_b32 s24, s51, s22
	s_cselect_b32 s23, s9, s54
	s_cselect_b32 s22, s52, s53
	v_lshl_add_u64 v[148:149], s[18:19], 0, v[138:139]
	s_add_i32 m0, s3, 0xc000
	ds_read_b128 v[172:175], v143
	ds_read_b128 v[176:179], v143 offset:1024
	ds_read_b128 v[180:183], v143 offset:2048
	ds_read_b128 v[184:187], v143 offset:3072
	ds_read_b128 v[188:191], v143 offset:4096
	ds_read_b128 v[192:195], v143 offset:5120
	ds_read_b128 v[196:199], v143 offset:6144
	ds_read_b128 v[200:203], v143 offset:7168
	global_load_lds_dwordx4 v[148:149], off
	v_lshl_add_u64 v[148:149], s[18:19], 0, v[136:137]
	s_add_i32 m0, s3, 0xe000
	s_nop 0
	global_load_lds_dwordx4 v[148:149], off
	s_waitcnt lgkmcnt(8)
	s_barrier
	s_waitcnt lgkmcnt(0)
	s_waitcnt lgkmcnt(0)
	v_mfma_f32_16x16x32_bf16 v[126:129], v[144:147], v[172:175], v[126:129]
	v_mfma_f32_16x16x32_bf16 v[122:125], v[164:167], v[172:175], v[122:125]
	v_mfma_f32_16x16x32_bf16 v[118:121], v[144:147], v[180:183], v[118:121]
	v_mfma_f32_16x16x32_bf16 v[114:117], v[164:167], v[180:183], v[114:117]
	v_mfma_f32_16x16x32_bf16 v[102:105], v[144:147], v[188:191], v[102:105]
	v_mfma_f32_16x16x32_bf16 v[98:101], v[164:167], v[188:191], v[98:101]
	v_mfma_f32_16x16x32_bf16 v[86:89], v[144:147], v[196:199], v[86:89]
	v_mfma_f32_16x16x32_bf16 v[82:85], v[164:167], v[196:199], v[82:85]
	v_mfma_f32_16x16x32_bf16 v[126:129], v[160:163], v[176:179], v[126:129]
	v_mfma_f32_16x16x32_bf16 v[122:125], v[168:171], v[176:179], v[122:125]
	v_mfma_f32_16x16x32_bf16 v[118:121], v[160:163], v[184:187], v[118:121]
	v_mfma_f32_16x16x32_bf16 v[114:117], v[168:171], v[184:187], v[114:117]
	v_mfma_f32_16x16x32_bf16 v[102:105], v[160:163], v[192:195], v[102:105]
	v_mfma_f32_16x16x32_bf16 v[98:101], v[168:171], v[192:195], v[98:101]
	v_mfma_f32_16x16x32_bf16 v[86:89], v[160:163], v[200:203], v[86:89]
	v_mfma_f32_16x16x32_bf16 v[82:85], v[168:171], v[200:203], v[82:85]
	s_barrier
	s_add_i32 s58, 0, 0x14000
	v_add_u32_e32 v148, s58, v141
	s_add_i32 s56, s56, s29
	ds_read_b128 v[234:237], v148
	ds_read_b128 v[238:241], v148 offset:1024
	ds_read_b128 v[242:245], v148 offset:2048
	ds_read_b128 v[246:249], v148 offset:3072
	v_lshl_add_u64 v[148:149], s[22:23], 0, v[0:1]
	s_mov_b32 m0, s56
	v_lshl_add_u64 v[204:205], s[22:23], 0, v[130:131]
	global_load_lds_dwordx4 v[148:149], off
	s_add_i32 m0, s56, 0x2000
	s_nop 0
	global_load_lds_dwordx4 v[204:205], off
	s_barrier
	s_waitcnt lgkmcnt(0)
	s_waitcnt lgkmcnt(0)
	v_mfma_f32_16x16x32_bf16 v[110:113], v[234:237], v[172:175], v[110:113]
	v_mfma_f32_16x16x32_bf16 v[106:109], v[242:245], v[172:175], v[106:109]
	v_mfma_f32_16x16x32_bf16 v[94:97], v[234:237], v[180:183], v[94:97]
	v_mfma_f32_16x16x32_bf16 v[90:93], v[242:245], v[180:183], v[90:93]
	v_mfma_f32_16x16x32_bf16 v[78:81], v[234:237], v[188:191], v[78:81]
	v_mfma_f32_16x16x32_bf16 v[74:77], v[242:245], v[188:191], v[74:77]
	v_mfma_f32_16x16x32_bf16 v[70:73], v[234:237], v[196:199], v[70:73]
	v_mfma_f32_16x16x32_bf16 v[66:69], v[242:245], v[196:199], v[66:69]
	v_mfma_f32_16x16x32_bf16 v[110:113], v[238:241], v[176:179], v[110:113]
	v_mfma_f32_16x16x32_bf16 v[106:109], v[246:249], v[176:179], v[106:109]
	v_mfma_f32_16x16x32_bf16 v[94:97], v[238:241], v[184:187], v[94:97]
	v_mfma_f32_16x16x32_bf16 v[90:93], v[246:249], v[184:187], v[90:93]
	v_mfma_f32_16x16x32_bf16 v[78:81], v[238:241], v[192:195], v[78:81]
	v_mfma_f32_16x16x32_bf16 v[74:77], v[246:249], v[192:195], v[74:77]
	v_mfma_f32_16x16x32_bf16 v[70:73], v[238:241], v[200:203], v[70:73]
	v_mfma_f32_16x16x32_bf16 v[66:69], v[246:249], v[200:203], v[66:69]
	s_mov_b32 m0, s3
	v_lshl_add_u64 v[250:251], s[24:25], 0, v[134:135]
	s_barrier
	ds_read_b128 v[172:175], v143 offset:16384
	ds_read_b128 v[176:179], v143 offset:17408
	ds_read_b128 v[180:183], v143 offset:18432
	ds_read_b128 v[184:187], v143 offset:19456
	ds_read_b128 v[188:191], v143 offset:20480
	ds_read_b128 v[192:195], v143 offset:21504
	ds_read_b128 v[196:199], v143 offset:22528
	ds_read_b128 v[200:203], v143 offset:23552
	global_load_lds_dwordx4 v[250:251], off
	v_lshl_add_u64 v[252:253], s[24:25], 0, v[132:133]
	s_mov_b32 m0, s35
	s_nop 0
	global_load_lds_dwordx4 v[252:253], off
	s_barrier
	s_waitcnt lgkmcnt(0)
	s_waitcnt lgkmcnt(0)
	v_mfma_f32_16x16x32_bf16 v[62:65], v[144:147], v[172:175], v[62:65]
	v_mfma_f32_16x16x32_bf16 v[58:61], v[164:167], v[172:175], v[58:61]
	v_mfma_f32_16x16x32_bf16 v[54:57], v[144:147], v[180:183], v[54:57]
	v_mfma_f32_16x16x32_bf16 v[50:53], v[164:167], v[180:183], v[50:53]
	v_mfma_f32_16x16x32_bf16 v[38:41], v[144:147], v[188:191], v[38:41]
	v_mfma_f32_16x16x32_bf16 v[34:37], v[164:167], v[188:191], v[34:37]
	v_mfma_f32_16x16x32_bf16 v[22:25], v[144:147], v[196:199], v[22:25]
	v_mfma_f32_16x16x32_bf16 v[18:21], v[164:167], v[196:199], v[18:21]
	v_mfma_f32_16x16x32_bf16 v[62:65], v[160:163], v[176:179], v[62:65]
	v_mfma_f32_16x16x32_bf16 v[58:61], v[168:171], v[176:179], v[58:61]
	v_mfma_f32_16x16x32_bf16 v[54:57], v[160:163], v[184:187], v[54:57]
	v_mfma_f32_16x16x32_bf16 v[50:53], v[168:171], v[184:187], v[50:53]
	v_mfma_f32_16x16x32_bf16 v[38:41], v[160:163], v[192:195], v[38:41]
	v_mfma_f32_16x16x32_bf16 v[34:37], v[168:171], v[192:195], v[34:37]
	v_mfma_f32_16x16x32_bf16 v[22:25], v[160:163], v[200:203], v[22:25]
	v_mfma_f32_16x16x32_bf16 v[18:21], v[168:171], v[200:203], v[18:21]
	s_barrier
	s_add_u32 s56, s22, 0x40000
	s_addc_u32 s57, s23, 0
	s_add_i32 s58, s58, s29
	v_lshl_add_u64 v[144:145], s[56:57], 0, v[0:1]
	s_mov_b32 m0, s58
	s_nop 0
	global_load_lds_dwordx4 v[144:145], off
	v_lshl_add_u64 v[144:145], s[56:57], 0, v[130:131]
	s_add_i32 m0, s58, 0x2000
	s_nop 0
	global_load_lds_dwordx4 v[144:145], off
	s_waitcnt vmcnt(6)
	s_barrier
	v_mfma_f32_16x16x32_bf16 v[46:49], v[234:237], v[172:175], v[46:49]
	v_mfma_f32_16x16x32_bf16 v[42:45], v[242:245], v[172:175], v[42:45]
	v_mfma_f32_16x16x32_bf16 v[30:33], v[234:237], v[180:183], v[30:33]
	v_mfma_f32_16x16x32_bf16 v[26:29], v[242:245], v[180:183], v[26:29]
	v_mfma_f32_16x16x32_bf16 v[14:17], v[234:237], v[188:191], v[14:17]
	v_mfma_f32_16x16x32_bf16 v[10:13], v[242:245], v[188:191], v[10:13]
	v_mfma_f32_16x16x32_bf16 v[6:9], v[234:237], v[196:199], v[6:9]
	v_mfma_f32_16x16x32_bf16 v[2:5], v[242:245], v[196:199], v[2:5]
	v_mfma_f32_16x16x32_bf16 v[46:49], v[238:241], v[176:179], v[46:49]
	v_mfma_f32_16x16x32_bf16 v[42:45], v[246:249], v[176:179], v[42:45]
	v_mfma_f32_16x16x32_bf16 v[30:33], v[238:241], v[184:187], v[30:33]
	v_mfma_f32_16x16x32_bf16 v[26:29], v[246:249], v[184:187], v[26:29]
	v_mfma_f32_16x16x32_bf16 v[14:17], v[238:241], v[192:195], v[14:17]
	v_mfma_f32_16x16x32_bf16 v[10:13], v[246:249], v[192:195], v[10:13]
	v_mfma_f32_16x16x32_bf16 v[6:9], v[238:241], v[200:203], v[6:9]
	v_mfma_f32_16x16x32_bf16 v[2:5], v[246:249], v[200:203], v[2:5]
	s_add_i32 s56, 0, 0x18000
	v_add_u32_e32 v159, s56, v141
	s_barrier
	ds_read_b128 v[144:147], v159
	ds_read_b128 v[160:163], v159 offset:1024
	ds_read_b128 v[164:167], v159 offset:2048
	ds_read_b128 v[168:171], v159 offset:3072
	s_add_u32 s24, s24, 0x40000
	s_addc_u32 s25, s25, 0
	s_mov_b32 m0, s38
	v_lshl_add_u64 v[234:235], s[24:25], 0, v[134:135]
	ds_read_b128 v[172:175], v143 offset:32768
	ds_read_b128 v[176:179], v143 offset:33792
	ds_read_b128 v[180:183], v143 offset:34816
	ds_read_b128 v[184:187], v143 offset:35840
	ds_read_b128 v[188:191], v143 offset:36864
	ds_read_b128 v[192:195], v143 offset:37888
	ds_read_b128 v[196:199], v143 offset:38912
	ds_read_b128 v[200:203], v143 offset:39936
	global_load_lds_dwordx4 v[234:235], off
	v_lshl_add_u64 v[234:235], s[24:25], 0, v[132:133]
	s_mov_b32 m0, s39
	s_nop 0
	global_load_lds_dwordx4 v[234:235], off
	s_waitcnt lgkmcnt(8)
	s_barrier
	s_waitcnt lgkmcnt(0)
	s_waitcnt lgkmcnt(0)
	v_mfma_f32_16x16x32_bf16 v[126:129], v[144:147], v[172:175], v[126:129]
	v_mfma_f32_16x16x32_bf16 v[122:125], v[164:167], v[172:175], v[122:125]
	v_mfma_f32_16x16x32_bf16 v[118:121], v[144:147], v[180:183], v[118:121]
	v_mfma_f32_16x16x32_bf16 v[114:117], v[164:167], v[180:183], v[114:117]
	v_mfma_f32_16x16x32_bf16 v[102:105], v[144:147], v[188:191], v[102:105]
	v_mfma_f32_16x16x32_bf16 v[98:101], v[164:167], v[188:191], v[98:101]
	v_mfma_f32_16x16x32_bf16 v[86:89], v[144:147], v[196:199], v[86:89]
	v_mfma_f32_16x16x32_bf16 v[82:85], v[164:167], v[196:199], v[82:85]
	v_mfma_f32_16x16x32_bf16 v[126:129], v[160:163], v[176:179], v[126:129]
	v_mfma_f32_16x16x32_bf16 v[122:125], v[168:171], v[176:179], v[122:125]
	v_mfma_f32_16x16x32_bf16 v[118:121], v[160:163], v[184:187], v[118:121]
	v_mfma_f32_16x16x32_bf16 v[114:117], v[168:171], v[184:187], v[114:117]
	v_mfma_f32_16x16x32_bf16 v[102:105], v[160:163], v[192:195], v[102:105]
	v_mfma_f32_16x16x32_bf16 v[98:101], v[168:171], v[192:195], v[98:101]
	v_mfma_f32_16x16x32_bf16 v[86:89], v[160:163], v[200:203], v[86:89]
	v_mfma_f32_16x16x32_bf16 v[82:85], v[168:171], v[200:203], v[82:85]
	s_barrier
	s_add_i32 s24, 0, 0x1c000
	s_add_i32 s25, s56, s29
	v_add_u32_e32 v159, s24, v141
	v_lshl_add_u64 v[148:149], v[148:149], 0, s[20:21]
	s_mov_b32 m0, s25
	ds_read_b128 v[234:237], v159
	ds_read_b128 v[238:241], v159 offset:1024
	ds_read_b128 v[242:245], v159 offset:2048
	ds_read_b128 v[246:249], v159 offset:3072
	global_load_lds_dwordx4 v[148:149], off
	v_lshl_add_u64 v[148:149], v[204:205], 0, s[20:21]
	s_add_i32 m0, s25, 0x2000
	s_nop 0
	global_load_lds_dwordx4 v[148:149], off
	s_barrier
	s_waitcnt lgkmcnt(0)
	s_waitcnt lgkmcnt(0)
	v_mfma_f32_16x16x32_bf16 v[110:113], v[234:237], v[172:175], v[110:113]
	v_mfma_f32_16x16x32_bf16 v[106:109], v[242:245], v[172:175], v[106:109]
	v_mfma_f32_16x16x32_bf16 v[94:97], v[234:237], v[180:183], v[94:97]
	v_mfma_f32_16x16x32_bf16 v[90:93], v[242:245], v[180:183], v[90:93]
	v_mfma_f32_16x16x32_bf16 v[78:81], v[234:237], v[188:191], v[78:81]
	v_mfma_f32_16x16x32_bf16 v[74:77], v[242:245], v[188:191], v[74:77]
	v_mfma_f32_16x16x32_bf16 v[70:73], v[234:237], v[196:199], v[70:73]
	v_mfma_f32_16x16x32_bf16 v[66:69], v[242:245], v[196:199], v[66:69]
	v_mfma_f32_16x16x32_bf16 v[110:113], v[238:241], v[176:179], v[110:113]
	v_mfma_f32_16x16x32_bf16 v[106:109], v[246:249], v[176:179], v[106:109]
	v_mfma_f32_16x16x32_bf16 v[94:97], v[238:241], v[184:187], v[94:97]
	v_mfma_f32_16x16x32_bf16 v[90:93], v[246:249], v[184:187], v[90:93]
	v_mfma_f32_16x16x32_bf16 v[78:81], v[238:241], v[192:195], v[78:81]
	v_mfma_f32_16x16x32_bf16 v[74:77], v[246:249], v[192:195], v[74:77]
	v_mfma_f32_16x16x32_bf16 v[70:73], v[238:241], v[200:203], v[70:73]
	v_mfma_f32_16x16x32_bf16 v[66:69], v[246:249], v[200:203], v[66:69]
	s_mov_b32 m0, s42
	v_lshl_add_u64 v[148:149], v[250:251], 0, s[20:21]
	s_barrier
	ds_read_b128 v[172:175], v143 offset:49152
	ds_read_b128 v[176:179], v143 offset:50176
	ds_read_b128 v[180:183], v143 offset:51200
	ds_read_b128 v[184:187], v143 offset:52224
	ds_read_b128 v[188:191], v143 offset:53248
	ds_read_b128 v[192:195], v143 offset:54272
	ds_read_b128 v[196:199], v143 offset:55296
	ds_read_b128 v[200:203], v143 offset:56320
	global_load_lds_dwordx4 v[148:149], off
	v_lshl_add_u64 v[148:149], v[252:253], 0, s[20:21]
	s_mov_b32 m0, s43
	s_nop 0
	global_load_lds_dwordx4 v[148:149], off
	s_barrier
	s_waitcnt lgkmcnt(0)
	s_waitcnt lgkmcnt(0)
	v_mfma_f32_16x16x32_bf16 v[62:65], v[144:147], v[172:175], v[62:65]
	v_mfma_f32_16x16x32_bf16 v[58:61], v[164:167], v[172:175], v[58:61]
	v_mfma_f32_16x16x32_bf16 v[54:57], v[144:147], v[180:183], v[54:57]
	v_mfma_f32_16x16x32_bf16 v[50:53], v[164:167], v[180:183], v[50:53]
	v_mfma_f32_16x16x32_bf16 v[38:41], v[144:147], v[188:191], v[38:41]
	v_mfma_f32_16x16x32_bf16 v[34:37], v[164:167], v[188:191], v[34:37]
	v_mfma_f32_16x16x32_bf16 v[22:25], v[144:147], v[196:199], v[22:25]
	v_mfma_f32_16x16x32_bf16 v[18:21], v[164:167], v[196:199], v[18:21]
	v_mfma_f32_16x16x32_bf16 v[62:65], v[160:163], v[176:179], v[62:65]
	v_mfma_f32_16x16x32_bf16 v[58:61], v[168:171], v[176:179], v[58:61]
	v_mfma_f32_16x16x32_bf16 v[54:57], v[160:163], v[184:187], v[54:57]
	v_mfma_f32_16x16x32_bf16 v[50:53], v[168:171], v[184:187], v[50:53]
	v_mfma_f32_16x16x32_bf16 v[38:41], v[160:163], v[192:195], v[38:41]
	v_mfma_f32_16x16x32_bf16 v[34:37], v[168:171], v[192:195], v[34:37]
	v_mfma_f32_16x16x32_bf16 v[22:25], v[160:163], v[200:203], v[22:25]
	v_mfma_f32_16x16x32_bf16 v[18:21], v[168:171], v[200:203], v[18:21]
	s_barrier
	s_add_u32 s22, s22, 0x40080
	s_addc_u32 s23, s23, 0
	s_add_i32 s24, s24, s29
	v_lshl_add_u64 v[144:145], s[22:23], 0, v[0:1]
	s_mov_b32 m0, s24
	s_nop 0
	global_load_lds_dwordx4 v[144:145], off
	v_lshl_add_u64 v[144:145], s[22:23], 0, v[130:131]
	s_add_i32 m0, s24, 0x2000
	s_nop 0
	global_load_lds_dwordx4 v[144:145], off
	s_waitcnt vmcnt(6)
	s_barrier
	v_mfma_f32_16x16x32_bf16 v[46:49], v[234:237], v[172:175], v[46:49]
	v_mfma_f32_16x16x32_bf16 v[42:45], v[242:245], v[172:175], v[42:45]
	v_mfma_f32_16x16x32_bf16 v[30:33], v[234:237], v[180:183], v[30:33]
	v_mfma_f32_16x16x32_bf16 v[26:29], v[242:245], v[180:183], v[26:29]
	v_mfma_f32_16x16x32_bf16 v[14:17], v[234:237], v[188:191], v[14:17]
	v_mfma_f32_16x16x32_bf16 v[10:13], v[242:245], v[188:191], v[10:13]
	v_mfma_f32_16x16x32_bf16 v[6:9], v[234:237], v[196:199], v[6:9]
	v_mfma_f32_16x16x32_bf16 v[2:5], v[242:245], v[196:199], v[2:5]
	v_mfma_f32_16x16x32_bf16 v[46:49], v[238:241], v[176:179], v[46:49]
	v_mfma_f32_16x16x32_bf16 v[42:45], v[246:249], v[176:179], v[42:45]
	v_mfma_f32_16x16x32_bf16 v[30:33], v[238:241], v[184:187], v[30:33]
	v_mfma_f32_16x16x32_bf16 v[26:29], v[246:249], v[184:187], v[26:29]
	v_mfma_f32_16x16x32_bf16 v[14:17], v[238:241], v[192:195], v[14:17]
	v_mfma_f32_16x16x32_bf16 v[10:13], v[246:249], v[192:195], v[10:13]
	v_mfma_f32_16x16x32_bf16 v[6:9], v[238:241], v[200:203], v[6:9]
	v_mfma_f32_16x16x32_bf16 v[2:5], v[246:249], v[200:203], v[2:5]
	s_add_i32 s55, s55, 2
	s_add_u32 s53, s53, 0x100
	s_addc_u32 s54, s54, 0
	s_add_u32 s18, s18, 0x100
	s_addc_u32 s19, s19, 0
	s_cmp_gt_u32 s55, 13
	s_barrier
	s_cbranch_scc0 .LBB0_177
	s_branch .Lup_epi
.Lup_peel:
	s_add_u32 s22, s18, 0xfffc0080
	s_addc_u32 s23, s19, -1
	s_add_i32 s56, 0, 0x10000
	v_add_u32_e32 v148, s56, v141
	ds_read_b128 v[144:147], v148
	ds_read_b128 v[160:163], v148 offset:1024
	ds_read_b128 v[164:167], v148 offset:2048
	ds_read_b128 v[168:171], v148 offset:3072
	s_cmp_eq_u32 s55, 12
	s_cselect_b32 s25, s11, s23
	s_cselect_b32 s24, s51, s22
	s_cselect_b32 s23, s9, s54
	s_cselect_b32 s22, s52, s53
	v_lshl_add_u64 v[148:149], s[18:19], 0, v[138:139]
	s_add_i32 m0, s3, 0xc000
	ds_read_b128 v[172:175], v143
	ds_read_b128 v[176:179], v143 offset:1024
	ds_read_b128 v[180:183], v143 offset:2048
	ds_read_b128 v[184:187], v143 offset:3072
	ds_read_b128 v[188:191], v143 offset:4096
	ds_read_b128 v[192:195], v143 offset:5120
	ds_read_b128 v[196:199], v143 offset:6144
	ds_read_b128 v[200:203], v143 offset:7168
	v_lshl_add_u64 v[148:149], s[18:19], 0, v[136:137]
	s_add_i32 m0, s3, 0xe000
	s_nop 0
	s_waitcnt lgkmcnt(8)
	s_barrier
	s_waitcnt lgkmcnt(0)
	s_waitcnt lgkmcnt(0)
	v_mfma_f32_16x16x32_bf16 v[126:129], v[144:147], v[172:175], v[126:129]
	v_mfma_f32_16x16x32_bf16 v[122:125], v[164:167], v[172:175], v[122:125]
	v_mfma_f32_16x16x32_bf16 v[118:121], v[144:147], v[180:183], v[118:121]
	v_mfma_f32_16x16x32_bf16 v[114:117], v[164:167], v[180:183], v[114:117]
	v_mfma_f32_16x16x32_bf16 v[102:105], v[144:147], v[188:191], v[102:105]
	v_mfma_f32_16x16x32_bf16 v[98:101], v[164:167], v[188:191], v[98:101]
	v_mfma_f32_16x16x32_bf16 v[86:89], v[144:147], v[196:199], v[86:89]
	v_mfma_f32_16x16x32_bf16 v[82:85], v[164:167], v[196:199], v[82:85]
	v_mfma_f32_16x16x32_bf16 v[126:129], v[160:163], v[176:179], v[126:129]
	v_mfma_f32_16x16x32_bf16 v[122:125], v[168:171], v[176:179], v[122:125]
	v_mfma_f32_16x16x32_bf16 v[118:121], v[160:163], v[184:187], v[118:121]
	v_mfma_f32_16x16x32_bf16 v[114:117], v[168:171], v[184:187], v[114:117]
	v_mfma_f32_16x16x32_bf16 v[102:105], v[160:163], v[192:195], v[102:105]
	v_mfma_f32_16x16x32_bf16 v[98:101], v[168:171], v[192:195], v[98:101]
	v_mfma_f32_16x16x32_bf16 v[86:89], v[160:163], v[200:203], v[86:89]
	v_mfma_f32_16x16x32_bf16 v[82:85], v[168:171], v[200:203], v[82:85]
	s_barrier
	s_add_i32 s58, 0, 0x14000
	v_add_u32_e32 v148, s58, v141
	s_add_i32 s56, s56, s29
	ds_read_b128 v[234:237], v148
	ds_read_b128 v[238:241], v148 offset:1024
	ds_read_b128 v[242:245], v148 offset:2048
	ds_read_b128 v[246:249], v148 offset:3072
	v_lshl_add_u64 v[148:149], s[22:23], 0, v[0:1]
	s_mov_b32 m0, s56
	v_lshl_add_u64 v[204:205], s[22:23], 0, v[130:131]
	global_load_lds_dwordx4 v[148:149], off
	s_add_i32 m0, s56, 0x2000
	s_nop 0
	global_load_lds_dwordx4 v[204:205], off
	s_barrier
	s_waitcnt lgkmcnt(0)
	s_waitcnt lgkmcnt(0)
	v_mfma_f32_16x16x32_bf16 v[110:113], v[234:237], v[172:175], v[110:113]
	v_mfma_f32_16x16x32_bf16 v[106:109], v[242:245], v[172:175], v[106:109]
	v_mfma_f32_16x16x32_bf16 v[94:97], v[234:237], v[180:183], v[94:97]
	v_mfma_f32_16x16x32_bf16 v[90:93], v[242:245], v[180:183], v[90:93]
	v_mfma_f32_16x16x32_bf16 v[78:81], v[234:237], v[188:191], v[78:81]
	v_mfma_f32_16x16x32_bf16 v[74:77], v[242:245], v[188:191], v[74:77]
	v_mfma_f32_16x16x32_bf16 v[70:73], v[234:237], v[196:199], v[70:73]
	v_mfma_f32_16x16x32_bf16 v[66:69], v[242:245], v[196:199], v[66:69]
	v_mfma_f32_16x16x32_bf16 v[110:113], v[238:241], v[176:179], v[110:113]
	v_mfma_f32_16x16x32_bf16 v[106:109], v[246:249], v[176:179], v[106:109]
	v_mfma_f32_16x16x32_bf16 v[94:97], v[238:241], v[184:187], v[94:97]
	v_mfma_f32_16x16x32_bf16 v[90:93], v[246:249], v[184:187], v[90:93]
	v_mfma_f32_16x16x32_bf16 v[78:81], v[238:241], v[192:195], v[78:81]
	v_mfma_f32_16x16x32_bf16 v[74:77], v[246:249], v[192:195], v[74:77]
	v_mfma_f32_16x16x32_bf16 v[70:73], v[238:241], v[200:203], v[70:73]
	v_mfma_f32_16x16x32_bf16 v[66:69], v[246:249], v[200:203], v[66:69]
	s_mov_b32 m0, s3
	v_lshl_add_u64 v[250:251], s[24:25], 0, v[134:135]
	s_barrier
	ds_read_b128 v[172:175], v143 offset:16384
	ds_read_b128 v[176:179], v143 offset:17408
	ds_read_b128 v[180:183], v143 offset:18432
	ds_read_b128 v[184:187], v143 offset:19456
	ds_read_b128 v[188:191], v143 offset:20480
	ds_read_b128 v[192:195], v143 offset:21504
	ds_read_b128 v[196:199], v143 offset:22528
	ds_read_b128 v[200:203], v143 offset:23552
	global_load_lds_dwordx4 v[250:251], off
	v_lshl_add_u64 v[252:253], s[24:25], 0, v[132:133]
	s_mov_b32 m0, s35
	s_nop 0
	global_load_lds_dwordx4 v[252:253], off
	s_barrier
	s_waitcnt lgkmcnt(0)
	s_waitcnt lgkmcnt(0)
	v_mfma_f32_16x16x32_bf16 v[62:65], v[144:147], v[172:175], v[62:65]
	v_mfma_f32_16x16x32_bf16 v[58:61], v[164:167], v[172:175], v[58:61]
	v_mfma_f32_16x16x32_bf16 v[54:57], v[144:147], v[180:183], v[54:57]
	v_mfma_f32_16x16x32_bf16 v[50:53], v[164:167], v[180:183], v[50:53]
	v_mfma_f32_16x16x32_bf16 v[38:41], v[144:147], v[188:191], v[38:41]
	v_mfma_f32_16x16x32_bf16 v[34:37], v[164:167], v[188:191], v[34:37]
	v_mfma_f32_16x16x32_bf16 v[22:25], v[144:147], v[196:199], v[22:25]
	v_mfma_f32_16x16x32_bf16 v[18:21], v[164:167], v[196:199], v[18:21]
	v_mfma_f32_16x16x32_bf16 v[62:65], v[160:163], v[176:179], v[62:65]
	v_mfma_f32_16x16x32_bf16 v[58:61], v[168:171], v[176:179], v[58:61]
	v_mfma_f32_16x16x32_bf16 v[54:57], v[160:163], v[184:187], v[54:57]
	v_mfma_f32_16x16x32_bf16 v[50:53], v[168:171], v[184:187], v[50:53]
	v_mfma_f32_16x16x32_bf16 v[38:41], v[160:163], v[192:195], v[38:41]
	v_mfma_f32_16x16x32_bf16 v[34:37], v[168:171], v[192:195], v[34:37]
	v_mfma_f32_16x16x32_bf16 v[22:25], v[160:163], v[200:203], v[22:25]
	v_mfma_f32_16x16x32_bf16 v[18:21], v[168:171], v[200:203], v[18:21]
	s_barrier
	s_add_u32 s56, s22, 0x40000
	s_addc_u32 s57, s23, 0
	s_add_i32 s58, s58, s29
	v_lshl_add_u64 v[144:145], s[56:57], 0, v[0:1]
	s_mov_b32 m0, s58
	s_nop 0
	global_load_lds_dwordx4 v[144:145], off
	v_lshl_add_u64 v[144:145], s[56:57], 0, v[130:131]
	s_add_i32 m0, s58, 0x2000
	s_nop 0
	global_load_lds_dwordx4 v[144:145], off
	s_waitcnt vmcnt(22)
	s_barrier
	v_mfma_f32_16x16x32_bf16 v[46:49], v[234:237], v[172:175], v[46:49]
	v_mfma_f32_16x16x32_bf16 v[42:45], v[242:245], v[172:175], v[42:45]
	v_mfma_f32_16x16x32_bf16 v[30:33], v[234:237], v[180:183], v[30:33]
	v_mfma_f32_16x16x32_bf16 v[26:29], v[242:245], v[180:183], v[26:29]
	v_mfma_f32_16x16x32_bf16 v[14:17], v[234:237], v[188:191], v[14:17]
	v_mfma_f32_16x16x32_bf16 v[10:13], v[242:245], v[188:191], v[10:13]
	v_mfma_f32_16x16x32_bf16 v[6:9], v[234:237], v[196:199], v[6:9]
	v_mfma_f32_16x16x32_bf16 v[2:5], v[242:245], v[196:199], v[2:5]
	v_mfma_f32_16x16x32_bf16 v[46:49], v[238:241], v[176:179], v[46:49]
	v_mfma_f32_16x16x32_bf16 v[42:45], v[246:249], v[176:179], v[42:45]
	v_mfma_f32_16x16x32_bf16 v[30:33], v[238:241], v[184:187], v[30:33]
	v_mfma_f32_16x16x32_bf16 v[26:29], v[246:249], v[184:187], v[26:29]
	v_mfma_f32_16x16x32_bf16 v[14:17], v[238:241], v[192:195], v[14:17]
	v_mfma_f32_16x16x32_bf16 v[10:13], v[246:249], v[192:195], v[10:13]
	v_mfma_f32_16x16x32_bf16 v[6:9], v[238:241], v[200:203], v[6:9]
	v_mfma_f32_16x16x32_bf16 v[2:5], v[246:249], v[200:203], v[2:5]
	s_add_i32 s56, 0, 0x18000
	v_add_u32_e32 v159, s56, v141
	s_barrier
	ds_read_b128 v[144:147], v159
	ds_read_b128 v[160:163], v159 offset:1024
	ds_read_b128 v[164:167], v159 offset:2048
	ds_read_b128 v[168:171], v159 offset:3072
	s_add_u32 s24, s24, 0x40000
	s_addc_u32 s25, s25, 0
	s_mov_b32 m0, s38
	v_lshl_add_u64 v[234:235], s[24:25], 0, v[134:135]
	ds_read_b128 v[172:175], v143 offset:32768
	ds_read_b128 v[176:179], v143 offset:33792
	ds_read_b128 v[180:183], v143 offset:34816
	ds_read_b128 v[184:187], v143 offset:35840
	ds_read_b128 v[188:191], v143 offset:36864
	ds_read_b128 v[192:195], v143 offset:37888
	ds_read_b128 v[196:199], v143 offset:38912
	ds_read_b128 v[200:203], v143 offset:39936
	global_load_lds_dwordx4 v[234:235], off
	v_lshl_add_u64 v[234:235], s[24:25], 0, v[132:133]
	s_mov_b32 m0, s39
	s_nop 0
	global_load_lds_dwordx4 v[234:235], off
	s_waitcnt lgkmcnt(8)
	s_barrier
	s_waitcnt lgkmcnt(0)
	s_waitcnt lgkmcnt(0)
	v_mfma_f32_16x16x32_bf16 v[126:129], v[144:147], v[172:175], v[126:129]
	v_mfma_f32_16x16x32_bf16 v[122:125], v[164:167], v[172:175], v[122:125]
	v_mfma_f32_16x16x32_bf16 v[118:121], v[144:147], v[180:183], v[118:121]
	v_mfma_f32_16x16x32_bf16 v[114:117], v[164:167], v[180:183], v[114:117]
	v_mfma_f32_16x16x32_bf16 v[102:105], v[144:147], v[188:191], v[102:105]
	v_mfma_f32_16x16x32_bf16 v[98:101], v[164:167], v[188:191], v[98:101]
	v_mfma_f32_16x16x32_bf16 v[86:89], v[144:147], v[196:199], v[86:89]
	v_mfma_f32_16x16x32_bf16 v[82:85], v[164:167], v[196:199], v[82:85]
	v_mfma_f32_16x16x32_bf16 v[126:129], v[160:163], v[176:179], v[126:129]
	v_mfma_f32_16x16x32_bf16 v[122:125], v[168:171], v[176:179], v[122:125]
	v_mfma_f32_16x16x32_bf16 v[118:121], v[160:163], v[184:187], v[118:121]
	v_mfma_f32_16x16x32_bf16 v[114:117], v[168:171], v[184:187], v[114:117]
	v_mfma_f32_16x16x32_bf16 v[102:105], v[160:163], v[192:195], v[102:105]
	v_mfma_f32_16x16x32_bf16 v[98:101], v[168:171], v[192:195], v[98:101]
	v_mfma_f32_16x16x32_bf16 v[86:89], v[160:163], v[200:203], v[86:89]
	v_mfma_f32_16x16x32_bf16 v[82:85], v[168:171], v[200:203], v[82:85]
	s_barrier
	s_add_i32 s24, 0, 0x1c000
	s_add_i32 s25, s56, s29
	v_add_u32_e32 v159, s24, v141
	v_lshl_add_u64 v[148:149], v[148:149], 0, s[20:21]
	s_mov_b32 m0, s25
	ds_read_b128 v[234:237], v159
	ds_read_b128 v[238:241], v159 offset:1024
	ds_read_b128 v[242:245], v159 offset:2048
	ds_read_b128 v[246:249], v159 offset:3072
	global_load_lds_dwordx4 v[148:149], off
	v_lshl_add_u64 v[148:149], v[204:205], 0, s[20:21]
	s_add_i32 m0, s25, 0x2000
	s_nop 0
	global_load_lds_dwordx4 v[148:149], off
	s_barrier
	s_waitcnt lgkmcnt(0)
	s_waitcnt lgkmcnt(0)
	v_mfma_f32_16x16x32_bf16 v[110:113], v[234:237], v[172:175], v[110:113]
	v_mfma_f32_16x16x32_bf16 v[106:109], v[242:245], v[172:175], v[106:109]
	v_mfma_f32_16x16x32_bf16 v[94:97], v[234:237], v[180:183], v[94:97]
	v_mfma_f32_16x16x32_bf16 v[90:93], v[242:245], v[180:183], v[90:93]
	v_mfma_f32_16x16x32_bf16 v[78:81], v[234:237], v[188:191], v[78:81]
	v_mfma_f32_16x16x32_bf16 v[74:77], v[242:245], v[188:191], v[74:77]
	v_mfma_f32_16x16x32_bf16 v[70:73], v[234:237], v[196:199], v[70:73]
	v_mfma_f32_16x16x32_bf16 v[66:69], v[242:245], v[196:199], v[66:69]
	v_mfma_f32_16x16x32_bf16 v[110:113], v[238:241], v[176:179], v[110:113]
	v_mfma_f32_16x16x32_bf16 v[106:109], v[246:249], v[176:179], v[106:109]
	v_mfma_f32_16x16x32_bf16 v[94:97], v[238:241], v[184:187], v[94:97]
	v_mfma_f32_16x16x32_bf16 v[90:93], v[246:249], v[184:187], v[90:93]
	v_mfma_f32_16x16x32_bf16 v[78:81], v[238:241], v[192:195], v[78:81]
	v_mfma_f32_16x16x32_bf16 v[74:77], v[246:249], v[192:195], v[74:77]
	v_mfma_f32_16x16x32_bf16 v[70:73], v[238:241], v[200:203], v[70:73]
	v_mfma_f32_16x16x32_bf16 v[66:69], v[246:249], v[200:203], v[66:69]
	s_mov_b32 m0, s42
	v_lshl_add_u64 v[148:149], v[250:251], 0, s[20:21]
	s_barrier
	ds_read_b128 v[172:175], v143 offset:49152
	ds_read_b128 v[176:179], v143 offset:50176
	ds_read_b128 v[180:183], v143 offset:51200
	ds_read_b128 v[184:187], v143 offset:52224
	ds_read_b128 v[188:191], v143 offset:53248
	ds_read_b128 v[192:195], v143 offset:54272
	ds_read_b128 v[196:199], v143 offset:55296
	ds_read_b128 v[200:203], v143 offset:56320
	global_load_lds_dwordx4 v[148:149], off
	v_lshl_add_u64 v[148:149], v[252:253], 0, s[20:21]
	s_mov_b32 m0, s43
	s_nop 0
	global_load_lds_dwordx4 v[148:149], off
	s_barrier
	s_waitcnt lgkmcnt(0)
	s_waitcnt lgkmcnt(0)
	v_mfma_f32_16x16x32_bf16 v[62:65], v[144:147], v[172:175], v[62:65]
	v_mfma_f32_16x16x32_bf16 v[58:61], v[164:167], v[172:175], v[58:61]
	v_mfma_f32_16x16x32_bf16 v[54:57], v[144:147], v[180:183], v[54:57]
	v_mfma_f32_16x16x32_bf16 v[50:53], v[164:167], v[180:183], v[50:53]
	v_mfma_f32_16x16x32_bf16 v[38:41], v[144:147], v[188:191], v[38:41]
	v_mfma_f32_16x16x32_bf16 v[34:37], v[164:167], v[188:191], v[34:37]
	v_mfma_f32_16x16x32_bf16 v[22:25], v[144:147], v[196:199], v[22:25]
	v_mfma_f32_16x16x32_bf16 v[18:21], v[164:167], v[196:199], v[18:21]
	v_mfma_f32_16x16x32_bf16 v[62:65], v[160:163], v[176:179], v[62:65]
	v_mfma_f32_16x16x32_bf16 v[58:61], v[168:171], v[176:179], v[58:61]
	v_mfma_f32_16x16x32_bf16 v[54:57], v[160:163], v[184:187], v[54:57]
	v_mfma_f32_16x16x32_bf16 v[50:53], v[168:171], v[184:187], v[50:53]
	v_mfma_f32_16x16x32_bf16 v[38:41], v[160:163], v[192:195], v[38:41]
	v_mfma_f32_16x16x32_bf16 v[34:37], v[168:171], v[192:195], v[34:37]
	v_mfma_f32_16x16x32_bf16 v[22:25], v[160:163], v[200:203], v[22:25]
	v_mfma_f32_16x16x32_bf16 v[18:21], v[168:171], v[200:203], v[18:21]
	s_barrier
	s_add_u32 s22, s22, 0x40080
	s_addc_u32 s23, s23, 0
	s_add_i32 s24, s24, s29
	v_lshl_add_u64 v[144:145], s[22:23], 0, v[0:1]
	s_mov_b32 m0, s24
	s_nop 0
	global_load_lds_dwordx4 v[144:145], off
	v_lshl_add_u64 v[144:145], s[22:23], 0, v[130:131]
	s_add_i32 m0, s24, 0x2000
	s_nop 0
	global_load_lds_dwordx4 v[144:145], off
	s_waitcnt vmcnt(6)
	s_barrier
	v_mfma_f32_16x16x32_bf16 v[46:49], v[234:237], v[172:175], v[46:49]
	v_mfma_f32_16x16x32_bf16 v[42:45], v[242:245], v[172:175], v[42:45]
	v_mfma_f32_16x16x32_bf16 v[30:33], v[234:237], v[180:183], v[30:33]
	v_mfma_f32_16x16x32_bf16 v[26:29], v[242:245], v[180:183], v[26:29]
	v_mfma_f32_16x16x32_bf16 v[14:17], v[234:237], v[188:191], v[14:17]
	v_mfma_f32_16x16x32_bf16 v[10:13], v[242:245], v[188:191], v[10:13]
	v_mfma_f32_16x16x32_bf16 v[6:9], v[234:237], v[196:199], v[6:9]
	v_mfma_f32_16x16x32_bf16 v[2:5], v[242:245], v[196:199], v[2:5]
	v_mfma_f32_16x16x32_bf16 v[46:49], v[238:241], v[176:179], v[46:49]
	v_mfma_f32_16x16x32_bf16 v[42:45], v[246:249], v[176:179], v[42:45]
	v_mfma_f32_16x16x32_bf16 v[30:33], v[238:241], v[184:187], v[30:33]
	v_mfma_f32_16x16x32_bf16 v[26:29], v[246:249], v[184:187], v[26:29]
	v_mfma_f32_16x16x32_bf16 v[14:17], v[238:241], v[192:195], v[14:17]
	v_mfma_f32_16x16x32_bf16 v[10:13], v[246:249], v[192:195], v[10:13]
	v_mfma_f32_16x16x32_bf16 v[6:9], v[238:241], v[200:203], v[6:9]
	v_mfma_f32_16x16x32_bf16 v[2:5], v[246:249], v[200:203], v[2:5]
	s_add_i32 s55, s55, 2
	s_add_u32 s53, s53, 0x100
	s_addc_u32 s54, s54, 0
	s_add_u32 s18, s18, 0x100
	s_addc_u32 s19, s19, 0
	s_cmp_gt_u32 s55, 13
	s_barrier
	s_cbranch_scc0 .LBB0_177
.Lup_epi:
	s_add_u32 s100, s51, 0x40080
	s_addc_u32 s101, s11, 0
	v_lshl_add_u64 v[160:161], s[100:101], 0, v[138:139]
	s_add_i32 m0, s3, 0xc000
	s_nop 0
	global_load_lds_dwordx4 v[160:161], off
	v_lshl_add_u64 v[160:161], s[100:101], 0, v[136:137]
	s_add_i32 m0, s3, 0xe000
	s_nop 0
	global_load_lds_dwordx4 v[160:161], off
	s_mov_b32 s100, 1
	s_mul_hi_i32 s11, s50, 0x2e8ba2e9
	s_lshr_b32 s18, s11, 31
	s_ashr_i32 s11, s11, 1
	s_add_i32 s11, s11, s18
	s_lshl_b32 s9, s50, 8
	s_mul_i32 s18, s11, 0xb580000
	s_mul_hi_i32 s19, s11, 0xb580000
	s_add_u32 s18, s46, s18
	s_mulk_i32 s11, 0xf500
	s_addc_u32 s19, s47, s19
	s_add_i32 s11, s11, s9
	v_or_b32_e32 v144, s11, v142
	v_lshl_add_u32 v148, s2, 8, v140
	v_ashrrev_i32_e32 v145, 31, v144
	v_lshl_add_u64 v[144:145], v[144:145], 1, s[18:19]
	s_movk_i32 s2, 0x1600
	v_cvt_pk_bf16_f32 v70, v70, v71
	v_cvt_pk_bf16_f32 v71, v72, v73
	v_cvt_pk_bf16_f32 v72, v66, v67
	v_add_u32_e32 v66, 0x80, v148
	v_mad_i64_i32 v[146:147], s[18:19], v148, s2, v[144:145]
	v_cvt_pk_bf16_f32 v110, v110, v111
	v_cvt_pk_bf16_f32 v111, v112, v113
	v_cvt_pk_bf16_f32 v112, v106, v107
	v_cvt_pk_bf16_f32 v113, v108, v109
	v_or_b32_e32 v106, 16, v148
	v_mad_i64_i32 v[66:67], s[18:19], v66, s2, v[144:145]
	v_cvt_pk_bf16_f32 v46, v46, v47
	v_cvt_pk_bf16_f32 v47, v48, v49
	v_cvt_pk_bf16_f32 v48, v42, v43
	v_cvt_pk_bf16_f32 v49, v44, v45
	v_add_u32_e32 v42, 0x90, v148
	global_store_dwordx4 v[146:147], v[110:113], off offset:256
	v_cvt_pk_bf16_f32 v94, v94, v95
	v_cvt_pk_bf16_f32 v95, v96, v97
	v_mad_i64_i32 v[110:111], s[18:19], v106, s2, v[144:145]
	v_cvt_pk_bf16_f32 v96, v90, v91
	v_cvt_pk_bf16_f32 v97, v92, v93
	v_or_b32_e32 v90, 32, v148
	global_store_dwordx4 v[66:67], v[46:49], off offset:256
	v_cvt_pk_bf16_f32 v30, v30, v31
	v_cvt_pk_bf16_f32 v31, v32, v33
	v_mad_i64_i32 v[46:47], s[18:19], v42, s2, v[144:145]
	v_cvt_pk_bf16_f32 v32, v26, v27
	v_cvt_pk_bf16_f32 v33, v28, v29
	v_add_u32_e32 v26, 0xa0, v148
	global_store_dwordx4 v[110:111], v[94:97], off offset:256
	v_cvt_pk_bf16_f32 v78, v78, v79
	v_cvt_pk_bf16_f32 v79, v80, v81
	v_mad_i64_i32 v[94:95], s[18:19], v90, s2, v[144:145]
	v_cvt_pk_bf16_f32 v80, v74, v75
	v_cvt_pk_bf16_f32 v81, v76, v77
	v_or_b32_e32 v74, 48, v148
	global_store_dwordx4 v[46:47], v[30:33], off offset:256
	v_cvt_pk_bf16_f32 v14, v14, v15
	v_cvt_pk_bf16_f32 v15, v16, v17
	v_mad_i64_i32 v[30:31], s[18:19], v26, s2, v[144:145]
	v_cvt_pk_bf16_f32 v16, v10, v11
	v_cvt_pk_bf16_f32 v17, v12, v13
	v_add_u32_e32 v10, 0xb0, v148
	global_store_dwordx4 v[94:95], v[78:81], off offset:256
	global_store_dwordx4 v[30:31], v[14:17], off offset:256
	v_cvt_pk_bf16_f32 v126, v126, v127
	v_mad_i64_i32 v[78:79], s[18:19], v74, s2, v[144:145]
	v_mad_i64_i32 v[14:15], s[18:19], v10, s2, v[144:145]
	v_cvt_pk_bf16_f32 v127, v128, v129
	v_cvt_pk_bf16_f32 v128, v122, v123
	v_cvt_pk_bf16_f32 v129, v124, v125
	v_cvt_pk_bf16_f32 v106, v118, v119
	v_cvt_pk_bf16_f32 v107, v120, v121
	v_cvt_pk_bf16_f32 v108, v114, v115
	v_cvt_pk_bf16_f32 v109, v116, v117
	v_cvt_pk_bf16_f32 v90, v102, v103
	v_cvt_pk_bf16_f32 v91, v104, v105
	v_cvt_pk_bf16_f32 v92, v98, v99
	v_cvt_pk_bf16_f32 v93, v100, v101
	v_cvt_pk_bf16_f32 v74, v86, v87
	v_cvt_pk_bf16_f32 v75, v88, v89
	v_cvt_pk_bf16_f32 v76, v82, v83
	v_cvt_pk_bf16_f32 v77, v84, v85
	v_cvt_pk_bf16_f32 v73, v68, v69
	v_cvt_pk_bf16_f32 v62, v62, v63
	v_cvt_pk_bf16_f32 v63, v64, v65
	v_cvt_pk_bf16_f32 v64, v58, v59
	v_cvt_pk_bf16_f32 v65, v60, v61
	v_cvt_pk_bf16_f32 v42, v54, v55
	v_cvt_pk_bf16_f32 v43, v56, v57
	v_cvt_pk_bf16_f32 v44, v50, v51
	v_cvt_pk_bf16_f32 v45, v52, v53
	v_cvt_pk_bf16_f32 v26, v38, v39
	v_cvt_pk_bf16_f32 v27, v40, v41
	v_cvt_pk_bf16_f32 v28, v34, v35
	v_cvt_pk_bf16_f32 v29, v36, v37
	v_cvt_pk_bf16_f32 v10, v22, v23
	v_cvt_pk_bf16_f32 v11, v24, v25
	v_cvt_pk_bf16_f32 v12, v18, v19
	v_cvt_pk_bf16_f32 v13, v20, v21
	v_cvt_pk_bf16_f32 v6, v6, v7
	v_cvt_pk_bf16_f32 v7, v8, v9
	v_cvt_pk_bf16_f32 v8, v2, v3
	v_cvt_pk_bf16_f32 v9, v4, v5
	s_and_b64 vcc, exec, s[40:41]
	s_mov_b32 s50, s8
	s_mov_b32 s2, s10
	s_mov_b64 s[18:19], s[14:15]
	s_mov_b64 s[22:23], s[12:13]
	s_mov_b32 s56, s66
	global_store_dwordx4 v[146:147], v[126:129], off
	global_store_dwordx4 v[110:111], v[106:109], off
	global_store_dwordx4 v[94:95], v[90:93], off
	global_store_dwordx4 v[78:79], v[74:77], off
	global_store_dwordx4 v[78:79], v[70:73], off offset:256
	global_store_dwordx4 v[66:67], v[62:65], off
	global_store_dwordx4 v[46:47], v[42:45], off
	global_store_dwordx4 v[30:31], v[26:29], off
	global_store_dwordx4 v[14:15], v[10:13], off
	global_store_dwordx4 v[14:15], v[6:9], off offset:256
	s_cbranch_vccz .LBB0_174
	s_waitcnt vmcnt(0)
	s_setprio 0
	s_cmpk_gt_u32 s26, 0xff
	s_cbranch_scc1 .LBB0_181
	s_barrier

.LBB0_192:
	v_ashrrev_i32_e32 v0, 31, v158
	v_lshrrev_b32_e32 v0, 26, v0
	v_add_u32_e32 v0, v158, v0
	s_waitcnt vmcnt(0)
	v_ashrrev_i32_e32 v10, 6, v0
	v_bfe_i32 v0, v158, 27, 1
	v_lshlrev_b32_e32 v2, 4, v158
	v_lshrrev_b32_e32 v0, 22, v0
	v_add_u32_e32 v0, v2, v0
	v_and_b32_e32 v0, 0xfffffc00, v0
	v_sub_u32_e32 v0, v2, v0
	v_lshrrev_b32_e32 v3, 4, v0
	v_bitop3_b32 v3, v3, v0, 32 bitop3:0x6c
	v_ashrrev_i32_e32 v0, 31, v0
	v_lshrrev_b32_e32 v0, 26, v0
	v_add_u32_e32 v0, v3, v0
	v_ashrrev_i32_e32 v11, 6, v0
	v_lshlrev_b32_e32 v4, 3, v10
	v_mul_i32_i24_e32 v5, 64, v11
	v_and_b32_e32 v4, -16, v4
	v_sub_u32_e32 v3, v3, v5
	v_add_u32_e32 v0, v11, v4
	v_ashrrev_i16_sdwa v3, v207, sext(v3) dst_sel:DWORD dst_unused:UNUSED_PAD src0_sel:DWORD src1_sel:BYTE_0
	v_lshlrev_b32_e32 v4, 5, v10
	v_bfe_i32 v12, v3, 0, 16
	v_lshlrev_b32_e32 v3, 1, v0
	v_lshrrev_b32_e32 v5, 2, v0
	v_and_b32_e32 v6, 3, v11
	s_mov_b32 s14, 0x1fffe0
	v_and_b32_e32 v4, 32, v4
	v_and_b32_e32 v3, 24, v3
	v_and_b32_e32 v5, 4, v5
	v_and_or_b32 v6, v0, s14, v6
	v_or3_b32 v3, v6, v5, v3
	v_add_lshl_u32 v4, v4, v12, 1
	v_add_u32_e32 v2, 0x2000, v2
	v_lshl_add_u32 v130, v0, 11, v4
	v_lshl_add_u32 v0, v3, 11, v4
	v_ashrrev_i32_e32 v3, 31, v2
	v_lshrrev_b32_e32 v3, 22, v3
	v_add_u32_e32 v3, v2, v3
	v_ashrrev_i32_e32 v13, 10, v3
	v_mul_i32_i24_e32 v3, 0x400, v13
	v_sub_u32_e32 v2, v2, v3
	v_lshrrev_b32_e32 v3, 4, v2
	v_bitop3_b32 v2, v3, v2, 32 bitop3:0x6c
	v_ashrrev_i32_e32 v4, 31, v2
	v_lshrrev_b32_e32 v4, 26, v4
	v_lshlrev_b32_e32 v3, 3, v13
	v_add_u32_e32 v4, v2, v4
	v_and_b32_e32 v3, -16, v3
	v_ashrrev_i32_e32 v14, 6, v4
	s_waitcnt lgkmcnt(0)
	s_add_u32 s46, s18, 0x4000000
	v_add_u32_e32 v3, v14, v3
	v_and_b32_e32 v6, 3, v14
	s_addc_u32 s47, s19, 0
	v_and_or_b32 v6, v3, s14, v6
	s_ashr_i32 s14, s24, 3
	s_add_i32 s14, s25, s14
	s_ashr_i32 s15, s14, 31
	v_and_b32_e32 v4, 0xc0, v4
	s_lshr_b32 s15, s15, 27
	v_sub_u32_e32 v2, v2, v4
	s_add_i32 s15, s14, s15
	v_ashrrev_i16_sdwa v2, v207, sext(v2) dst_sel:DWORD dst_unused:UNUSED_PAD src0_sel:DWORD src1_sel:BYTE_0
	s_ashr_i32 s18, s15, 5
	v_lshlrev_b32_e32 v5, 5, v13
	v_bfe_i32 v15, v2, 0, 16
	v_lshlrev_b32_e32 v2, 1, v3
	v_lshrrev_b32_e32 v4, 2, v3
	s_lshl_b32 s18, s18, 3
	v_and_b32_e32 v5, 32, v5
	v_and_b32_e32 v2, 24, v2
	v_and_b32_e32 v4, 4, v4
	s_sub_i32 s19, 4, s18
	v_or3_b32 v2, v6, v4, v2
	v_add_lshl_u32 v4, v5, v15, 1
	s_min_u32 s19, s19, 8
	s_andn2_b32 s15, s15, 31
	v_lshl_add_u32 v132, v3, 11, v4
	s_sub_i32 s24, s14, s15
	v_cvt_f32_ubyte0_e32 v3, s19
	v_lshl_add_u32 v134, v2, 11, v4
	v_cvt_f32_i32_e32 v2, s24
	v_rcp_iflag_f32_e32 v4, v3
	s_ashr_i32 s22, s1, 6
	s_ashr_i32 s14, s24, 30
	s_ashr_i32 s23, s1, 8
	v_mul_f32_e32 v4, v2, v4
	v_trunc_f32_e32 v4, v4
	v_fma_f32 v2, -v4, v3, v2
	v_cvt_i32_f32_e32 v4, v4
	s_lshl_b32 s48, s22, 10
	s_or_b32 s25, s14, 1
	v_cmp_ge_f32_e64 s[14:15], |v2|, v3
	s_and_b64 s[14:15], s[14:15], exec
	s_cselect_b32 s14, s25, 0
	v_readfirstlane_b32 s15, v4
	s_add_i32 s14, s15, s14
	s_mul_i32 s15, s14, s19
	s_sub_i32 s15, s24, s15
	s_sext_i32_i8 s15, s15
	s_add_i32 s18, s18, s15
	s_ashr_i32 s19, s18, 31
	s_bfe_i64 s[26:27], s[14:15], 0x80000
	s_lshl_b64 s[24:25], s[18:19], 19
	s_lshl_b64 s[26:27], s[26:27], 19
	s_add_u32 s34, s12, s26
	s_addc_u32 s35, s13, s27
	s_add_i32 s19, s48, 0
	s_add_i32 m0, s19, 0x10000
	v_mov_b32_e32 v135, v1
	global_load_lds_dwordx4 v0, s[34:35]
	s_add_i32 m0, s19, 0x12000
	s_add_u32 s44, s46, s24
	global_load_lds_dwordx4 v134, s[34:35]
	s_addc_u32 s45, s47, s25
	s_mov_b32 m0, s19
	s_add_i32 s49, s19, 0x2000
	global_load_lds_dwordx4 v130, s[44:45]
	s_mov_b32 m0, s49
	s_add_u32 s24, s34, 0x40000
	global_load_lds_dwordx4 v132, s[44:45]
	s_addc_u32 s25, s35, 0
	s_add_i32 m0, s19, 0x14000
	v_mov_b32_e32 v131, v1
	global_load_lds_dwordx4 v0, s[24:25]
	s_add_i32 m0, s19, 0x16000
	v_mov_b32_e32 v133, v1
	global_load_lds_dwordx4 v134, s[24:25]
	s_add_u32 s24, s44, 0x40000
	s_addc_u32 s25, s45, 0
	s_add_i32 s50, s19, 0x4000
	s_mov_b32 m0, s50
	s_add_i32 s51, s19, 0x6000
	global_load_lds_dwordx4 v130, s[24:25]
	s_mov_b32 m0, s51
	v_lshl_add_u64 v[8:9], s[34:35], 0, v[0:1]
	global_load_lds_dwordx4 v132, s[24:25]
	v_lshl_add_u64 v[6:7], s[34:35], 0, v[134:135]
	v_lshl_add_u64 v[4:5], s[44:45], 0, v[130:131]
	s_cmp_lg_u32 s23, 1
	v_lshl_add_u64 v[2:3], s[44:45], 0, v[132:133]
	s_cbranch_scc1 .LBB0_194
	s_barrier
	s_setprio 1

.LBB0_202:
	s_add_u32 s38, s34, 0xfffc0080
	s_addc_u32 s39, s35, -1
	s_add_i32 s60, 0, 0x10000
	v_add_u32_e32 v148, s60, v141
	ds_read_b128 v[144:147], v148
	ds_read_b128 v[160:163], v148 offset:1024
	ds_read_b128 v[164:167], v148 offset:2048
	ds_read_b128 v[168:171], v148 offset:3072
	s_cmp_eq_u32 s59, 12
	s_cselect_b32 s39, s27, s39
	s_cselect_b32 s38, s55, s38
	s_cselect_b32 s45, s25, s58
	s_cselect_b32 s44, s56, s57
	v_lshl_add_u64 v[148:149], s[34:35], 0, v[138:139]
	s_add_i32 m0, s19, 0xc000
	ds_read_b128 v[172:175], v143
	ds_read_b128 v[176:179], v143 offset:1024
	ds_read_b128 v[180:183], v143 offset:2048
	ds_read_b128 v[184:187], v143 offset:3072
	ds_read_b128 v[188:191], v143 offset:4096
	ds_read_b128 v[192:195], v143 offset:5120
	ds_read_b128 v[196:199], v143 offset:6144
	ds_read_b128 v[200:203], v143 offset:7168
	global_load_lds_dwordx4 v[148:149], off
	v_lshl_add_u64 v[148:149], s[34:35], 0, v[136:137]
	s_add_i32 m0, s19, 0xe000
	s_nop 0
	global_load_lds_dwordx4 v[148:149], off
	s_waitcnt lgkmcnt(8)
	s_barrier
	s_waitcnt lgkmcnt(0)
	s_waitcnt lgkmcnt(0)
	v_mfma_f32_16x16x32_bf16 v[126:129], v[144:147], v[172:175], v[126:129]
	v_mfma_f32_16x16x32_bf16 v[122:125], v[164:167], v[172:175], v[122:125]
	v_mfma_f32_16x16x32_bf16 v[118:121], v[144:147], v[180:183], v[118:121]
	v_mfma_f32_16x16x32_bf16 v[114:117], v[164:167], v[180:183], v[114:117]
	v_mfma_f32_16x16x32_bf16 v[102:105], v[144:147], v[188:191], v[102:105]
	v_mfma_f32_16x16x32_bf16 v[98:101], v[164:167], v[188:191], v[98:101]
	v_mfma_f32_16x16x32_bf16 v[86:89], v[144:147], v[196:199], v[86:89]
	v_mfma_f32_16x16x32_bf16 v[82:85], v[164:167], v[196:199], v[82:85]
	v_mfma_f32_16x16x32_bf16 v[126:129], v[160:163], v[176:179], v[126:129]
	v_mfma_f32_16x16x32_bf16 v[122:125], v[168:171], v[176:179], v[122:125]
	v_mfma_f32_16x16x32_bf16 v[118:121], v[160:163], v[184:187], v[118:121]
	v_mfma_f32_16x16x32_bf16 v[114:117], v[168:171], v[184:187], v[114:117]
	v_mfma_f32_16x16x32_bf16 v[102:105], v[160:163], v[192:195], v[102:105]
	v_mfma_f32_16x16x32_bf16 v[98:101], v[168:171], v[192:195], v[98:101]
	v_mfma_f32_16x16x32_bf16 v[86:89], v[160:163], v[200:203], v[86:89]
	v_mfma_f32_16x16x32_bf16 v[82:85], v[168:171], v[200:203], v[82:85]
	s_barrier
	s_add_i32 s62, 0, 0x14000
	v_add_u32_e32 v148, s62, v141
	s_add_i32 s60, s60, s48
	ds_read_b128 v[234:237], v148
	ds_read_b128 v[238:241], v148 offset:1024
	ds_read_b128 v[242:245], v148 offset:2048
	ds_read_b128 v[246:249], v148 offset:3072
	v_lshl_add_u64 v[148:149], s[44:45], 0, v[0:1]
	s_mov_b32 m0, s60
	v_lshl_add_u64 v[204:205], s[44:45], 0, v[134:135]
	global_load_lds_dwordx4 v[148:149], off
	s_add_i32 m0, s60, 0x2000
	s_nop 0
	global_load_lds_dwordx4 v[204:205], off
	s_barrier
	s_waitcnt lgkmcnt(0)
	s_waitcnt lgkmcnt(0)
	v_mfma_f32_16x16x32_bf16 v[110:113], v[234:237], v[172:175], v[110:113]
	v_mfma_f32_16x16x32_bf16 v[106:109], v[242:245], v[172:175], v[106:109]
	v_mfma_f32_16x16x32_bf16 v[94:97], v[234:237], v[180:183], v[94:97]
	v_mfma_f32_16x16x32_bf16 v[90:93], v[242:245], v[180:183], v[90:93]
	v_mfma_f32_16x16x32_bf16 v[78:81], v[234:237], v[188:191], v[78:81]
	v_mfma_f32_16x16x32_bf16 v[74:77], v[242:245], v[188:191], v[74:77]
	v_mfma_f32_16x16x32_bf16 v[70:73], v[234:237], v[196:199], v[70:73]
	v_mfma_f32_16x16x32_bf16 v[66:69], v[242:245], v[196:199], v[66:69]
	v_mfma_f32_16x16x32_bf16 v[110:113], v[238:241], v[176:179], v[110:113]
	v_mfma_f32_16x16x32_bf16 v[106:109], v[246:249], v[176:179], v[106:109]
	v_mfma_f32_16x16x32_bf16 v[94:97], v[238:241], v[184:187], v[94:97]
	v_mfma_f32_16x16x32_bf16 v[90:93], v[246:249], v[184:187], v[90:93]
	v_mfma_f32_16x16x32_bf16 v[78:81], v[238:241], v[192:195], v[78:81]
	v_mfma_f32_16x16x32_bf16 v[74:77], v[246:249], v[192:195], v[74:77]
	v_mfma_f32_16x16x32_bf16 v[70:73], v[238:241], v[200:203], v[70:73]
	v_mfma_f32_16x16x32_bf16 v[66:69], v[246:249], v[200:203], v[66:69]
	s_mov_b32 m0, s19
	v_lshl_add_u64 v[250:251], s[38:39], 0, v[130:131]
	s_barrier
	ds_read_b128 v[172:175], v143 offset:16384
	ds_read_b128 v[176:179], v143 offset:17408
	ds_read_b128 v[180:183], v143 offset:18432
	ds_read_b128 v[184:187], v143 offset:19456
	ds_read_b128 v[188:191], v143 offset:20480
	ds_read_b128 v[192:195], v143 offset:21504
	ds_read_b128 v[196:199], v143 offset:22528
	ds_read_b128 v[200:203], v143 offset:23552
	global_load_lds_dwordx4 v[250:251], off
	v_lshl_add_u64 v[252:253], s[38:39], 0, v[132:133]
	s_mov_b32 m0, s49
	s_nop 0
	global_load_lds_dwordx4 v[252:253], off
	s_barrier
	s_waitcnt lgkmcnt(0)
	s_waitcnt lgkmcnt(0)
	v_mfma_f32_16x16x32_bf16 v[62:65], v[144:147], v[172:175], v[62:65]
	v_mfma_f32_16x16x32_bf16 v[58:61], v[164:167], v[172:175], v[58:61]
	v_mfma_f32_16x16x32_bf16 v[54:57], v[144:147], v[180:183], v[54:57]
	v_mfma_f32_16x16x32_bf16 v[50:53], v[164:167], v[180:183], v[50:53]
	v_mfma_f32_16x16x32_bf16 v[38:41], v[144:147], v[188:191], v[38:41]
	v_mfma_f32_16x16x32_bf16 v[34:37], v[164:167], v[188:191], v[34:37]
	v_mfma_f32_16x16x32_bf16 v[22:25], v[144:147], v[196:199], v[22:25]
	v_mfma_f32_16x16x32_bf16 v[18:21], v[164:167], v[196:199], v[18:21]
	v_mfma_f32_16x16x32_bf16 v[62:65], v[160:163], v[176:179], v[62:65]
	v_mfma_f32_16x16x32_bf16 v[58:61], v[168:171], v[176:179], v[58:61]
	v_mfma_f32_16x16x32_bf16 v[54:57], v[160:163], v[184:187], v[54:57]
	v_mfma_f32_16x16x32_bf16 v[50:53], v[168:171], v[184:187], v[50:53]
	v_mfma_f32_16x16x32_bf16 v[38:41], v[160:163], v[192:195], v[38:41]
	v_mfma_f32_16x16x32_bf16 v[34:37], v[168:171], v[192:195], v[34:37]
	v_mfma_f32_16x16x32_bf16 v[22:25], v[160:163], v[200:203], v[22:25]
	v_mfma_f32_16x16x32_bf16 v[18:21], v[168:171], v[200:203], v[18:21]
	s_barrier
	s_add_u32 s60, s44, 0x40000
	s_addc_u32 s61, s45, 0
	s_add_i32 s62, s62, s48
	v_lshl_add_u64 v[144:145], s[60:61], 0, v[0:1]
	s_mov_b32 m0, s62
	s_nop 0
	global_load_lds_dwordx4 v[144:145], off
	v_lshl_add_u64 v[144:145], s[60:61], 0, v[134:135]
	s_add_i32 m0, s62, 0x2000
	s_nop 0
	global_load_lds_dwordx4 v[144:145], off
	s_waitcnt vmcnt(6)
	s_barrier
	v_mfma_f32_16x16x32_bf16 v[46:49], v[234:237], v[172:175], v[46:49]
	v_mfma_f32_16x16x32_bf16 v[42:45], v[242:245], v[172:175], v[42:45]
	v_mfma_f32_16x16x32_bf16 v[30:33], v[234:237], v[180:183], v[30:33]
	v_mfma_f32_16x16x32_bf16 v[26:29], v[242:245], v[180:183], v[26:29]
	v_mfma_f32_16x16x32_bf16 v[14:17], v[234:237], v[188:191], v[14:17]
	v_mfma_f32_16x16x32_bf16 v[10:13], v[242:245], v[188:191], v[10:13]
	v_mfma_f32_16x16x32_bf16 v[6:9], v[234:237], v[196:199], v[6:9]
	v_mfma_f32_16x16x32_bf16 v[2:5], v[242:245], v[196:199], v[2:5]
	v_mfma_f32_16x16x32_bf16 v[46:49], v[238:241], v[176:179], v[46:49]
	v_mfma_f32_16x16x32_bf16 v[42:45], v[246:249], v[176:179], v[42:45]
	v_mfma_f32_16x16x32_bf16 v[30:33], v[238:241], v[184:187], v[30:33]
	v_mfma_f32_16x16x32_bf16 v[26:29], v[246:249], v[184:187], v[26:29]
	v_mfma_f32_16x16x32_bf16 v[14:17], v[238:241], v[192:195], v[14:17]
	v_mfma_f32_16x16x32_bf16 v[10:13], v[246:249], v[192:195], v[10:13]
	v_mfma_f32_16x16x32_bf16 v[6:9], v[238:241], v[200:203], v[6:9]
	v_mfma_f32_16x16x32_bf16 v[2:5], v[246:249], v[200:203], v[2:5]
	s_add_i32 s60, 0, 0x18000
	v_add_u32_e32 v159, s60, v141
	s_barrier
	ds_read_b128 v[144:147], v159
	ds_read_b128 v[160:163], v159 offset:1024
	ds_read_b128 v[164:167], v159 offset:2048
	ds_read_b128 v[168:171], v159 offset:3072
	s_add_u32 s38, s38, 0x40000
	s_addc_u32 s39, s39, 0
	s_mov_b32 m0, s50
	v_lshl_add_u64 v[234:235], s[38:39], 0, v[130:131]
	ds_read_b128 v[172:175], v143 offset:32768
	ds_read_b128 v[176:179], v143 offset:33792
	ds_read_b128 v[180:183], v143 offset:34816
	ds_read_b128 v[184:187], v143 offset:35840
	ds_read_b128 v[188:191], v143 offset:36864
	ds_read_b128 v[192:195], v143 offset:37888
	ds_read_b128 v[196:199], v143 offset:38912
	ds_read_b128 v[200:203], v143 offset:39936
	global_load_lds_dwordx4 v[234:235], off
	v_lshl_add_u64 v[234:235], s[38:39], 0, v[132:133]
	s_mov_b32 m0, s51
	s_nop 0
	global_load_lds_dwordx4 v[234:235], off
	s_waitcnt lgkmcnt(8)
	s_barrier
	s_waitcnt lgkmcnt(0)
	s_waitcnt lgkmcnt(0)
	v_mfma_f32_16x16x32_bf16 v[126:129], v[144:147], v[172:175], v[126:129]
	v_mfma_f32_16x16x32_bf16 v[122:125], v[164:167], v[172:175], v[122:125]
	v_mfma_f32_16x16x32_bf16 v[118:121], v[144:147], v[180:183], v[118:121]
	v_mfma_f32_16x16x32_bf16 v[114:117], v[164:167], v[180:183], v[114:117]
	v_mfma_f32_16x16x32_bf16 v[102:105], v[144:147], v[188:191], v[102:105]
	v_mfma_f32_16x16x32_bf16 v[98:101], v[164:167], v[188:191], v[98:101]
	v_mfma_f32_16x16x32_bf16 v[86:89], v[144:147], v[196:199], v[86:89]
	v_mfma_f32_16x16x32_bf16 v[82:85], v[164:167], v[196:199], v[82:85]
	v_mfma_f32_16x16x32_bf16 v[126:129], v[160:163], v[176:179], v[126:129]
	v_mfma_f32_16x16x32_bf16 v[122:125], v[168:171], v[176:179], v[122:125]
	v_mfma_f32_16x16x32_bf16 v[118:121], v[160:163], v[184:187], v[118:121]
	v_mfma_f32_16x16x32_bf16 v[114:117], v[168:171], v[184:187], v[114:117]
	v_mfma_f32_16x16x32_bf16 v[102:105], v[160:163], v[192:195], v[102:105]
	v_mfma_f32_16x16x32_bf16 v[98:101], v[168:171], v[192:195], v[98:101]
	v_mfma_f32_16x16x32_bf16 v[86:89], v[160:163], v[200:203], v[86:89]
	v_mfma_f32_16x16x32_bf16 v[82:85], v[168:171], v[200:203], v[82:85]
	s_barrier
	s_add_i32 s61, 0, 0x1c000
	s_add_i32 s38, s60, s48
	v_add_u32_e32 v159, s61, v141
	v_lshl_add_u64 v[148:149], v[148:149], 0, s[20:21]
	s_mov_b32 m0, s38
	ds_read_b128 v[234:237], v159
	ds_read_b128 v[238:241], v159 offset:1024
	ds_read_b128 v[242:245], v159 offset:2048
	ds_read_b128 v[246:249], v159 offset:3072
	global_load_lds_dwordx4 v[148:149], off
	v_lshl_add_u64 v[148:149], v[204:205], 0, s[20:21]
	s_add_i32 m0, s38, 0x2000
	s_nop 0
	global_load_lds_dwordx4 v[148:149], off
	s_barrier
	s_waitcnt lgkmcnt(0)
	s_waitcnt lgkmcnt(0)
	v_mfma_f32_16x16x32_bf16 v[110:113], v[234:237], v[172:175], v[110:113]
	v_mfma_f32_16x16x32_bf16 v[106:109], v[242:245], v[172:175], v[106:109]
	v_mfma_f32_16x16x32_bf16 v[94:97], v[234:237], v[180:183], v[94:97]
	v_mfma_f32_16x16x32_bf16 v[90:93], v[242:245], v[180:183], v[90:93]
	v_mfma_f32_16x16x32_bf16 v[78:81], v[234:237], v[188:191], v[78:81]
	v_mfma_f32_16x16x32_bf16 v[74:77], v[242:245], v[188:191], v[74:77]
	v_mfma_f32_16x16x32_bf16 v[70:73], v[234:237], v[196:199], v[70:73]
	v_mfma_f32_16x16x32_bf16 v[66:69], v[242:245], v[196:199], v[66:69]
	v_mfma_f32_16x16x32_bf16 v[110:113], v[238:241], v[176:179], v[110:113]
	v_mfma_f32_16x16x32_bf16 v[106:109], v[246:249], v[176:179], v[106:109]
	v_mfma_f32_16x16x32_bf16 v[94:97], v[238:241], v[184:187], v[94:97]
	v_mfma_f32_16x16x32_bf16 v[90:93], v[246:249], v[184:187], v[90:93]
	v_mfma_f32_16x16x32_bf16 v[78:81], v[238:241], v[192:195], v[78:81]
	v_mfma_f32_16x16x32_bf16 v[74:77], v[246:249], v[192:195], v[74:77]
	v_mfma_f32_16x16x32_bf16 v[70:73], v[238:241], v[200:203], v[70:73]
	v_mfma_f32_16x16x32_bf16 v[66:69], v[246:249], v[200:203], v[66:69]
	s_mov_b32 m0, s52
	v_lshl_add_u64 v[148:149], v[250:251], 0, s[20:21]
	s_barrier
	ds_read_b128 v[172:175], v143 offset:49152
	ds_read_b128 v[176:179], v143 offset:50176
	ds_read_b128 v[180:183], v143 offset:51200
	ds_read_b128 v[184:187], v143 offset:52224
	ds_read_b128 v[188:191], v143 offset:53248
	ds_read_b128 v[192:195], v143 offset:54272
	ds_read_b128 v[196:199], v143 offset:55296
	ds_read_b128 v[200:203], v143 offset:56320
	global_load_lds_dwordx4 v[148:149], off
	v_lshl_add_u64 v[148:149], v[252:253], 0, s[20:21]
	s_mov_b32 m0, s53
	s_nop 0
	global_load_lds_dwordx4 v[148:149], off
	s_barrier
	s_waitcnt lgkmcnt(0)
	s_waitcnt lgkmcnt(0)
	v_mfma_f32_16x16x32_bf16 v[62:65], v[144:147], v[172:175], v[62:65]
	v_mfma_f32_16x16x32_bf16 v[58:61], v[164:167], v[172:175], v[58:61]
	v_mfma_f32_16x16x32_bf16 v[54:57], v[144:147], v[180:183], v[54:57]
	v_mfma_f32_16x16x32_bf16 v[50:53], v[164:167], v[180:183], v[50:53]
	v_mfma_f32_16x16x32_bf16 v[38:41], v[144:147], v[188:191], v[38:41]
	v_mfma_f32_16x16x32_bf16 v[34:37], v[164:167], v[188:191], v[34:37]
	v_mfma_f32_16x16x32_bf16 v[22:25], v[144:147], v[196:199], v[22:25]
	v_mfma_f32_16x16x32_bf16 v[18:21], v[164:167], v[196:199], v[18:21]
	v_mfma_f32_16x16x32_bf16 v[62:65], v[160:163], v[176:179], v[62:65]
	v_mfma_f32_16x16x32_bf16 v[58:61], v[168:171], v[176:179], v[58:61]
	v_mfma_f32_16x16x32_bf16 v[54:57], v[160:163], v[184:187], v[54:57]
	v_mfma_f32_16x16x32_bf16 v[50:53], v[168:171], v[184:187], v[50:53]
	v_mfma_f32_16x16x32_bf16 v[38:41], v[160:163], v[192:195], v[38:41]
	v_mfma_f32_16x16x32_bf16 v[34:37], v[168:171], v[192:195], v[34:37]
	v_mfma_f32_16x16x32_bf16 v[22:25], v[160:163], v[200:203], v[22:25]
	v_mfma_f32_16x16x32_bf16 v[18:21], v[168:171], v[200:203], v[18:21]
	s_barrier
	s_add_u32 s38, s44, 0x40080
	s_addc_u32 s39, s45, 0
	s_add_i32 s44, s61, s48
	v_lshl_add_u64 v[144:145], s[38:39], 0, v[0:1]
	s_mov_b32 m0, s44
	s_nop 0
	global_load_lds_dwordx4 v[144:145], off
	v_lshl_add_u64 v[144:145], s[38:39], 0, v[134:135]
	s_add_i32 m0, s44, 0x2000
	s_nop 0
	global_load_lds_dwordx4 v[144:145], off
	s_waitcnt vmcnt(6)
	s_barrier
	v_mfma_f32_16x16x32_bf16 v[46:49], v[234:237], v[172:175], v[46:49]
	v_mfma_f32_16x16x32_bf16 v[42:45], v[242:245], v[172:175], v[42:45]
	v_mfma_f32_16x16x32_bf16 v[30:33], v[234:237], v[180:183], v[30:33]
	v_mfma_f32_16x16x32_bf16 v[26:29], v[242:245], v[180:183], v[26:29]
	v_mfma_f32_16x16x32_bf16 v[14:17], v[234:237], v[188:191], v[14:17]
	v_mfma_f32_16x16x32_bf16 v[10:13], v[242:245], v[188:191], v[10:13]
	v_mfma_f32_16x16x32_bf16 v[6:9], v[234:237], v[196:199], v[6:9]
	v_mfma_f32_16x16x32_bf16 v[2:5], v[242:245], v[196:199], v[2:5]
	v_mfma_f32_16x16x32_bf16 v[46:49], v[238:241], v[176:179], v[46:49]
	v_mfma_f32_16x16x32_bf16 v[42:45], v[246:249], v[176:179], v[42:45]
	v_mfma_f32_16x16x32_bf16 v[30:33], v[238:241], v[184:187], v[30:33]
	v_mfma_f32_16x16x32_bf16 v[26:29], v[246:249], v[184:187], v[26:29]
	v_mfma_f32_16x16x32_bf16 v[14:17], v[238:241], v[192:195], v[14:17]
	v_mfma_f32_16x16x32_bf16 v[10:13], v[246:249], v[192:195], v[10:13]
	v_mfma_f32_16x16x32_bf16 v[6:9], v[238:241], v[200:203], v[6:9]
	v_mfma_f32_16x16x32_bf16 v[2:5], v[246:249], v[200:203], v[2:5]
	s_add_i32 s59, s59, 2
	s_add_u32 s57, s57, 0x100
	s_addc_u32 s58, s58, 0
	s_add_u32 s34, s34, 0x100
	s_addc_u32 s35, s35, 0
	s_cmp_gt_u32 s59, 13
	s_barrier
	s_cbranch_scc0 .LBB0_202
	v_lshl_add_u32 v144, s18, 8, v140
	v_lshl_or_b32 v146, s54, 8, v142
	v_ashrrev_i32_e32 v147, 31, v146
	v_ashrrev_i32_e32 v145, 31, v144
	v_lshl_add_u64 v[146:147], v[146:147], 1, s[14:15]
	v_lshlrev_b64 v[148:149], 11, v[144:145]
	v_lshl_add_u64 v[148:149], v[146:147], 0, v[148:149]
	s_mov_b64 s[34:35], 0x40000
	v_cvt_pk_bf16_f32 v62, v62, v63
	v_cvt_pk_bf16_f32 v63, v64, v65
	v_cvt_pk_bf16_f32 v64, v58, v59
	v_add_co_u32_e32 v58, vcc, s79, v148
	v_cvt_pk_bf16_f32 v70, v70, v71
	v_cvt_pk_bf16_f32 v71, v72, v73
	v_cvt_pk_bf16_f32 v72, v66, v67
	v_lshl_add_u64 v[66:67], v[148:149], 0, s[34:35]
	v_addc_co_u32_e32 v59, vcc, 0, v149, vcc
	v_cvt_pk_bf16_f32 v46, v46, v47
	v_cvt_pk_bf16_f32 v47, v48, v49
	v_cvt_pk_bf16_f32 v48, v42, v43
	v_cvt_pk_bf16_f32 v49, v44, v45
	global_store_dwordx4 v[66:67], v[46:49], off offset:256
	s_mov_b64 s[34:35], 0x48000
	v_cvt_pk_bf16_f32 v110, v110, v111
	v_add_co_u32_e32 v48, vcc, s91, v148
	v_cvt_pk_bf16_f32 v111, v112, v113
	v_cvt_pk_bf16_f32 v112, v106, v107
	v_or_b32_e32 v106, 16, v144
	v_lshl_add_u64 v[46:47], v[148:149], 0, s[34:35]
	v_addc_co_u32_e32 v49, vcc, 0, v149, vcc
	v_cvt_pk_bf16_f32 v30, v30, v31
	v_cvt_pk_bf16_f32 v31, v32, v33
	v_cvt_pk_bf16_f32 v32, v26, v27
	v_cvt_pk_bf16_f32 v33, v28, v29
	v_ashrrev_i32_e32 v107, 31, v106
	v_cvt_pk_bf16_f32 v94, v94, v95
	v_cvt_pk_bf16_f32 v95, v96, v97
	v_cvt_pk_bf16_f32 v96, v90, v91
	v_or_b32_e32 v90, 32, v144
	global_store_dwordx4 v[46:47], v[30:33], off offset:256
	s_mov_b64 s[34:35], 0x50000
	v_cvt_pk_bf16_f32 v113, v108, v109
	v_add_co_u32_e32 v32, vcc, s92, v148
	v_lshlrev_b64 v[106:107], 11, v[106:107]
	v_ashrrev_i32_e32 v91, 31, v90
	v_cvt_pk_bf16_f32 v78, v78, v79
	v_cvt_pk_bf16_f32 v79, v80, v81
	v_cvt_pk_bf16_f32 v80, v74, v75
	v_or_b32_e32 v74, 48, v144
	v_lshl_add_u64 v[30:31], v[148:149], 0, s[34:35]
	v_addc_co_u32_e32 v33, vcc, 0, v149, vcc
	v_cvt_pk_bf16_f32 v14, v14, v15
	v_cvt_pk_bf16_f32 v15, v16, v17
	v_cvt_pk_bf16_f32 v16, v10, v11
	v_cvt_pk_bf16_f32 v17, v12, v13
	global_store_dwordx4 v[148:149], v[110:113], off offset:256
	v_cvt_pk_bf16_f32 v97, v92, v93
	v_lshlrev_b64 v[90:91], 11, v[90:91]
	v_lshl_add_u64 v[110:111], v[146:147], 0, v[106:107]
	v_ashrrev_i32_e32 v75, 31, v74
	global_store_dwordx4 v[30:31], v[14:17], off offset:256
	global_store_dwordx4 v[110:111], v[94:97], off offset:256
	v_cvt_pk_bf16_f32 v81, v76, v77
	v_add_co_u32_e32 v16, vcc, 0x58000, v148
	v_lshl_add_u64 v[94:95], v[146:147], 0, v[90:91]
	v_lshlrev_b64 v[74:75], 11, v[74:75]
	s_mov_b64 s[34:35], 0x58000
	v_addc_co_u32_e32 v17, vcc, 0, v149, vcc
	v_cvt_pk_bf16_f32 v126, v126, v127
	v_cvt_pk_bf16_f32 v127, v128, v129
	v_cvt_pk_bf16_f32 v128, v122, v123
	v_cvt_pk_bf16_f32 v129, v124, v125
	v_cvt_pk_bf16_f32 v106, v118, v119
	v_cvt_pk_bf16_f32 v107, v120, v121
	v_cvt_pk_bf16_f32 v108, v114, v115
	v_cvt_pk_bf16_f32 v109, v116, v117
	v_cvt_pk_bf16_f32 v90, v102, v103
	v_cvt_pk_bf16_f32 v91, v104, v105
	v_cvt_pk_bf16_f32 v92, v98, v99
	v_cvt_pk_bf16_f32 v93, v100, v101
	global_store_dwordx4 v[94:95], v[78:81], off offset:256
	v_cvt_pk_bf16_f32 v76, v82, v83
	v_cvt_pk_bf16_f32 v77, v84, v85
	v_lshl_add_u64 v[78:79], v[146:147], 0, v[74:75]
	v_cvt_pk_bf16_f32 v74, v86, v87
	v_cvt_pk_bf16_f32 v75, v88, v89
	v_cvt_pk_bf16_f32 v73, v68, v69
	v_cvt_pk_bf16_f32 v65, v60, v61
	v_cvt_pk_bf16_f32 v42, v54, v55
	v_cvt_pk_bf16_f32 v43, v56, v57
	v_cvt_pk_bf16_f32 v44, v50, v51
	v_cvt_pk_bf16_f32 v45, v52, v53
	v_cvt_pk_bf16_f32 v26, v38, v39
	v_cvt_pk_bf16_f32 v27, v40, v41
	v_cvt_pk_bf16_f32 v28, v34, v35
	v_cvt_pk_bf16_f32 v29, v36, v37
	v_lshl_add_u64 v[14:15], v[148:149], 0, s[34:35]
	v_cvt_pk_bf16_f32 v10, v22, v23
	v_cvt_pk_bf16_f32 v11, v24, v25
	v_cvt_pk_bf16_f32 v12, v18, v19
	v_cvt_pk_bf16_f32 v13, v20, v21
	v_cvt_pk_bf16_f32 v6, v6, v7
	v_cvt_pk_bf16_f32 v7, v8, v9
	v_cvt_pk_bf16_f32 v8, v2, v3
	v_cvt_pk_bf16_f32 v9, v4, v5
	s_and_b64 vcc, exec, s[22:23]
	s_mov_b32 s54, s24
	s_mov_b32 s18, s26
	s_mov_b64 s[34:35], s[30:31]
	s_mov_b64 s[44:45], s[28:29]
	s_movk_i32 s59, 0x7f
	s_movk_i32 s58, 0x15ff
	s_mov_b32 s57, s67
	global_store_dwordx4 v[148:149], v[126:129], off
	global_store_dwordx4 v[110:111], v[106:109], off
	global_store_dwordx4 v[94:95], v[90:93], off
	global_store_dwordx4 v[78:79], v[74:77], off
	global_store_dwordx4 v[78:79], v[70:73], off offset:256
	global_store_dwordx4 v[58:59], v[62:65], off
	global_store_dwordx4 v[48:49], v[42:45], off
	global_store_dwordx4 v[32:33], v[26:29], off
	global_store_dwordx4 v[16:17], v[10:13], off
	global_store_dwordx4 v[14:15], v[6:9], off offset:256
	s_cbranch_vccz .LBB0_195
	s_waitcnt vmcnt(0)
	s_setprio 0
	v_readlane_b32 s54, v255, 3
	s_mov_b32 s56, s66
	s_cmpk_gt_u32 s1, 0xff
	v_readlane_b32 s55, v255, 4
	s_cbranch_scc1 .LBB0_206
	s_barrier

.LBB0_239:
	v_lshrrev_b32_e32 v0, 26, v159
	v_add_u32_e32 v0, v158, v0
	v_ashrrev_i32_e32 v10, 6, v0
	v_bfe_i32 v0, v158, 27, 1
	v_lshlrev_b32_e32 v2, 4, v158
	v_lshrrev_b32_e32 v0, 22, v0
	v_add_u32_e32 v0, v2, v0
	v_and_b32_e32 v0, 0xfffffc00, v0
	v_sub_u32_e32 v0, v2, v0
	v_lshrrev_b32_e32 v3, 4, v0
	v_bitop3_b32 v3, v3, v0, 32 bitop3:0x6c
	v_ashrrev_i32_e32 v0, 31, v0
	v_lshrrev_b32_e32 v0, 26, v0
	v_lshlrev_b32_e32 v4, 3, v10
	v_add_u32_e32 v0, v3, v0
	v_and_b32_e32 v4, -16, v4
	v_ashrrev_i32_e32 v11, 6, v0
	v_add_u32_e32 v0, v11, v4
	v_lshlrev_b32_e32 v4, 5, v10
	v_and_b32_e32 v12, 32, v4
	v_mul_i32_i24_e32 v4, 64, v11
	v_sub_u32_e32 v3, v3, v4
	s_add_u32 s29, s2, 0x16580000
	v_ashrrev_i16_sdwa v3, v207, sext(v3) dst_sel:DWORD dst_unused:UNUSED_PAD src0_sel:DWORD src1_sel:BYTE_0
	v_lshlrev_b32_e32 v4, 1, v0
	v_lshrrev_b32_e32 v5, 2, v0
	v_and_b32_e32 v6, 3, v11
	s_mov_b32 s2, 0xffffe0
	v_bfe_i32 v13, v3, 0, 16
	v_and_b32_e32 v4, 24, v4
	v_and_b32_e32 v5, 4, v5
	v_and_or_b32 v6, v0, s2, v6
	v_add_u32_e32 v3, v12, v13
	v_or3_b32 v4, v6, v5, v4
	v_mul_lo_u32 v0, v0, s71
	v_add_lshl_u32 v130, v3, v0, 1
	v_mul_u32_u24_e32 v0, 0xb00, v4
	v_add_u32_e32 v2, 0x2000, v2
	v_add_lshl_u32 v0, v0, v3, 1
	v_ashrrev_i32_e32 v3, 31, v2
	v_lshrrev_b32_e32 v3, 22, v3
	v_add_u32_e32 v3, v2, v3
	v_ashrrev_i32_e32 v14, 10, v3
	v_mul_i32_i24_e32 v3, 0x400, v14
	v_sub_u32_e32 v2, v2, v3
	v_lshrrev_b32_e32 v3, 4, v2
	v_bitop3_b32 v2, v3, v2, 32 bitop3:0x6c
	v_ashrrev_i32_e32 v4, 31, v2
	v_lshrrev_b32_e32 v4, 26, v4
	v_lshlrev_b32_e32 v3, 3, v14
	v_add_u32_e32 v4, v2, v4
	v_and_b32_e32 v3, -16, v3
	v_ashrrev_i32_e32 v15, 6, v4
	v_add_u32_e32 v3, v15, v3
	v_and_b32_e32 v6, 3, v15
	s_addc_u32 s30, s3, 0
	v_and_or_b32 v6, v3, s2, v6
	s_ashr_i32 s2, s14, 3
	s_add_i32 s2, s15, s2
	s_ashr_i32 s3, s2, 31
	v_and_b32_e32 v4, 0xc0, v4
	s_lshr_b32 s3, s3, 27
	v_lshlrev_b32_e32 v5, 5, v14
	v_sub_u32_e32 v2, v2, v4
	s_add_i32 s3, s2, s3
	v_and_b32_e32 v16, 32, v5
	v_ashrrev_i16_sdwa v2, v207, sext(v2) dst_sel:DWORD dst_unused:UNUSED_PAD src0_sel:DWORD src1_sel:BYTE_0
	v_lshlrev_b32_e32 v4, 1, v3
	v_lshrrev_b32_e32 v5, 2, v3
	s_ashr_i32 s14, s3, 5
	v_bfe_i32 v17, v2, 0, 16
	v_and_b32_e32 v4, 24, v4
	v_and_b32_e32 v5, 4, v5
	s_lshl_b32 s14, s14, 3
	v_add_u32_e32 v2, v16, v17
	v_or3_b32 v4, v6, v5, v4
	v_mul_lo_u32 v3, v3, s71
	s_sub_i32 s15, 4, s14
	v_add_lshl_u32 v132, v2, v3, 1
	v_mul_u32_u24_e32 v3, 0xb00, v4
	s_min_u32 s15, s15, 8
	s_andn2_b32 s3, s3, 31
	v_add_lshl_u32 v134, v3, v2, 1
	s_sub_i32 s18, s2, s3
	v_cvt_f32_ubyte0_e32 v3, s15
	v_cvt_f32_i32_e32 v2, s18
	v_rcp_iflag_f32_e32 v4, v3
	s_ashr_i32 s12, s28, 6
	s_ashr_i32 s2, s18, 30
	s_ashr_i32 s13, s28, 8
	v_mul_f32_e32 v4, v2, v4
	v_trunc_f32_e32 v4, v4
	v_fma_f32 v2, -v4, v3, v2
	v_cvt_i32_f32_e32 v4, v4
	s_lshl_b32 s31, s12, 10
	s_or_b32 s19, s2, 1
	v_cmp_ge_f32_e64 s[2:3], |v2|, v3
	s_and_b64 s[2:3], s[2:3], exec
	s_cselect_b32 s2, s19, 0
	v_readfirstlane_b32 s3, v4
	s_add_i32 s2, s3, s2
	s_mul_i32 s3, s2, s15
	s_sub_i32 s3, s18, s3
	s_sext_i32_i8 s3, s3
	s_mov_b32 s52, s44
	s_add_i32 s44, s14, s3
	s_mul_hi_i32 s3, s44, 0x160000
	s_bfe_i64 s[14:15], s[2:3], 0x80000
	s_mul_hi_i32 s15, s14, 0x160000
	s_mul_i32 s14, s14, 0x160000
	s_waitcnt lgkmcnt(0)
	s_add_u32 s22, s8, s14
	s_addc_u32 s23, s9, s15
	s_add_i32 s34, s31, 0
	s_add_i32 m0, s34, 0x10000
	s_mul_i32 s18, s44, 0x160000
	global_load_lds_dwordx4 v0, s[22:23]
	s_add_i32 m0, s34, 0x12000
	s_add_u32 s18, s29, s18
	global_load_lds_dwordx4 v134, s[22:23]
	s_addc_u32 s19, s30, s3
	s_mov_b32 m0, s34
	s_add_i32 s35, s34, 0x2000
	global_load_lds_dwordx4 v130, s[18:19]
	s_mov_b32 m0, s35
	s_add_u32 s14, s22, 0xb0000
	global_load_lds_dwordx4 v132, s[18:19]
	s_addc_u32 s15, s23, 0
	s_add_i32 m0, s34, 0x14000
	v_mov_b32_e32 v135, v1
	global_load_lds_dwordx4 v0, s[14:15]
	s_add_i32 m0, s34, 0x16000
	v_mov_b32_e32 v131, v1
	global_load_lds_dwordx4 v134, s[14:15]
	s_add_u32 s14, s18, 0xb0000
	s_addc_u32 s15, s19, 0
	s_add_i32 s38, s34, 0x4000
	s_mov_b32 m0, s38
	s_add_i32 s39, s34, 0x6000
	global_load_lds_dwordx4 v130, s[14:15]
	s_mov_b32 m0, s39
	v_mov_b32_e32 v133, v1
	global_load_lds_dwordx4 v132, s[14:15]
	v_lshl_add_u64 v[8:9], s[22:23], 0, v[0:1]
	v_lshl_add_u64 v[6:7], s[22:23], 0, v[134:135]
	v_lshl_add_u64 v[4:5], s[18:19], 0, v[130:131]
	s_cmp_lg_u32 s13, 1
	v_lshl_add_u64 v[2:3], s[18:19], 0, v[132:133]
	s_cbranch_scc1 .LBB0_241
	s_barrier
	s_setprio 1

.LBB0_253:
	s_add_u32 s22, s18, 0x100
	s_addc_u32 s23, s19, 0
	s_add_i32 s49, 0, 0x10000
	v_add_u32_e32 v148, s49, v141
	ds_read_b128 v[144:147], v148
	ds_read_b128 v[160:163], v148 offset:1024
	ds_read_b128 v[164:167], v148 offset:2048
	ds_read_b128 v[168:171], v148 offset:3072
	s_cmp_eq_u32 s48, 40
	s_cselect_b32 s27, s13, s23
	s_cselect_b32 s26, s12, s22
	s_cselect_b32 s25, s15, s41
	s_cselect_b32 s24, s14, s40
	v_lshl_add_u64 v[148:149], s[18:19], 0, v[138:139]
	s_add_i32 m0, s34, 0xc000
	ds_read_b128 v[172:175], v143
	ds_read_b128 v[176:179], v143 offset:1024
	ds_read_b128 v[180:183], v143 offset:2048
	ds_read_b128 v[184:187], v143 offset:3072
	ds_read_b128 v[188:191], v143 offset:4096
	ds_read_b128 v[192:195], v143 offset:5120
	ds_read_b128 v[196:199], v143 offset:6144
	ds_read_b128 v[200:203], v143 offset:7168
	global_load_lds_dwordx4 v[148:149], off
	v_lshl_add_u64 v[148:149], s[18:19], 0, v[136:137]
	s_add_i32 m0, s34, 0xe000
	s_nop 0
	global_load_lds_dwordx4 v[148:149], off
	s_waitcnt lgkmcnt(8)
	s_barrier
	s_waitcnt lgkmcnt(0)
	s_waitcnt lgkmcnt(0)
	v_mfma_f32_16x16x32_bf16 v[126:129], v[144:147], v[172:175], v[126:129]
	v_mfma_f32_16x16x32_bf16 v[122:125], v[164:167], v[172:175], v[122:125]
	v_mfma_f32_16x16x32_bf16 v[118:121], v[144:147], v[180:183], v[118:121]
	v_mfma_f32_16x16x32_bf16 v[114:117], v[164:167], v[180:183], v[114:117]
	v_mfma_f32_16x16x32_bf16 v[102:105], v[144:147], v[188:191], v[102:105]
	v_mfma_f32_16x16x32_bf16 v[98:101], v[164:167], v[188:191], v[98:101]
	v_mfma_f32_16x16x32_bf16 v[86:89], v[144:147], v[196:199], v[86:89]
	v_mfma_f32_16x16x32_bf16 v[82:85], v[164:167], v[196:199], v[82:85]
	v_mfma_f32_16x16x32_bf16 v[126:129], v[160:163], v[176:179], v[126:129]
	v_mfma_f32_16x16x32_bf16 v[122:125], v[168:171], v[176:179], v[122:125]
	v_mfma_f32_16x16x32_bf16 v[118:121], v[160:163], v[184:187], v[118:121]
	v_mfma_f32_16x16x32_bf16 v[114:117], v[168:171], v[184:187], v[114:117]
	v_mfma_f32_16x16x32_bf16 v[102:105], v[160:163], v[192:195], v[102:105]
	v_mfma_f32_16x16x32_bf16 v[98:101], v[168:171], v[192:195], v[98:101]
	v_mfma_f32_16x16x32_bf16 v[86:89], v[160:163], v[200:203], v[86:89]
	v_mfma_f32_16x16x32_bf16 v[82:85], v[168:171], v[200:203], v[82:85]
	s_barrier
	s_add_i32 s50, 0, 0x14000
	v_add_u32_e32 v148, s50, v141
	s_add_i32 s18, s49, s31
	ds_read_b128 v[234:237], v148
	ds_read_b128 v[238:241], v148 offset:1024
	ds_read_b128 v[242:245], v148 offset:2048
	ds_read_b128 v[246:249], v148 offset:3072
	v_lshl_add_u64 v[148:149], s[24:25], 0, v[0:1]
	s_mov_b32 m0, s18
	v_lshl_add_u64 v[204:205], s[24:25], 0, v[134:135]
	global_load_lds_dwordx4 v[148:149], off
	s_add_i32 m0, s18, 0x2000
	s_nop 0
	global_load_lds_dwordx4 v[204:205], off
	s_barrier
	s_waitcnt lgkmcnt(0)
	s_waitcnt lgkmcnt(0)
	v_mfma_f32_16x16x32_bf16 v[110:113], v[234:237], v[172:175], v[110:113]
	v_mfma_f32_16x16x32_bf16 v[106:109], v[242:245], v[172:175], v[106:109]
	v_mfma_f32_16x16x32_bf16 v[94:97], v[234:237], v[180:183], v[94:97]
	v_mfma_f32_16x16x32_bf16 v[90:93], v[242:245], v[180:183], v[90:93]
	v_mfma_f32_16x16x32_bf16 v[78:81], v[234:237], v[188:191], v[78:81]
	v_mfma_f32_16x16x32_bf16 v[74:77], v[242:245], v[188:191], v[74:77]
	v_mfma_f32_16x16x32_bf16 v[70:73], v[234:237], v[196:199], v[70:73]
	v_mfma_f32_16x16x32_bf16 v[66:69], v[242:245], v[196:199], v[66:69]
	v_mfma_f32_16x16x32_bf16 v[110:113], v[238:241], v[176:179], v[110:113]
	v_mfma_f32_16x16x32_bf16 v[106:109], v[246:249], v[176:179], v[106:109]
	v_mfma_f32_16x16x32_bf16 v[94:97], v[238:241], v[184:187], v[94:97]
	v_mfma_f32_16x16x32_bf16 v[90:93], v[246:249], v[184:187], v[90:93]
	v_mfma_f32_16x16x32_bf16 v[78:81], v[238:241], v[192:195], v[78:81]
	v_mfma_f32_16x16x32_bf16 v[74:77], v[246:249], v[192:195], v[74:77]
	v_mfma_f32_16x16x32_bf16 v[70:73], v[238:241], v[200:203], v[70:73]
	v_mfma_f32_16x16x32_bf16 v[66:69], v[246:249], v[200:203], v[66:69]
	s_mov_b32 m0, s34
	v_lshl_add_u64 v[250:251], s[26:27], 0, v[130:131]
	s_barrier
	ds_read_b128 v[172:175], v143 offset:16384
	ds_read_b128 v[176:179], v143 offset:17408
	ds_read_b128 v[180:183], v143 offset:18432
	ds_read_b128 v[184:187], v143 offset:19456
	ds_read_b128 v[188:191], v143 offset:20480
	ds_read_b128 v[192:195], v143 offset:21504
	ds_read_b128 v[196:199], v143 offset:22528
	ds_read_b128 v[200:203], v143 offset:23552
	global_load_lds_dwordx4 v[250:251], off
	v_lshl_add_u64 v[252:253], s[26:27], 0, v[132:133]
	s_mov_b32 m0, s35
	s_nop 0
	global_load_lds_dwordx4 v[252:253], off
	s_barrier
	s_waitcnt lgkmcnt(0)
	s_waitcnt lgkmcnt(0)
	v_mfma_f32_16x16x32_bf16 v[62:65], v[144:147], v[172:175], v[62:65]
	v_mfma_f32_16x16x32_bf16 v[58:61], v[164:167], v[172:175], v[58:61]
	v_mfma_f32_16x16x32_bf16 v[54:57], v[144:147], v[180:183], v[54:57]
	v_mfma_f32_16x16x32_bf16 v[50:53], v[164:167], v[180:183], v[50:53]
	v_mfma_f32_16x16x32_bf16 v[38:41], v[144:147], v[188:191], v[38:41]
	v_mfma_f32_16x16x32_bf16 v[34:37], v[164:167], v[188:191], v[34:37]
	v_mfma_f32_16x16x32_bf16 v[22:25], v[144:147], v[196:199], v[22:25]
	v_mfma_f32_16x16x32_bf16 v[18:21], v[164:167], v[196:199], v[18:21]
	v_mfma_f32_16x16x32_bf16 v[62:65], v[160:163], v[176:179], v[62:65]
	v_mfma_f32_16x16x32_bf16 v[58:61], v[168:171], v[176:179], v[58:61]
	v_mfma_f32_16x16x32_bf16 v[54:57], v[160:163], v[184:187], v[54:57]
	v_mfma_f32_16x16x32_bf16 v[50:53], v[168:171], v[184:187], v[50:53]
	v_mfma_f32_16x16x32_bf16 v[38:41], v[160:163], v[192:195], v[38:41]
	v_mfma_f32_16x16x32_bf16 v[34:37], v[168:171], v[192:195], v[34:37]
	v_mfma_f32_16x16x32_bf16 v[22:25], v[160:163], v[200:203], v[22:25]
	v_mfma_f32_16x16x32_bf16 v[18:21], v[168:171], v[200:203], v[18:21]
	s_barrier
	s_add_u32 s18, s24, 0xb0000
	s_addc_u32 s19, s25, 0
	s_add_i32 s49, s50, s31
	v_lshl_add_u64 v[144:145], s[18:19], 0, v[0:1]
	s_mov_b32 m0, s49
	s_nop 0
	global_load_lds_dwordx4 v[144:145], off
	v_lshl_add_u64 v[144:145], s[18:19], 0, v[134:135]
	s_add_i32 m0, s49, 0x2000
	s_nop 0
	global_load_lds_dwordx4 v[144:145], off
	s_waitcnt vmcnt(6)
	s_barrier
	v_mfma_f32_16x16x32_bf16 v[46:49], v[234:237], v[172:175], v[46:49]
	v_mfma_f32_16x16x32_bf16 v[42:45], v[242:245], v[172:175], v[42:45]
	v_mfma_f32_16x16x32_bf16 v[30:33], v[234:237], v[180:183], v[30:33]
	v_mfma_f32_16x16x32_bf16 v[26:29], v[242:245], v[180:183], v[26:29]
	v_mfma_f32_16x16x32_bf16 v[14:17], v[234:237], v[188:191], v[14:17]
	v_mfma_f32_16x16x32_bf16 v[10:13], v[242:245], v[188:191], v[10:13]
	v_mfma_f32_16x16x32_bf16 v[6:9], v[234:237], v[196:199], v[6:9]
	v_mfma_f32_16x16x32_bf16 v[2:5], v[242:245], v[196:199], v[2:5]
	v_mfma_f32_16x16x32_bf16 v[46:49], v[238:241], v[176:179], v[46:49]
	v_mfma_f32_16x16x32_bf16 v[42:45], v[246:249], v[176:179], v[42:45]
	v_mfma_f32_16x16x32_bf16 v[30:33], v[238:241], v[184:187], v[30:33]
	v_mfma_f32_16x16x32_bf16 v[26:29], v[246:249], v[184:187], v[26:29]
	v_mfma_f32_16x16x32_bf16 v[14:17], v[238:241], v[192:195], v[14:17]
	v_mfma_f32_16x16x32_bf16 v[10:13], v[246:249], v[192:195], v[10:13]
	v_mfma_f32_16x16x32_bf16 v[6:9], v[238:241], v[200:203], v[6:9]
	v_mfma_f32_16x16x32_bf16 v[2:5], v[246:249], v[200:203], v[2:5]
	s_add_i32 s49, 0, 0x18000
	v_add_u32_e32 v159, s49, v141
	s_barrier
	ds_read_b128 v[144:147], v159
	ds_read_b128 v[160:163], v159 offset:1024
	ds_read_b128 v[164:167], v159 offset:2048
	ds_read_b128 v[168:171], v159 offset:3072
	s_add_u32 s18, s26, 0xb0000
	s_addc_u32 s19, s27, 0
	s_mov_b32 m0, s38
	v_lshl_add_u64 v[234:235], s[18:19], 0, v[130:131]
	ds_read_b128 v[172:175], v143 offset:32768
	ds_read_b128 v[176:179], v143 offset:33792
	ds_read_b128 v[180:183], v143 offset:34816
	ds_read_b128 v[184:187], v143 offset:35840
	ds_read_b128 v[188:191], v143 offset:36864
	ds_read_b128 v[192:195], v143 offset:37888
	ds_read_b128 v[196:199], v143 offset:38912
	ds_read_b128 v[200:203], v143 offset:39936
	global_load_lds_dwordx4 v[234:235], off
	v_lshl_add_u64 v[234:235], s[18:19], 0, v[132:133]
	s_mov_b32 m0, s39
	s_nop 0
	global_load_lds_dwordx4 v[234:235], off
	s_waitcnt lgkmcnt(8)
	s_barrier
	s_waitcnt lgkmcnt(0)
	s_waitcnt lgkmcnt(0)
	v_mfma_f32_16x16x32_bf16 v[126:129], v[144:147], v[172:175], v[126:129]
	v_mfma_f32_16x16x32_bf16 v[122:125], v[164:167], v[172:175], v[122:125]
	v_mfma_f32_16x16x32_bf16 v[118:121], v[144:147], v[180:183], v[118:121]
	v_mfma_f32_16x16x32_bf16 v[114:117], v[164:167], v[180:183], v[114:117]
	v_mfma_f32_16x16x32_bf16 v[102:105], v[144:147], v[188:191], v[102:105]
	v_mfma_f32_16x16x32_bf16 v[98:101], v[164:167], v[188:191], v[98:101]
	v_mfma_f32_16x16x32_bf16 v[86:89], v[144:147], v[196:199], v[86:89]
	v_mfma_f32_16x16x32_bf16 v[82:85], v[164:167], v[196:199], v[82:85]
	v_mfma_f32_16x16x32_bf16 v[126:129], v[160:163], v[176:179], v[126:129]
	v_mfma_f32_16x16x32_bf16 v[122:125], v[168:171], v[176:179], v[122:125]
	v_mfma_f32_16x16x32_bf16 v[118:121], v[160:163], v[184:187], v[118:121]
	v_mfma_f32_16x16x32_bf16 v[114:117], v[168:171], v[184:187], v[114:117]
	v_mfma_f32_16x16x32_bf16 v[102:105], v[160:163], v[192:195], v[102:105]
	v_mfma_f32_16x16x32_bf16 v[98:101], v[168:171], v[192:195], v[98:101]
	v_mfma_f32_16x16x32_bf16 v[86:89], v[160:163], v[200:203], v[86:89]
	v_mfma_f32_16x16x32_bf16 v[82:85], v[168:171], v[200:203], v[82:85]
	s_barrier
	s_add_i32 s26, 0, 0x1c000
	s_add_i32 s18, s49, s31
	v_add_u32_e32 v159, s26, v141
	v_lshl_add_u64 v[148:149], v[148:149], 0, s[20:21]
	s_mov_b32 m0, s18
	ds_read_b128 v[234:237], v159
	ds_read_b128 v[238:241], v159 offset:1024
	ds_read_b128 v[242:245], v159 offset:2048
	ds_read_b128 v[246:249], v159 offset:3072
	global_load_lds_dwordx4 v[148:149], off
	v_lshl_add_u64 v[148:149], v[204:205], 0, s[20:21]
	s_add_i32 m0, s18, 0x2000
	s_nop 0
	global_load_lds_dwordx4 v[148:149], off
	s_barrier
	s_waitcnt lgkmcnt(0)
	s_waitcnt lgkmcnt(0)
	v_mfma_f32_16x16x32_bf16 v[110:113], v[234:237], v[172:175], v[110:113]
	v_mfma_f32_16x16x32_bf16 v[106:109], v[242:245], v[172:175], v[106:109]
	v_mfma_f32_16x16x32_bf16 v[94:97], v[234:237], v[180:183], v[94:97]
	v_mfma_f32_16x16x32_bf16 v[90:93], v[242:245], v[180:183], v[90:93]
	v_mfma_f32_16x16x32_bf16 v[78:81], v[234:237], v[188:191], v[78:81]
	v_mfma_f32_16x16x32_bf16 v[74:77], v[242:245], v[188:191], v[74:77]
	v_mfma_f32_16x16x32_bf16 v[70:73], v[234:237], v[196:199], v[70:73]
	v_mfma_f32_16x16x32_bf16 v[66:69], v[242:245], v[196:199], v[66:69]
	v_mfma_f32_16x16x32_bf16 v[110:113], v[238:241], v[176:179], v[110:113]
	v_mfma_f32_16x16x32_bf16 v[106:109], v[246:249], v[176:179], v[106:109]
	v_mfma_f32_16x16x32_bf16 v[94:97], v[238:241], v[184:187], v[94:97]
	v_mfma_f32_16x16x32_bf16 v[90:93], v[246:249], v[184:187], v[90:93]
	v_mfma_f32_16x16x32_bf16 v[78:81], v[238:241], v[192:195], v[78:81]
	v_mfma_f32_16x16x32_bf16 v[74:77], v[246:249], v[192:195], v[74:77]
	v_mfma_f32_16x16x32_bf16 v[70:73], v[238:241], v[200:203], v[70:73]
	v_mfma_f32_16x16x32_bf16 v[66:69], v[246:249], v[200:203], v[66:69]
	s_mov_b32 m0, s42
	v_lshl_add_u64 v[148:149], v[250:251], 0, s[20:21]
	s_barrier
	ds_read_b128 v[172:175], v143 offset:49152
	ds_read_b128 v[176:179], v143 offset:50176
	ds_read_b128 v[180:183], v143 offset:51200
	ds_read_b128 v[184:187], v143 offset:52224
	ds_read_b128 v[188:191], v143 offset:53248
	ds_read_b128 v[192:195], v143 offset:54272
	ds_read_b128 v[196:199], v143 offset:55296
	ds_read_b128 v[200:203], v143 offset:56320
	global_load_lds_dwordx4 v[148:149], off
	v_lshl_add_u64 v[148:149], v[252:253], 0, s[20:21]
	s_mov_b32 m0, s43
	s_nop 0
	global_load_lds_dwordx4 v[148:149], off
	s_barrier
	s_waitcnt lgkmcnt(0)
	s_waitcnt lgkmcnt(0)
	v_mfma_f32_16x16x32_bf16 v[62:65], v[144:147], v[172:175], v[62:65]
	v_mfma_f32_16x16x32_bf16 v[58:61], v[164:167], v[172:175], v[58:61]
	v_mfma_f32_16x16x32_bf16 v[54:57], v[144:147], v[180:183], v[54:57]
	v_mfma_f32_16x16x32_bf16 v[50:53], v[164:167], v[180:183], v[50:53]
	v_mfma_f32_16x16x32_bf16 v[38:41], v[144:147], v[188:191], v[38:41]
	v_mfma_f32_16x16x32_bf16 v[34:37], v[164:167], v[188:191], v[34:37]
	v_mfma_f32_16x16x32_bf16 v[22:25], v[144:147], v[196:199], v[22:25]
	v_mfma_f32_16x16x32_bf16 v[18:21], v[164:167], v[196:199], v[18:21]
	v_mfma_f32_16x16x32_bf16 v[62:65], v[160:163], v[176:179], v[62:65]
	v_mfma_f32_16x16x32_bf16 v[58:61], v[168:171], v[176:179], v[58:61]
	v_mfma_f32_16x16x32_bf16 v[54:57], v[160:163], v[184:187], v[54:57]
	v_mfma_f32_16x16x32_bf16 v[50:53], v[168:171], v[184:187], v[50:53]
	v_mfma_f32_16x16x32_bf16 v[38:41], v[160:163], v[192:195], v[38:41]
	v_mfma_f32_16x16x32_bf16 v[34:37], v[168:171], v[192:195], v[34:37]
	v_mfma_f32_16x16x32_bf16 v[22:25], v[160:163], v[200:203], v[22:25]
	v_mfma_f32_16x16x32_bf16 v[18:21], v[168:171], v[200:203], v[18:21]
	s_barrier
	s_add_u32 s18, s24, 0xb0080
	s_addc_u32 s19, s25, 0
	s_add_i32 s24, s26, s31
	v_lshl_add_u64 v[144:145], s[18:19], 0, v[0:1]
	s_mov_b32 m0, s24
	s_nop 0
	global_load_lds_dwordx4 v[144:145], off
	v_lshl_add_u64 v[144:145], s[18:19], 0, v[134:135]
	s_add_i32 m0, s24, 0x2000
	s_nop 0
	global_load_lds_dwordx4 v[144:145], off
	s_waitcnt vmcnt(6)
	s_barrier
	v_mfma_f32_16x16x32_bf16 v[46:49], v[234:237], v[172:175], v[46:49]
	v_mfma_f32_16x16x32_bf16 v[42:45], v[242:245], v[172:175], v[42:45]
	v_mfma_f32_16x16x32_bf16 v[30:33], v[234:237], v[180:183], v[30:33]
	v_mfma_f32_16x16x32_bf16 v[26:29], v[242:245], v[180:183], v[26:29]
	v_mfma_f32_16x16x32_bf16 v[14:17], v[234:237], v[188:191], v[14:17]
	v_mfma_f32_16x16x32_bf16 v[10:13], v[242:245], v[188:191], v[10:13]
	v_mfma_f32_16x16x32_bf16 v[6:9], v[234:237], v[196:199], v[6:9]
	v_mfma_f32_16x16x32_bf16 v[2:5], v[242:245], v[196:199], v[2:5]
	v_mfma_f32_16x16x32_bf16 v[46:49], v[238:241], v[176:179], v[46:49]
	v_mfma_f32_16x16x32_bf16 v[42:45], v[246:249], v[176:179], v[42:45]
	v_mfma_f32_16x16x32_bf16 v[30:33], v[238:241], v[184:187], v[30:33]
	v_mfma_f32_16x16x32_bf16 v[26:29], v[246:249], v[184:187], v[26:29]
	v_mfma_f32_16x16x32_bf16 v[14:17], v[238:241], v[192:195], v[14:17]
	v_mfma_f32_16x16x32_bf16 v[10:13], v[246:249], v[192:195], v[10:13]
	v_mfma_f32_16x16x32_bf16 v[6:9], v[238:241], v[200:203], v[6:9]
	v_mfma_f32_16x16x32_bf16 v[2:5], v[246:249], v[200:203], v[2:5]
	s_add_i32 s48, s48, 2
	s_add_u32 s40, s40, 0x100
	s_addc_u32 s41, s41, 0
	s_cmp_gt_u32 s48, 41
	s_mov_b64 s[18:19], s[22:23]
	s_barrier
	s_cbranch_scc0 .LBB0_253
	v_lshl_add_u32 v144, s44, 8, v140
	v_lshl_or_b32 v146, s45, 8, v142
	v_ashrrev_i32_e32 v147, 31, v146
	v_ashrrev_i32_e32 v145, 31, v144
	v_lshl_add_u64 v[146:147], v[146:147], 1, s[2:3]
	v_lshlrev_b64 v[148:149], 11, v[144:145]
	v_lshl_add_u64 v[148:149], v[146:147], 0, v[148:149]
	s_mov_b64 s[18:19], 0x40000
	v_cvt_pk_bf16_f32 v62, v62, v63
	v_cvt_pk_bf16_f32 v63, v64, v65
	v_cvt_pk_bf16_f32 v64, v58, v59
	v_add_co_u32_e32 v58, vcc, s79, v148
	v_cvt_pk_bf16_f32 v70, v70, v71
	v_cvt_pk_bf16_f32 v71, v72, v73
	v_cvt_pk_bf16_f32 v72, v66, v67
	v_lshl_add_u64 v[66:67], v[148:149], 0, s[18:19]
	v_addc_co_u32_e32 v59, vcc, 0, v149, vcc
	v_cvt_pk_bf16_f32 v46, v46, v47
	v_cvt_pk_bf16_f32 v47, v48, v49
	v_cvt_pk_bf16_f32 v48, v42, v43
	v_cvt_pk_bf16_f32 v49, v44, v45
	global_store_dwordx4 v[66:67], v[46:49], off offset:256
	s_mov_b64 s[18:19], 0x48000
	v_cvt_pk_bf16_f32 v110, v110, v111
	v_add_co_u32_e32 v48, vcc, s91, v148
	v_cvt_pk_bf16_f32 v111, v112, v113
	v_cvt_pk_bf16_f32 v112, v106, v107
	v_or_b32_e32 v106, 16, v144
	v_lshl_add_u64 v[46:47], v[148:149], 0, s[18:19]
	v_addc_co_u32_e32 v49, vcc, 0, v149, vcc
	v_cvt_pk_bf16_f32 v30, v30, v31
	v_cvt_pk_bf16_f32 v31, v32, v33
	v_cvt_pk_bf16_f32 v32, v26, v27
	v_cvt_pk_bf16_f32 v33, v28, v29
	v_ashrrev_i32_e32 v107, 31, v106
	v_cvt_pk_bf16_f32 v94, v94, v95
	v_cvt_pk_bf16_f32 v95, v96, v97
	v_cvt_pk_bf16_f32 v96, v90, v91
	v_or_b32_e32 v90, 32, v144
	global_store_dwordx4 v[46:47], v[30:33], off offset:256
	s_mov_b64 s[18:19], 0x50000
	v_cvt_pk_bf16_f32 v113, v108, v109
	v_add_co_u32_e32 v32, vcc, s92, v148
	v_lshlrev_b64 v[106:107], 11, v[106:107]
	v_ashrrev_i32_e32 v91, 31, v90
	v_cvt_pk_bf16_f32 v78, v78, v79
	v_cvt_pk_bf16_f32 v79, v80, v81
	v_cvt_pk_bf16_f32 v80, v74, v75
	v_or_b32_e32 v74, 48, v144
	v_lshl_add_u64 v[30:31], v[148:149], 0, s[18:19]
	v_addc_co_u32_e32 v33, vcc, 0, v149, vcc
	v_cvt_pk_bf16_f32 v14, v14, v15
	v_cvt_pk_bf16_f32 v15, v16, v17
	v_cvt_pk_bf16_f32 v16, v10, v11
	v_cvt_pk_bf16_f32 v17, v12, v13
	global_store_dwordx4 v[148:149], v[110:113], off offset:256
	v_cvt_pk_bf16_f32 v97, v92, v93
	v_lshlrev_b64 v[90:91], 11, v[90:91]
	v_lshl_add_u64 v[110:111], v[146:147], 0, v[106:107]
	v_ashrrev_i32_e32 v75, 31, v74
	global_store_dwordx4 v[30:31], v[14:17], off offset:256
	global_store_dwordx4 v[110:111], v[94:97], off offset:256
	v_cvt_pk_bf16_f32 v81, v76, v77
	v_add_co_u32_e32 v16, vcc, 0x58000, v148
	v_lshl_add_u64 v[94:95], v[146:147], 0, v[90:91]
	v_lshlrev_b64 v[74:75], 11, v[74:75]
	s_mov_b64 s[18:19], 0x58000
	v_addc_co_u32_e32 v17, vcc, 0, v149, vcc
	v_cvt_pk_bf16_f32 v126, v126, v127
	v_cvt_pk_bf16_f32 v127, v128, v129
	v_cvt_pk_bf16_f32 v128, v122, v123
	v_cvt_pk_bf16_f32 v129, v124, v125
	v_cvt_pk_bf16_f32 v106, v118, v119
	v_cvt_pk_bf16_f32 v107, v120, v121
	v_cvt_pk_bf16_f32 v108, v114, v115
	v_cvt_pk_bf16_f32 v109, v116, v117
	v_cvt_pk_bf16_f32 v90, v102, v103
	v_cvt_pk_bf16_f32 v91, v104, v105
	v_cvt_pk_bf16_f32 v92, v98, v99
	v_cvt_pk_bf16_f32 v93, v100, v101
	global_store_dwordx4 v[94:95], v[78:81], off offset:256
	v_cvt_pk_bf16_f32 v76, v82, v83
	v_cvt_pk_bf16_f32 v77, v84, v85
	v_lshl_add_u64 v[78:79], v[146:147], 0, v[74:75]
	v_cvt_pk_bf16_f32 v74, v86, v87
	v_cvt_pk_bf16_f32 v75, v88, v89
	v_cvt_pk_bf16_f32 v73, v68, v69
	v_cvt_pk_bf16_f32 v65, v60, v61
	v_cvt_pk_bf16_f32 v42, v54, v55
	v_cvt_pk_bf16_f32 v43, v56, v57
	v_cvt_pk_bf16_f32 v44, v50, v51
	v_cvt_pk_bf16_f32 v45, v52, v53
	v_cvt_pk_bf16_f32 v26, v38, v39
	v_cvt_pk_bf16_f32 v27, v40, v41
	v_cvt_pk_bf16_f32 v28, v34, v35
	v_cvt_pk_bf16_f32 v29, v36, v37
	v_lshl_add_u64 v[14:15], v[148:149], 0, s[18:19]
	v_cvt_pk_bf16_f32 v10, v22, v23
	v_cvt_pk_bf16_f32 v11, v24, v25
	v_cvt_pk_bf16_f32 v12, v18, v19
	v_cvt_pk_bf16_f32 v13, v20, v21
	v_cvt_pk_bf16_f32 v6, v6, v7
	v_cvt_pk_bf16_f32 v7, v8, v9
	v_cvt_pk_bf16_f32 v8, v2, v3
	v_cvt_pk_bf16_f32 v9, v4, v5
	s_and_b64 vcc, exec, s[10:11]
	s_mov_b32 s45, s46
	s_mov_b32 s44, s47
	s_mov_b64 s[22:23], s[14:15]
	s_mov_b64 s[18:19], s[12:13]
	global_store_dwordx4 v[148:149], v[126:129], off
	global_store_dwordx4 v[110:111], v[106:109], off
	global_store_dwordx4 v[94:95], v[90:93], off
	global_store_dwordx4 v[78:79], v[74:77], off
	global_store_dwordx4 v[78:79], v[70:73], off offset:256
	global_store_dwordx4 v[58:59], v[62:65], off
	global_store_dwordx4 v[48:49], v[42:45], off
	global_store_dwordx4 v[32:33], v[26:29], off
	global_store_dwordx4 v[16:17], v[10:13], off
	global_store_dwordx4 v[14:15], v[6:9], off offset:256
	s_cbranch_vccz .LBB0_242
	s_waitcnt vmcnt(0)
	s_setprio 0
	s_cmpk_gt_u32 s28, 0xff
	s_cbranch_scc1 .LBB0_257
	s_barrier

.LBB0_276:
	v_ashrrev_i32_e32 v0, 31, v158
	v_lshrrev_b32_e32 v0, 26, v0
	v_add_u32_e32 v0, v158, v0
	s_waitcnt vmcnt(0)
	v_ashrrev_i32_e32 v10, 6, v0
	v_bfe_i32 v0, v158, 27, 1
	v_lshlrev_b32_e32 v2, 4, v158
	v_lshrrev_b32_e32 v0, 22, v0
	v_add_u32_e32 v0, v2, v0
	v_and_b32_e32 v0, 0xfffffc00, v0
	v_sub_u32_e32 v0, v2, v0
	v_lshrrev_b32_e32 v3, 4, v0
	v_bitop3_b32 v3, v3, v0, 32 bitop3:0x6c
	v_ashrrev_i32_e32 v0, 31, v0
	v_lshrrev_b32_e32 v0, 26, v0
	v_add_u32_e32 v0, v3, v0
	v_ashrrev_i32_e32 v11, 6, v0
	v_lshlrev_b32_e32 v4, 3, v10
	v_mul_i32_i24_e32 v5, 64, v11
	s_ashr_i32 s15, s14, 31
	v_and_b32_e32 v4, -16, v4
	v_sub_u32_e32 v3, v3, v5
	s_ashr_i32 s12, s10, 3
	s_lshl_b64 s[8:9], s[14:15], 21
	v_add_u32_e32 v0, v11, v4
	v_ashrrev_i16_sdwa v3, v207, sext(v3) dst_sel:DWORD dst_unused:UNUSED_PAD src0_sel:DWORD src1_sel:BYTE_0
	s_waitcnt lgkmcnt(0)
	s_add_u32 s27, s2, s8
	v_lshlrev_b32_e32 v4, 5, v10
	v_bfe_i32 v12, v3, 0, 16
	v_lshlrev_b32_e32 v3, 1, v0
	v_lshrrev_b32_e32 v5, 2, v0
	v_and_b32_e32 v6, 3, v11
	s_mov_b32 s2, 0x1fffe0
	v_and_b32_e32 v4, 32, v4
	v_and_b32_e32 v3, 24, v3
	v_and_b32_e32 v5, 4, v5
	v_and_or_b32 v6, v0, s2, v6
	v_or3_b32 v3, v6, v5, v3
	v_add_lshl_u32 v4, v4, v12, 1
	v_add_u32_e32 v2, 0x2000, v2
	v_lshl_add_u32 v130, v0, 11, v4
	v_lshl_add_u32 v0, v3, 11, v4
	v_ashrrev_i32_e32 v3, 31, v2
	v_lshrrev_b32_e32 v3, 22, v3
	v_add_u32_e32 v3, v2, v3
	v_ashrrev_i32_e32 v13, 10, v3
	v_mul_i32_i24_e32 v3, 0x400, v13
	v_sub_u32_e32 v2, v2, v3
	v_lshrrev_b32_e32 v3, 4, v2
	v_bitop3_b32 v2, v3, v2, 32 bitop3:0x6c
	v_ashrrev_i32_e32 v4, 31, v2
	v_lshrrev_b32_e32 v4, 26, v4
	v_lshlrev_b32_e32 v3, 3, v13
	v_add_u32_e32 v4, v2, v4
	v_and_b32_e32 v3, -16, v3
	v_ashrrev_i32_e32 v14, 6, v4
	v_add_u32_e32 v3, v14, v3
	v_and_b32_e32 v6, 3, v14
	s_addc_u32 s28, s3, s9
	v_and_or_b32 v6, v3, s2, v6
	s_add_i32 s2, s11, s12
	s_ashr_i32 s3, s2, 31
	s_lshr_b32 s3, s3, 27
	s_add_i32 s3, s2, s3
	s_ashr_i32 s8, s3, 5
	s_and_b32 s3, s3, 0xffe0
	s_sub_i32 s2, s2, s3
	s_bfe_i32 s3, s2, 0x80000
	s_bfe_u32 s3, s3, 0x3000c
	s_add_i32 s3, s2, s3
	s_lshl_b32 s11, s8, 3
	s_bfe_i32 s8, s3, 0x80000
	s_and_b32 s3, s3, 0xf8
	s_sub_i32 s2, s2, s3
	s_sext_i32_i16 s8, s8
	s_sext_i32_i8 s2, s2
	s_ashr_i32 s9, s1, 6
	s_lshr_b32 s8, s8, 3
	s_add_i32 s2, s11, s2
	s_mov_b32 s60, s14
	v_and_b32_e32 v4, 0xc0, v4
	s_ashr_i32 s3, s2, 31
	s_bfe_i64 s[14:15], s[8:9], 0x100000
	v_sub_u32_e32 v2, v2, v4
	s_ashr_i32 s10, s1, 8
	s_lshl_b32 s29, s9, 10
	s_lshl_b64 s[12:13], s[2:3], 19
	s_lshl_b64 s[14:15], s[14:15], 19
	v_ashrrev_i16_sdwa v2, v207, sext(v2) dst_sel:DWORD dst_unused:UNUSED_PAD src0_sel:DWORD src1_sel:BYTE_0
	s_add_u32 s18, s27, s14
	v_lshlrev_b32_e32 v5, 5, v13
	v_bfe_i32 v15, v2, 0, 16
	v_lshlrev_b32_e32 v2, 1, v3
	v_lshrrev_b32_e32 v4, 2, v3
	s_addc_u32 s19, s28, s15
	s_add_i32 s3, s29, 0
	v_and_b32_e32 v5, 32, v5
	v_and_b32_e32 v2, 24, v2
	v_and_b32_e32 v4, 4, v4
	s_add_i32 m0, s3, 0x10000
	v_or3_b32 v2, v6, v4, v2
	v_add_lshl_u32 v4, v5, v15, 1
	global_load_lds_dwordx4 v0, s[18:19]
	s_add_i32 m0, s3, 0x12000
	v_lshl_add_u32 v134, v2, 11, v4
	s_add_u32 s22, s44, s12
	global_load_lds_dwordx4 v134, s[18:19]
	s_addc_u32 s23, s45, s13
	s_mov_b32 m0, s3
	s_add_i32 s30, s3, 0x2000
	v_lshl_add_u32 v132, v3, 11, v4
	global_load_lds_dwordx4 v130, s[22:23]
	s_mov_b32 m0, s30
	s_add_u32 s12, s18, 0x40000
	global_load_lds_dwordx4 v132, s[22:23]
	s_addc_u32 s13, s19, 0
	s_add_i32 m0, s3, 0x14000
	v_mov_b32_e32 v135, v1
	global_load_lds_dwordx4 v0, s[12:13]
	s_add_i32 m0, s3, 0x16000
	v_mov_b32_e32 v131, v1
	global_load_lds_dwordx4 v134, s[12:13]
	s_add_u32 s12, s22, 0x40000
	s_addc_u32 s13, s23, 0
	s_add_i32 s31, s3, 0x4000
	s_mov_b32 m0, s31
	s_add_i32 s34, s3, 0x6000
	global_load_lds_dwordx4 v130, s[12:13]
	s_mov_b32 m0, s34
	v_mov_b32_e32 v133, v1
	global_load_lds_dwordx4 v132, s[12:13]
	v_lshl_add_u64 v[8:9], s[18:19], 0, v[0:1]
	v_lshl_add_u64 v[6:7], s[18:19], 0, v[134:135]
	v_lshl_add_u64 v[4:5], s[22:23], 0, v[130:131]
	s_cmp_lg_u32 s10, 1
	v_lshl_add_u64 v[2:3], s[22:23], 0, v[132:133]
	s_cbranch_scc1 .LBB0_278
	s_barrier
	s_setprio 1

.LBB0_286:
	s_add_u32 s22, s18, 0xfffc0080
	s_addc_u32 s23, s19, -1
	s_add_i32 s53, 0, 0x10000
	v_add_u32_e32 v148, s53, v141
	ds_read_b128 v[144:147], v148
	ds_read_b128 v[160:163], v148 offset:1024
	ds_read_b128 v[164:167], v148 offset:2048
	ds_read_b128 v[168:171], v148 offset:3072
	s_cmp_eq_u32 s52, 12
	s_cselect_b32 s25, s11, s23
	s_cselect_b32 s24, s48, s22
	s_cselect_b32 s23, s9, s51
	s_cselect_b32 s22, s49, s50
	v_lshl_add_u64 v[148:149], s[18:19], 0, v[138:139]
	s_add_i32 m0, s3, 0xc000
	ds_read_b128 v[172:175], v143
	ds_read_b128 v[176:179], v143 offset:1024
	ds_read_b128 v[180:183], v143 offset:2048
	ds_read_b128 v[184:187], v143 offset:3072
	ds_read_b128 v[188:191], v143 offset:4096
	ds_read_b128 v[192:195], v143 offset:5120
	ds_read_b128 v[196:199], v143 offset:6144
	ds_read_b128 v[200:203], v143 offset:7168
	global_load_lds_dwordx4 v[148:149], off
	v_lshl_add_u64 v[148:149], s[18:19], 0, v[136:137]
	s_add_i32 m0, s3, 0xe000
	s_nop 0
	global_load_lds_dwordx4 v[148:149], off
	s_waitcnt lgkmcnt(8)
	s_barrier
	s_waitcnt lgkmcnt(0)
	s_waitcnt lgkmcnt(0)
	v_mfma_f32_16x16x32_bf16 v[126:129], v[144:147], v[172:175], v[126:129]
	v_mfma_f32_16x16x32_bf16 v[122:125], v[164:167], v[172:175], v[122:125]
	v_mfma_f32_16x16x32_bf16 v[118:121], v[144:147], v[180:183], v[118:121]
	v_mfma_f32_16x16x32_bf16 v[114:117], v[164:167], v[180:183], v[114:117]
	v_mfma_f32_16x16x32_bf16 v[102:105], v[144:147], v[188:191], v[102:105]
	v_mfma_f32_16x16x32_bf16 v[98:101], v[164:167], v[188:191], v[98:101]
	v_mfma_f32_16x16x32_bf16 v[86:89], v[144:147], v[196:199], v[86:89]
	v_mfma_f32_16x16x32_bf16 v[82:85], v[164:167], v[196:199], v[82:85]
	v_mfma_f32_16x16x32_bf16 v[126:129], v[160:163], v[176:179], v[126:129]
	v_mfma_f32_16x16x32_bf16 v[122:125], v[168:171], v[176:179], v[122:125]
	v_mfma_f32_16x16x32_bf16 v[118:121], v[160:163], v[184:187], v[118:121]
	v_mfma_f32_16x16x32_bf16 v[114:117], v[168:171], v[184:187], v[114:117]
	v_mfma_f32_16x16x32_bf16 v[102:105], v[160:163], v[192:195], v[102:105]
	v_mfma_f32_16x16x32_bf16 v[98:101], v[168:171], v[192:195], v[98:101]
	v_mfma_f32_16x16x32_bf16 v[86:89], v[160:163], v[200:203], v[86:89]
	v_mfma_f32_16x16x32_bf16 v[82:85], v[168:171], v[200:203], v[82:85]
	s_barrier
	s_add_i32 s56, 0, 0x14000
	v_add_u32_e32 v148, s56, v141
	s_add_i32 s53, s53, s29
	ds_read_b128 v[234:237], v148
	ds_read_b128 v[238:241], v148 offset:1024
	ds_read_b128 v[242:245], v148 offset:2048
	ds_read_b128 v[246:249], v148 offset:3072
	v_lshl_add_u64 v[148:149], s[22:23], 0, v[0:1]
	s_mov_b32 m0, s53
	v_lshl_add_u64 v[204:205], s[22:23], 0, v[134:135]
	global_load_lds_dwordx4 v[148:149], off
	s_add_i32 m0, s53, 0x2000
	s_nop 0
	global_load_lds_dwordx4 v[204:205], off
	s_barrier
	s_waitcnt lgkmcnt(0)
	s_waitcnt lgkmcnt(0)
	v_mfma_f32_16x16x32_bf16 v[110:113], v[234:237], v[172:175], v[110:113]
	v_mfma_f32_16x16x32_bf16 v[106:109], v[242:245], v[172:175], v[106:109]
	v_mfma_f32_16x16x32_bf16 v[94:97], v[234:237], v[180:183], v[94:97]
	v_mfma_f32_16x16x32_bf16 v[90:93], v[242:245], v[180:183], v[90:93]
	v_mfma_f32_16x16x32_bf16 v[78:81], v[234:237], v[188:191], v[78:81]
	v_mfma_f32_16x16x32_bf16 v[74:77], v[242:245], v[188:191], v[74:77]
	v_mfma_f32_16x16x32_bf16 v[70:73], v[234:237], v[196:199], v[70:73]
	v_mfma_f32_16x16x32_bf16 v[66:69], v[242:245], v[196:199], v[66:69]
	v_mfma_f32_16x16x32_bf16 v[110:113], v[238:241], v[176:179], v[110:113]
	v_mfma_f32_16x16x32_bf16 v[106:109], v[246:249], v[176:179], v[106:109]
	v_mfma_f32_16x16x32_bf16 v[94:97], v[238:241], v[184:187], v[94:97]
	v_mfma_f32_16x16x32_bf16 v[90:93], v[246:249], v[184:187], v[90:93]
	v_mfma_f32_16x16x32_bf16 v[78:81], v[238:241], v[192:195], v[78:81]
	v_mfma_f32_16x16x32_bf16 v[74:77], v[246:249], v[192:195], v[74:77]
	v_mfma_f32_16x16x32_bf16 v[70:73], v[238:241], v[200:203], v[70:73]
	v_mfma_f32_16x16x32_bf16 v[66:69], v[246:249], v[200:203], v[66:69]
	s_mov_b32 m0, s3
	v_lshl_add_u64 v[250:251], s[24:25], 0, v[130:131]
	s_barrier
	ds_read_b128 v[172:175], v143 offset:16384
	ds_read_b128 v[176:179], v143 offset:17408
	ds_read_b128 v[180:183], v143 offset:18432
	ds_read_b128 v[184:187], v143 offset:19456
	ds_read_b128 v[188:191], v143 offset:20480
	ds_read_b128 v[192:195], v143 offset:21504
	ds_read_b128 v[196:199], v143 offset:22528
	ds_read_b128 v[200:203], v143 offset:23552
	global_load_lds_dwordx4 v[250:251], off
	v_lshl_add_u64 v[252:253], s[24:25], 0, v[132:133]
	s_mov_b32 m0, s30
	s_nop 0
	global_load_lds_dwordx4 v[252:253], off
	s_barrier
	s_waitcnt lgkmcnt(0)
	s_waitcnt lgkmcnt(0)
	v_mfma_f32_16x16x32_bf16 v[62:65], v[144:147], v[172:175], v[62:65]
	v_mfma_f32_16x16x32_bf16 v[58:61], v[164:167], v[172:175], v[58:61]
	v_mfma_f32_16x16x32_bf16 v[54:57], v[144:147], v[180:183], v[54:57]
	v_mfma_f32_16x16x32_bf16 v[50:53], v[164:167], v[180:183], v[50:53]
	v_mfma_f32_16x16x32_bf16 v[38:41], v[144:147], v[188:191], v[38:41]
	v_mfma_f32_16x16x32_bf16 v[34:37], v[164:167], v[188:191], v[34:37]
	v_mfma_f32_16x16x32_bf16 v[22:25], v[144:147], v[196:199], v[22:25]
	v_mfma_f32_16x16x32_bf16 v[18:21], v[164:167], v[196:199], v[18:21]
	v_mfma_f32_16x16x32_bf16 v[62:65], v[160:163], v[176:179], v[62:65]
	v_mfma_f32_16x16x32_bf16 v[58:61], v[168:171], v[176:179], v[58:61]
	v_mfma_f32_16x16x32_bf16 v[54:57], v[160:163], v[184:187], v[54:57]
	v_mfma_f32_16x16x32_bf16 v[50:53], v[168:171], v[184:187], v[50:53]
	v_mfma_f32_16x16x32_bf16 v[38:41], v[160:163], v[192:195], v[38:41]
	v_mfma_f32_16x16x32_bf16 v[34:37], v[168:171], v[192:195], v[34:37]
	v_mfma_f32_16x16x32_bf16 v[22:25], v[160:163], v[200:203], v[22:25]
	v_mfma_f32_16x16x32_bf16 v[18:21], v[168:171], v[200:203], v[18:21]
	s_barrier
	s_add_u32 s54, s22, 0x40000
	s_addc_u32 s55, s23, 0
	s_add_i32 s53, s56, s29
	v_lshl_add_u64 v[144:145], s[54:55], 0, v[0:1]
	s_mov_b32 m0, s53
	s_nop 0
	global_load_lds_dwordx4 v[144:145], off
	v_lshl_add_u64 v[144:145], s[54:55], 0, v[134:135]
	s_add_i32 m0, s53, 0x2000
	s_nop 0
	global_load_lds_dwordx4 v[144:145], off
	s_waitcnt vmcnt(6)
	s_barrier
	v_mfma_f32_16x16x32_bf16 v[46:49], v[234:237], v[172:175], v[46:49]
	v_mfma_f32_16x16x32_bf16 v[42:45], v[242:245], v[172:175], v[42:45]
	v_mfma_f32_16x16x32_bf16 v[30:33], v[234:237], v[180:183], v[30:33]
	v_mfma_f32_16x16x32_bf16 v[26:29], v[242:245], v[180:183], v[26:29]
	v_mfma_f32_16x16x32_bf16 v[14:17], v[234:237], v[188:191], v[14:17]
	v_mfma_f32_16x16x32_bf16 v[10:13], v[242:245], v[188:191], v[10:13]
	v_mfma_f32_16x16x32_bf16 v[6:9], v[234:237], v[196:199], v[6:9]
	v_mfma_f32_16x16x32_bf16 v[2:5], v[242:245], v[196:199], v[2:5]
	v_mfma_f32_16x16x32_bf16 v[46:49], v[238:241], v[176:179], v[46:49]
	v_mfma_f32_16x16x32_bf16 v[42:45], v[246:249], v[176:179], v[42:45]
	v_mfma_f32_16x16x32_bf16 v[30:33], v[238:241], v[184:187], v[30:33]
	v_mfma_f32_16x16x32_bf16 v[26:29], v[246:249], v[184:187], v[26:29]
	v_mfma_f32_16x16x32_bf16 v[14:17], v[238:241], v[192:195], v[14:17]
	v_mfma_f32_16x16x32_bf16 v[10:13], v[246:249], v[192:195], v[10:13]
	v_mfma_f32_16x16x32_bf16 v[6:9], v[238:241], v[200:203], v[6:9]
	v_mfma_f32_16x16x32_bf16 v[2:5], v[246:249], v[200:203], v[2:5]
	s_add_i32 s53, 0, 0x18000
	v_add_u32_e32 v159, s53, v141
	s_barrier
	ds_read_b128 v[144:147], v159
	ds_read_b128 v[160:163], v159 offset:1024
	ds_read_b128 v[164:167], v159 offset:2048
	ds_read_b128 v[168:171], v159 offset:3072
	s_add_u32 s24, s24, 0x40000
	s_addc_u32 s25, s25, 0
	s_mov_b32 m0, s31
	v_lshl_add_u64 v[234:235], s[24:25], 0, v[130:131]
	ds_read_b128 v[172:175], v143 offset:32768
	ds_read_b128 v[176:179], v143 offset:33792
	ds_read_b128 v[180:183], v143 offset:34816
	ds_read_b128 v[184:187], v143 offset:35840
	ds_read_b128 v[188:191], v143 offset:36864
	ds_read_b128 v[192:195], v143 offset:37888
	ds_read_b128 v[196:199], v143 offset:38912
	ds_read_b128 v[200:203], v143 offset:39936
	global_load_lds_dwordx4 v[234:235], off
	v_lshl_add_u64 v[234:235], s[24:25], 0, v[132:133]
	s_mov_b32 m0, s34
	s_nop 0
	global_load_lds_dwordx4 v[234:235], off
	s_waitcnt lgkmcnt(8)
	s_barrier
	s_waitcnt lgkmcnt(0)
	s_waitcnt lgkmcnt(0)
	v_mfma_f32_16x16x32_bf16 v[126:129], v[144:147], v[172:175], v[126:129]
	v_mfma_f32_16x16x32_bf16 v[122:125], v[164:167], v[172:175], v[122:125]
	v_mfma_f32_16x16x32_bf16 v[118:121], v[144:147], v[180:183], v[118:121]
	v_mfma_f32_16x16x32_bf16 v[114:117], v[164:167], v[180:183], v[114:117]
	v_mfma_f32_16x16x32_bf16 v[102:105], v[144:147], v[188:191], v[102:105]
	v_mfma_f32_16x16x32_bf16 v[98:101], v[164:167], v[188:191], v[98:101]
	v_mfma_f32_16x16x32_bf16 v[86:89], v[144:147], v[196:199], v[86:89]
	v_mfma_f32_16x16x32_bf16 v[82:85], v[164:167], v[196:199], v[82:85]
	v_mfma_f32_16x16x32_bf16 v[126:129], v[160:163], v[176:179], v[126:129]
	v_mfma_f32_16x16x32_bf16 v[122:125], v[168:171], v[176:179], v[122:125]
	v_mfma_f32_16x16x32_bf16 v[118:121], v[160:163], v[184:187], v[118:121]
	v_mfma_f32_16x16x32_bf16 v[114:117], v[168:171], v[184:187], v[114:117]
	v_mfma_f32_16x16x32_bf16 v[102:105], v[160:163], v[192:195], v[102:105]
	v_mfma_f32_16x16x32_bf16 v[98:101], v[168:171], v[192:195], v[98:101]
	v_mfma_f32_16x16x32_bf16 v[86:89], v[160:163], v[200:203], v[86:89]
	v_mfma_f32_16x16x32_bf16 v[82:85], v[168:171], v[200:203], v[82:85]
	s_barrier
	s_add_i32 s24, 0, 0x1c000
	s_add_i32 s25, s53, s29
	v_add_u32_e32 v159, s24, v141
	v_lshl_add_u64 v[148:149], v[148:149], 0, s[20:21]
	s_mov_b32 m0, s25
	ds_read_b128 v[234:237], v159
	ds_read_b128 v[238:241], v159 offset:1024
	ds_read_b128 v[242:245], v159 offset:2048
	ds_read_b128 v[246:249], v159 offset:3072
	global_load_lds_dwordx4 v[148:149], off
	v_lshl_add_u64 v[148:149], v[204:205], 0, s[20:21]
	s_add_i32 m0, s25, 0x2000
	s_nop 0
	global_load_lds_dwordx4 v[148:149], off
	s_barrier
	s_waitcnt lgkmcnt(0)
	s_waitcnt lgkmcnt(0)
	v_mfma_f32_16x16x32_bf16 v[110:113], v[234:237], v[172:175], v[110:113]
	v_mfma_f32_16x16x32_bf16 v[106:109], v[242:245], v[172:175], v[106:109]
	v_mfma_f32_16x16x32_bf16 v[94:97], v[234:237], v[180:183], v[94:97]
	v_mfma_f32_16x16x32_bf16 v[90:93], v[242:245], v[180:183], v[90:93]
	v_mfma_f32_16x16x32_bf16 v[78:81], v[234:237], v[188:191], v[78:81]
	v_mfma_f32_16x16x32_bf16 v[74:77], v[242:245], v[188:191], v[74:77]
	v_mfma_f32_16x16x32_bf16 v[70:73], v[234:237], v[196:199], v[70:73]
	v_mfma_f32_16x16x32_bf16 v[66:69], v[242:245], v[196:199], v[66:69]
	v_mfma_f32_16x16x32_bf16 v[110:113], v[238:241], v[176:179], v[110:113]
	v_mfma_f32_16x16x32_bf16 v[106:109], v[246:249], v[176:179], v[106:109]
	v_mfma_f32_16x16x32_bf16 v[94:97], v[238:241], v[184:187], v[94:97]
	v_mfma_f32_16x16x32_bf16 v[90:93], v[246:249], v[184:187], v[90:93]
	v_mfma_f32_16x16x32_bf16 v[78:81], v[238:241], v[192:195], v[78:81]
	v_mfma_f32_16x16x32_bf16 v[74:77], v[246:249], v[192:195], v[74:77]
	v_mfma_f32_16x16x32_bf16 v[70:73], v[238:241], v[200:203], v[70:73]
	v_mfma_f32_16x16x32_bf16 v[66:69], v[246:249], v[200:203], v[66:69]
	s_mov_b32 m0, s35
	v_lshl_add_u64 v[148:149], v[250:251], 0, s[20:21]
	s_barrier
	ds_read_b128 v[172:175], v143 offset:49152
	ds_read_b128 v[176:179], v143 offset:50176
	ds_read_b128 v[180:183], v143 offset:51200
	ds_read_b128 v[184:187], v143 offset:52224
	ds_read_b128 v[188:191], v143 offset:53248
	ds_read_b128 v[192:195], v143 offset:54272
	ds_read_b128 v[196:199], v143 offset:55296
	ds_read_b128 v[200:203], v143 offset:56320
	global_load_lds_dwordx4 v[148:149], off
	v_lshl_add_u64 v[148:149], v[252:253], 0, s[20:21]
	s_mov_b32 m0, s38
	s_nop 0
	global_load_lds_dwordx4 v[148:149], off
	s_barrier
	s_waitcnt lgkmcnt(0)
	s_waitcnt lgkmcnt(0)
	v_mfma_f32_16x16x32_bf16 v[62:65], v[144:147], v[172:175], v[62:65]
	v_mfma_f32_16x16x32_bf16 v[58:61], v[164:167], v[172:175], v[58:61]
	v_mfma_f32_16x16x32_bf16 v[54:57], v[144:147], v[180:183], v[54:57]
	v_mfma_f32_16x16x32_bf16 v[50:53], v[164:167], v[180:183], v[50:53]
	v_mfma_f32_16x16x32_bf16 v[38:41], v[144:147], v[188:191], v[38:41]
	v_mfma_f32_16x16x32_bf16 v[34:37], v[164:167], v[188:191], v[34:37]
	v_mfma_f32_16x16x32_bf16 v[22:25], v[144:147], v[196:199], v[22:25]
	v_mfma_f32_16x16x32_bf16 v[18:21], v[164:167], v[196:199], v[18:21]
	v_mfma_f32_16x16x32_bf16 v[62:65], v[160:163], v[176:179], v[62:65]
	v_mfma_f32_16x16x32_bf16 v[58:61], v[168:171], v[176:179], v[58:61]
	v_mfma_f32_16x16x32_bf16 v[54:57], v[160:163], v[184:187], v[54:57]
	v_mfma_f32_16x16x32_bf16 v[50:53], v[168:171], v[184:187], v[50:53]
	v_mfma_f32_16x16x32_bf16 v[38:41], v[160:163], v[192:195], v[38:41]
	v_mfma_f32_16x16x32_bf16 v[34:37], v[168:171], v[192:195], v[34:37]
	v_mfma_f32_16x16x32_bf16 v[22:25], v[160:163], v[200:203], v[22:25]
	v_mfma_f32_16x16x32_bf16 v[18:21], v[168:171], v[200:203], v[18:21]
	s_barrier
	s_add_u32 s22, s22, 0x40080
	s_addc_u32 s23, s23, 0
	s_add_i32 s24, s24, s29
	v_lshl_add_u64 v[144:145], s[22:23], 0, v[0:1]
	s_mov_b32 m0, s24
	s_nop 0
	global_load_lds_dwordx4 v[144:145], off
	v_lshl_add_u64 v[144:145], s[22:23], 0, v[134:135]
	s_add_i32 m0, s24, 0x2000
	s_nop 0
	global_load_lds_dwordx4 v[144:145], off
	s_waitcnt vmcnt(6)
	s_barrier
	v_mfma_f32_16x16x32_bf16 v[46:49], v[234:237], v[172:175], v[46:49]
	v_mfma_f32_16x16x32_bf16 v[42:45], v[242:245], v[172:175], v[42:45]
	v_mfma_f32_16x16x32_bf16 v[30:33], v[234:237], v[180:183], v[30:33]
	v_mfma_f32_16x16x32_bf16 v[26:29], v[242:245], v[180:183], v[26:29]
	v_mfma_f32_16x16x32_bf16 v[14:17], v[234:237], v[188:191], v[14:17]
	v_mfma_f32_16x16x32_bf16 v[10:13], v[242:245], v[188:191], v[10:13]
	v_mfma_f32_16x16x32_bf16 v[6:9], v[234:237], v[196:199], v[6:9]
	v_mfma_f32_16x16x32_bf16 v[2:5], v[242:245], v[196:199], v[2:5]
	v_mfma_f32_16x16x32_bf16 v[46:49], v[238:241], v[176:179], v[46:49]
	v_mfma_f32_16x16x32_bf16 v[42:45], v[246:249], v[176:179], v[42:45]
	v_mfma_f32_16x16x32_bf16 v[30:33], v[238:241], v[184:187], v[30:33]
	v_mfma_f32_16x16x32_bf16 v[26:29], v[246:249], v[184:187], v[26:29]
	v_mfma_f32_16x16x32_bf16 v[14:17], v[238:241], v[192:195], v[14:17]
	v_mfma_f32_16x16x32_bf16 v[10:13], v[246:249], v[192:195], v[10:13]
	v_mfma_f32_16x16x32_bf16 v[6:9], v[238:241], v[200:203], v[6:9]
	v_mfma_f32_16x16x32_bf16 v[2:5], v[246:249], v[200:203], v[2:5]
	s_add_i32 s52, s52, 2
	s_add_u32 s50, s50, 0x100
	s_addc_u32 s51, s51, 0
	s_add_u32 s18, s18, 0x100
	s_addc_u32 s19, s19, 0
	s_cmp_gt_u32 s52, 13
	s_barrier
	s_cbranch_scc0 .LBB0_286
	v_lshl_add_u32 v144, s2, 8, v140
	v_lshl_or_b32 v146, s43, 8, v142
	v_ashrrev_i32_e32 v147, 31, v146
	v_ashrrev_i32_e32 v145, 31, v144
	v_lshl_add_u64 v[146:147], v[146:147], 1, s[46:47]
	v_lshlrev_b64 v[148:149], 11, v[144:145]
	v_lshl_add_u64 v[148:149], v[146:147], 0, v[148:149]
	s_mov_b64 s[18:19], 0x40000
	v_cvt_pk_bf16_f32 v62, v62, v63
	v_cvt_pk_bf16_f32 v63, v64, v65
	v_cvt_pk_bf16_f32 v64, v58, v59
	v_add_co_u32_e32 v58, vcc, s79, v148
	v_cvt_pk_bf16_f32 v70, v70, v71
	v_cvt_pk_bf16_f32 v71, v72, v73
	v_cvt_pk_bf16_f32 v72, v66, v67
	v_lshl_add_u64 v[66:67], v[148:149], 0, s[18:19]
	v_addc_co_u32_e32 v59, vcc, 0, v149, vcc
	v_cvt_pk_bf16_f32 v46, v46, v47
	v_cvt_pk_bf16_f32 v47, v48, v49
	v_cvt_pk_bf16_f32 v48, v42, v43
	v_cvt_pk_bf16_f32 v49, v44, v45
	global_store_dwordx4 v[66:67], v[46:49], off offset:256
	s_mov_b64 s[18:19], 0x48000
	v_cvt_pk_bf16_f32 v110, v110, v111
	v_add_co_u32_e32 v48, vcc, s91, v148
	v_cvt_pk_bf16_f32 v111, v112, v113
	v_cvt_pk_bf16_f32 v112, v106, v107
	v_or_b32_e32 v106, 16, v144
	v_lshl_add_u64 v[46:47], v[148:149], 0, s[18:19]
	v_addc_co_u32_e32 v49, vcc, 0, v149, vcc
	v_cvt_pk_bf16_f32 v30, v30, v31
	v_cvt_pk_bf16_f32 v31, v32, v33
	v_cvt_pk_bf16_f32 v32, v26, v27
	v_cvt_pk_bf16_f32 v33, v28, v29
	v_ashrrev_i32_e32 v107, 31, v106
	v_cvt_pk_bf16_f32 v94, v94, v95
	v_cvt_pk_bf16_f32 v95, v96, v97
	v_cvt_pk_bf16_f32 v96, v90, v91
	v_or_b32_e32 v90, 32, v144
	global_store_dwordx4 v[46:47], v[30:33], off offset:256
	s_mov_b64 s[18:19], 0x50000
	v_cvt_pk_bf16_f32 v113, v108, v109
	v_add_co_u32_e32 v32, vcc, s92, v148
	v_lshlrev_b64 v[106:107], 11, v[106:107]
	v_ashrrev_i32_e32 v91, 31, v90
	v_cvt_pk_bf16_f32 v78, v78, v79
	v_cvt_pk_bf16_f32 v79, v80, v81
	v_cvt_pk_bf16_f32 v80, v74, v75
	v_or_b32_e32 v74, 48, v144
	v_lshl_add_u64 v[30:31], v[148:149], 0, s[18:19]
	v_addc_co_u32_e32 v33, vcc, 0, v149, vcc
	v_cvt_pk_bf16_f32 v14, v14, v15
	v_cvt_pk_bf16_f32 v15, v16, v17
	v_cvt_pk_bf16_f32 v16, v10, v11
	v_cvt_pk_bf16_f32 v17, v12, v13
	global_store_dwordx4 v[148:149], v[110:113], off offset:256
	v_cvt_pk_bf16_f32 v97, v92, v93
	v_lshlrev_b64 v[90:91], 11, v[90:91]
	v_lshl_add_u64 v[110:111], v[146:147], 0, v[106:107]
	v_ashrrev_i32_e32 v75, 31, v74
	global_store_dwordx4 v[30:31], v[14:17], off offset:256
	global_store_dwordx4 v[110:111], v[94:97], off offset:256
	v_cvt_pk_bf16_f32 v81, v76, v77
	v_add_co_u32_e32 v16, vcc, 0x58000, v148
	v_lshl_add_u64 v[94:95], v[146:147], 0, v[90:91]
	v_lshlrev_b64 v[74:75], 11, v[74:75]
	s_mov_b64 s[18:19], 0x58000
	v_addc_co_u32_e32 v17, vcc, 0, v149, vcc
	v_readlane_b32 s54, v255, 3
	v_cvt_pk_bf16_f32 v126, v126, v127
	v_cvt_pk_bf16_f32 v127, v128, v129
	v_cvt_pk_bf16_f32 v128, v122, v123
	v_cvt_pk_bf16_f32 v129, v124, v125
	v_cvt_pk_bf16_f32 v106, v118, v119
	v_cvt_pk_bf16_f32 v107, v120, v121
	v_cvt_pk_bf16_f32 v108, v114, v115
	v_cvt_pk_bf16_f32 v109, v116, v117
	v_cvt_pk_bf16_f32 v90, v102, v103
	v_cvt_pk_bf16_f32 v91, v104, v105
	v_cvt_pk_bf16_f32 v92, v98, v99
	v_cvt_pk_bf16_f32 v93, v100, v101
	global_store_dwordx4 v[94:95], v[78:81], off offset:256
	v_cvt_pk_bf16_f32 v76, v82, v83
	v_cvt_pk_bf16_f32 v77, v84, v85
	v_lshl_add_u64 v[78:79], v[146:147], 0, v[74:75]
	v_cvt_pk_bf16_f32 v74, v86, v87
	v_cvt_pk_bf16_f32 v75, v88, v89
	v_cvt_pk_bf16_f32 v73, v68, v69
	v_cvt_pk_bf16_f32 v65, v60, v61
	v_cvt_pk_bf16_f32 v42, v54, v55
	v_cvt_pk_bf16_f32 v43, v56, v57
	v_cvt_pk_bf16_f32 v44, v50, v51
	v_cvt_pk_bf16_f32 v45, v52, v53
	v_cvt_pk_bf16_f32 v26, v38, v39
	v_cvt_pk_bf16_f32 v27, v40, v41
	v_cvt_pk_bf16_f32 v28, v34, v35
	v_cvt_pk_bf16_f32 v29, v36, v37
	v_lshl_add_u64 v[14:15], v[148:149], 0, s[18:19]
	v_cvt_pk_bf16_f32 v10, v22, v23
	v_cvt_pk_bf16_f32 v11, v24, v25
	v_cvt_pk_bf16_f32 v12, v18, v19
	v_cvt_pk_bf16_f32 v13, v20, v21
	v_cvt_pk_bf16_f32 v6, v6, v7
	v_cvt_pk_bf16_f32 v7, v8, v9
	v_cvt_pk_bf16_f32 v8, v2, v3
	v_cvt_pk_bf16_f32 v9, v4, v5
	s_and_b64 vcc, exec, s[40:41]
	s_mov_b32 s43, s8
	s_mov_b32 s2, s10
	s_mov_b64 s[18:19], s[14:15]
	s_mov_b64 s[22:23], s[12:13]
	v_readlane_b32 s55, v255, 4
	s_mov_b32 s56, s66
	global_store_dwordx4 v[148:149], v[126:129], off
	global_store_dwordx4 v[110:111], v[106:109], off
	global_store_dwordx4 v[94:95], v[90:93], off
	global_store_dwordx4 v[78:79], v[74:77], off
	global_store_dwordx4 v[78:79], v[70:73], off offset:256
	global_store_dwordx4 v[58:59], v[62:65], off
	global_store_dwordx4 v[48:49], v[42:45], off
	global_store_dwordx4 v[32:33], v[26:29], off
	global_store_dwordx4 v[16:17], v[10:13], off
	global_store_dwordx4 v[14:15], v[6:9], off offset:256
	s_cbranch_vccz .LBB0_279
	s_waitcnt vmcnt(0)
	s_setprio 0
	s_cmpk_gt_u32 s1, 0xff
	s_cbranch_scc1 .LBB0_290
	s_barrier

.LBB0_664:
	s_and_b64 vcc, exec, s[2:3]
	s_cbranch_vccz .LBB0_677
	s_cmpk_gt_i32 s0, 0x62f
	v_readfirstlane_b32 s1, v158
	s_cbranch_scc1 .LBB0_677
	v_lshlrev_b32_e32 v0, 4, v158
	s_waitcnt vmcnt(0)
	v_add_u32_e32 v2, 0x2000, v0
	v_ashrrev_i32_e32 v3, 31, v2
	v_lshrrev_b32_e32 v3, 22, v3
	v_add_u32_e32 v3, v2, v3
	v_ashrrev_i32_e32 v10, 10, v3
	v_mul_i32_i24_e32 v3, 0x400, v10
	v_sub_u32_e32 v2, v2, v3
	v_lshrrev_b32_e32 v3, 4, v2
	v_bitop3_b32 v2, v3, v2, 32 bitop3:0x6c
	s_load_dwordx2 s[2:3], s[54:55], 0x108
	v_ashrrev_i32_e32 v3, 31, v2
	v_lshrrev_b32_e32 v3, 26, v3
	v_add_u32_e32 v3, v2, v3
	v_lshlrev_b32_e32 v4, 3, v10
	s_mov_b32 s10, s44
	v_ashrrev_i32_e32 v11, 6, v3
	v_and_b32_e32 v4, -16, v4
	s_mul_i32 s9, s10, 0x600000
	v_add_u32_e32 v4, v11, v4
	s_load_dwordx4 s[44:47], s[54:55], 0x158
	s_waitcnt lgkmcnt(0)
	s_add_u32 s26, s2, s9
	v_and_b32_e32 v5, 3, v11
	s_mov_b32 s2, 0x1fffe0
	v_lshrrev_b32_e32 v6, 2, v4
	v_lshlrev_b32_e32 v7, 1, v4
	v_and_b32_e32 v3, 0xc0, v3
	v_and_or_b32 v5, v4, s2, v5
	v_and_b32_e32 v6, 4, v6
	v_and_b32_e32 v7, 24, v7
	v_sub_u32_e32 v2, v2, v3
	v_or3_b32 v5, v5, v6, v7
	v_lshlrev_b32_e32 v6, 5, v10
	v_ashrrev_i16_sdwa v2, v207, sext(v2) dst_sel:DWORD dst_unused:UNUSED_PAD src0_sel:DWORD src1_sel:BYTE_0
	v_and_b32_e32 v6, 32, v6
	v_bfe_i32 v12, v2, 0, 16
	v_add_lshl_u32 v2, v6, v12, 1
	v_lshl_add_u32 v130, v5, 11, v2
	v_lshl_add_u32 v132, v4, 11, v2
	v_bfe_i32 v2, v158, 27, 1
	v_lshrrev_b32_e32 v2, 22, v2
	v_add_u32_e32 v2, v0, v2
	v_and_b32_e32 v2, 0xfffffc00, v2
	v_sub_u32_e32 v0, v0, v2
	v_lshrrev_b32_e32 v2, 4, v0
	v_bitop3_b32 v2, v2, v0, 32 bitop3:0x6c
	v_ashrrev_i32_e32 v0, 31, v0
	v_lshrrev_b32_e32 v0, 26, v0
	v_add_u32_e32 v0, v2, v0
	v_ashrrev_i32_e32 v13, 6, v0
	v_ashrrev_i32_e32 v0, 31, v158
	v_lshrrev_b32_e32 v0, 26, v0
	v_add_u32_e32 v0, v158, v0
	v_ashrrev_i32_e32 v14, 6, v0
	v_lshlrev_b32_e32 v0, 3, v14
	s_mul_hi_i32 s8, s10, 0x600000
	v_and_b32_e32 v0, -16, v0
	s_addc_u32 s27, s3, s8
	v_add_u32_e32 v3, v13, v0
	v_and_b32_e32 v0, 3, v13
	s_ashr_i32 s29, s0, 31
	v_and_or_b32 v0, v3, s2, v0
	s_lshr_b32 s2, s29, 29
	s_add_i32 s2, s0, s2
	s_ashr_i32 s10, s1, 6
	s_ashr_i32 s3, s2, 3
	s_and_b32 s2, s2, -8
	s_ashr_i32 s9, s1, 8
	s_lshl_b32 s28, s10, 10
	s_sub_i32 s2, s0, s2
	s_mov_b32 s59, s57
	s_cmp_lt_i32 s2, 0
	s_movk_i32 s57, 0xc7
	s_cselect_b32 s8, s57, 0xc6
	s_mul_i32 s2, s8, s2
	s_add_i32 s2, s2, s3
	s_mul_hi_i32 s3, s2, 0x2aaaaaab
	v_lshrrev_b32_e32 v4, 2, v3
	v_lshlrev_b32_e32 v5, 1, v3
	s_lshr_b32 s8, s3, 31
	s_ashr_i32 s3, s3, 4
	v_and_b32_e32 v4, 4, v4
	v_and_b32_e32 v5, 24, v5
	s_add_i32 s3, s3, s8
	v_or3_b32 v0, v0, v4, v5
	v_mul_i32_i24_e32 v5, 64, v13
	s_lshl_b32 s11, s3, 3
	v_sub_u32_e32 v2, v2, v5
	s_sub_i32 s8, 0x84, s11
	v_lshlrev_b32_e32 v4, 5, v14
	v_ashrrev_i16_sdwa v2, v207, sext(v2) dst_sel:DWORD dst_unused:UNUSED_PAD src0_sel:DWORD src1_sel:BYTE_0
	s_min_u32 s12, s8, 8
	s_mulk_i32 s3, 0x60
	v_and_b32_e32 v4, 32, v4
	v_bfe_i32 v15, v2, 0, 16
	s_sub_i32 s13, s2, s3
	v_cvt_f32_ubyte0_e32 v5, s12
	v_add_lshl_u32 v2, v4, v15, 1
	v_cvt_f32_i32_e32 v4, s13
	v_rcp_iflag_f32_e32 v6, v5
	v_lshl_add_u32 v0, v0, 11, v2
	v_lshl_add_u32 v134, v3, 11, v2
	s_ashr_i32 s2, s13, 30
	v_mul_f32_e32 v2, v4, v6
	v_trunc_f32_e32 v2, v2
	v_fma_f32 v3, -v2, v5, v4
	v_cvt_i32_f32_e32 v2, v2
	s_or_b32 s8, s2, 1
	v_cmp_ge_f32_e64 s[2:3], |v3|, v5
	s_and_b64 s[2:3], s[2:3], exec
	s_cselect_b32 s2, s8, 0
	v_readfirstlane_b32 s3, v2
	s_add_i32 s8, s3, s2
	s_mul_i32 s2, s8, s12
	s_sub_i32 s2, s13, s2
	s_sext_i32_i8 s2, s2
	s_add_i32 s2, s11, s2
	s_ashr_i32 s3, s2, 31
	s_bfe_i64 s[14:15], s[8:9], 0x80000
	s_lshl_b64 s[12:13], s[2:3], 19
	s_lshl_b64 s[14:15], s[14:15], 19
	s_add_u32 s18, s26, s14
	s_addc_u32 s19, s27, s15
	s_add_i32 s3, s28, 0
	s_add_i32 m0, s3, 0x10000
	v_mov_b32_e32 v131, v1
	global_load_lds_dwordx4 v0, s[18:19]
	s_add_i32 m0, s3, 0x12000
	s_add_u32 s22, s44, s12
	global_load_lds_dwordx4 v130, s[18:19]
	s_addc_u32 s23, s45, s13
	s_mov_b32 m0, s3
	s_add_i32 s30, s3, 0x2000
	global_load_lds_dwordx4 v134, s[22:23]
	s_mov_b32 m0, s30
	s_add_u32 s12, s18, 0x40000
	global_load_lds_dwordx4 v132, s[22:23]
	s_addc_u32 s13, s19, 0
	s_add_i32 m0, s3, 0x14000
	v_mov_b32_e32 v135, v1
	global_load_lds_dwordx4 v0, s[12:13]
	s_add_i32 m0, s3, 0x16000
	v_mov_b32_e32 v133, v1
	global_load_lds_dwordx4 v130, s[12:13]
	s_add_u32 s12, s22, 0x40000
	s_addc_u32 s13, s23, 0
	s_add_i32 s31, s3, 0x4000
	s_mov_b32 m0, s31
	s_add_i32 s34, s3, 0x6000
	global_load_lds_dwordx4 v134, s[12:13]
	s_mov_b32 m0, s34
	s_mov_b32 s60, s56
	global_load_lds_dwordx4 v132, s[12:13]
	v_lshl_add_u64 v[8:9], s[18:19], 0, v[0:1]
	v_lshl_add_u64 v[6:7], s[18:19], 0, v[130:131]
	v_lshl_add_u64 v[4:5], s[22:23], 0, v[134:135]
	s_cmp_lg_u32 s9, 1
	v_lshl_add_u64 v[2:3], s[22:23], 0, v[132:133]
	s_cbranch_scc1 .LBB0_668
	s_barrier
	s_setprio 1

.LBB0_672:
	s_add_u32 s22, s18, 0xfffc0080
	s_addc_u32 s23, s19, -1
	s_add_i32 s53, 0, 0x10000
	v_add_u32_e32 v148, s53, v141
	ds_read_b128 v[144:147], v148
	ds_read_b128 v[160:163], v148 offset:1024
	ds_read_b128 v[164:167], v148 offset:2048
	ds_read_b128 v[168:171], v148 offset:3072
	s_cmp_eq_u32 s52, 12
	s_cselect_b32 s25, s11, s23
	s_cselect_b32 s24, s48, s22
	s_cselect_b32 s23, s9, s51
	s_cselect_b32 s22, s49, s50
	v_lshl_add_u64 v[148:149], s[18:19], 0, v[138:139]
	s_add_i32 m0, s3, 0xc000
	ds_read_b128 v[172:175], v143
	ds_read_b128 v[176:179], v143 offset:1024
	ds_read_b128 v[180:183], v143 offset:2048
	ds_read_b128 v[184:187], v143 offset:3072
	ds_read_b128 v[188:191], v143 offset:4096
	ds_read_b128 v[192:195], v143 offset:5120
	ds_read_b128 v[196:199], v143 offset:6144
	ds_read_b128 v[200:203], v143 offset:7168
	global_load_lds_dwordx4 v[148:149], off
	v_lshl_add_u64 v[148:149], s[18:19], 0, v[136:137]
	s_add_i32 m0, s3, 0xe000
	s_nop 0
	global_load_lds_dwordx4 v[148:149], off
	s_waitcnt lgkmcnt(8)
	s_barrier
	s_waitcnt lgkmcnt(0)
	s_waitcnt lgkmcnt(0)
	v_mfma_f32_16x16x32_bf16 v[126:129], v[144:147], v[172:175], v[126:129]
	v_mfma_f32_16x16x32_bf16 v[122:125], v[164:167], v[172:175], v[122:125]
	v_mfma_f32_16x16x32_bf16 v[118:121], v[144:147], v[180:183], v[118:121]
	v_mfma_f32_16x16x32_bf16 v[114:117], v[164:167], v[180:183], v[114:117]
	v_mfma_f32_16x16x32_bf16 v[102:105], v[144:147], v[188:191], v[102:105]
	v_mfma_f32_16x16x32_bf16 v[98:101], v[164:167], v[188:191], v[98:101]
	v_mfma_f32_16x16x32_bf16 v[86:89], v[144:147], v[196:199], v[86:89]
	v_mfma_f32_16x16x32_bf16 v[82:85], v[164:167], v[196:199], v[82:85]
	v_mfma_f32_16x16x32_bf16 v[126:129], v[160:163], v[176:179], v[126:129]
	v_mfma_f32_16x16x32_bf16 v[122:125], v[168:171], v[176:179], v[122:125]
	v_mfma_f32_16x16x32_bf16 v[118:121], v[160:163], v[184:187], v[118:121]
	v_mfma_f32_16x16x32_bf16 v[114:117], v[168:171], v[184:187], v[114:117]
	v_mfma_f32_16x16x32_bf16 v[102:105], v[160:163], v[192:195], v[102:105]
	v_mfma_f32_16x16x32_bf16 v[98:101], v[168:171], v[192:195], v[98:101]
	v_mfma_f32_16x16x32_bf16 v[86:89], v[160:163], v[200:203], v[86:89]
	v_mfma_f32_16x16x32_bf16 v[82:85], v[168:171], v[200:203], v[82:85]
	s_barrier
	s_add_i32 s56, 0, 0x14000
	v_add_u32_e32 v148, s56, v141
	s_add_i32 s53, s53, s28
	ds_read_b128 v[234:237], v148
	ds_read_b128 v[238:241], v148 offset:1024
	ds_read_b128 v[242:245], v148 offset:2048
	ds_read_b128 v[246:249], v148 offset:3072
	v_lshl_add_u64 v[148:149], s[22:23], 0, v[0:1]
	s_mov_b32 m0, s53
	v_lshl_add_u64 v[204:205], s[22:23], 0, v[130:131]
	global_load_lds_dwordx4 v[148:149], off
	s_add_i32 m0, s53, 0x2000
	s_nop 0
	global_load_lds_dwordx4 v[204:205], off
	s_barrier
	s_waitcnt lgkmcnt(0)
	s_waitcnt lgkmcnt(0)
	v_mfma_f32_16x16x32_bf16 v[110:113], v[234:237], v[172:175], v[110:113]
	v_mfma_f32_16x16x32_bf16 v[106:109], v[242:245], v[172:175], v[106:109]
	v_mfma_f32_16x16x32_bf16 v[94:97], v[234:237], v[180:183], v[94:97]
	v_mfma_f32_16x16x32_bf16 v[90:93], v[242:245], v[180:183], v[90:93]
	v_mfma_f32_16x16x32_bf16 v[78:81], v[234:237], v[188:191], v[78:81]
	v_mfma_f32_16x16x32_bf16 v[74:77], v[242:245], v[188:191], v[74:77]
	v_mfma_f32_16x16x32_bf16 v[70:73], v[234:237], v[196:199], v[70:73]
	v_mfma_f32_16x16x32_bf16 v[66:69], v[242:245], v[196:199], v[66:69]
	v_mfma_f32_16x16x32_bf16 v[110:113], v[238:241], v[176:179], v[110:113]
	v_mfma_f32_16x16x32_bf16 v[106:109], v[246:249], v[176:179], v[106:109]
	v_mfma_f32_16x16x32_bf16 v[94:97], v[238:241], v[184:187], v[94:97]
	v_mfma_f32_16x16x32_bf16 v[90:93], v[246:249], v[184:187], v[90:93]
	v_mfma_f32_16x16x32_bf16 v[78:81], v[238:241], v[192:195], v[78:81]
	v_mfma_f32_16x16x32_bf16 v[74:77], v[246:249], v[192:195], v[74:77]
	v_mfma_f32_16x16x32_bf16 v[70:73], v[238:241], v[200:203], v[70:73]
	v_mfma_f32_16x16x32_bf16 v[66:69], v[246:249], v[200:203], v[66:69]
	s_mov_b32 m0, s3
	v_lshl_add_u64 v[250:251], s[24:25], 0, v[134:135]
	s_barrier
	ds_read_b128 v[172:175], v143 offset:16384
	ds_read_b128 v[176:179], v143 offset:17408
	ds_read_b128 v[180:183], v143 offset:18432
	ds_read_b128 v[184:187], v143 offset:19456
	ds_read_b128 v[188:191], v143 offset:20480
	ds_read_b128 v[192:195], v143 offset:21504
	ds_read_b128 v[196:199], v143 offset:22528
	ds_read_b128 v[200:203], v143 offset:23552
	global_load_lds_dwordx4 v[250:251], off
	v_lshl_add_u64 v[252:253], s[24:25], 0, v[132:133]
	s_mov_b32 m0, s30
	s_nop 0
	global_load_lds_dwordx4 v[252:253], off
	s_barrier
	s_waitcnt lgkmcnt(0)
	s_waitcnt lgkmcnt(0)
	v_mfma_f32_16x16x32_bf16 v[62:65], v[144:147], v[172:175], v[62:65]
	v_mfma_f32_16x16x32_bf16 v[58:61], v[164:167], v[172:175], v[58:61]
	v_mfma_f32_16x16x32_bf16 v[54:57], v[144:147], v[180:183], v[54:57]
	v_mfma_f32_16x16x32_bf16 v[50:53], v[164:167], v[180:183], v[50:53]
	v_mfma_f32_16x16x32_bf16 v[38:41], v[144:147], v[188:191], v[38:41]
	v_mfma_f32_16x16x32_bf16 v[34:37], v[164:167], v[188:191], v[34:37]
	v_mfma_f32_16x16x32_bf16 v[22:25], v[144:147], v[196:199], v[22:25]
	v_mfma_f32_16x16x32_bf16 v[18:21], v[164:167], v[196:199], v[18:21]
	v_mfma_f32_16x16x32_bf16 v[62:65], v[160:163], v[176:179], v[62:65]
	v_mfma_f32_16x16x32_bf16 v[58:61], v[168:171], v[176:179], v[58:61]
	v_mfma_f32_16x16x32_bf16 v[54:57], v[160:163], v[184:187], v[54:57]
	v_mfma_f32_16x16x32_bf16 v[50:53], v[168:171], v[184:187], v[50:53]
	v_mfma_f32_16x16x32_bf16 v[38:41], v[160:163], v[192:195], v[38:41]
	v_mfma_f32_16x16x32_bf16 v[34:37], v[168:171], v[192:195], v[34:37]
	v_mfma_f32_16x16x32_bf16 v[22:25], v[160:163], v[200:203], v[22:25]
	v_mfma_f32_16x16x32_bf16 v[18:21], v[168:171], v[200:203], v[18:21]
	s_barrier
	s_add_u32 s54, s22, 0x40000
	s_addc_u32 s55, s23, 0
	s_add_i32 s53, s56, s28
	v_lshl_add_u64 v[144:145], s[54:55], 0, v[0:1]
	s_mov_b32 m0, s53
	s_nop 0
	global_load_lds_dwordx4 v[144:145], off
	v_lshl_add_u64 v[144:145], s[54:55], 0, v[130:131]
	s_add_i32 m0, s53, 0x2000
	s_nop 0
	global_load_lds_dwordx4 v[144:145], off
	s_waitcnt vmcnt(6)
	s_barrier
	v_mfma_f32_16x16x32_bf16 v[46:49], v[234:237], v[172:175], v[46:49]
	v_mfma_f32_16x16x32_bf16 v[42:45], v[242:245], v[172:175], v[42:45]
	v_mfma_f32_16x16x32_bf16 v[30:33], v[234:237], v[180:183], v[30:33]
	v_mfma_f32_16x16x32_bf16 v[26:29], v[242:245], v[180:183], v[26:29]
	v_mfma_f32_16x16x32_bf16 v[14:17], v[234:237], v[188:191], v[14:17]
	v_mfma_f32_16x16x32_bf16 v[10:13], v[242:245], v[188:191], v[10:13]
	v_mfma_f32_16x16x32_bf16 v[6:9], v[234:237], v[196:199], v[6:9]
	v_mfma_f32_16x16x32_bf16 v[2:5], v[242:245], v[196:199], v[2:5]
	v_mfma_f32_16x16x32_bf16 v[46:49], v[238:241], v[176:179], v[46:49]
	v_mfma_f32_16x16x32_bf16 v[42:45], v[246:249], v[176:179], v[42:45]
	v_mfma_f32_16x16x32_bf16 v[30:33], v[238:241], v[184:187], v[30:33]
	v_mfma_f32_16x16x32_bf16 v[26:29], v[246:249], v[184:187], v[26:29]
	v_mfma_f32_16x16x32_bf16 v[14:17], v[238:241], v[192:195], v[14:17]
	v_mfma_f32_16x16x32_bf16 v[10:13], v[246:249], v[192:195], v[10:13]
	v_mfma_f32_16x16x32_bf16 v[6:9], v[238:241], v[200:203], v[6:9]
	v_mfma_f32_16x16x32_bf16 v[2:5], v[246:249], v[200:203], v[2:5]
	s_add_i32 s53, 0, 0x18000
	v_add_u32_e32 v159, s53, v141
	s_barrier
	ds_read_b128 v[144:147], v159
	ds_read_b128 v[160:163], v159 offset:1024
	ds_read_b128 v[164:167], v159 offset:2048
	ds_read_b128 v[168:171], v159 offset:3072
	s_add_u32 s24, s24, 0x40000
	s_addc_u32 s25, s25, 0
	s_mov_b32 m0, s31
	v_lshl_add_u64 v[234:235], s[24:25], 0, v[134:135]
	ds_read_b128 v[172:175], v143 offset:32768
	ds_read_b128 v[176:179], v143 offset:33792
	ds_read_b128 v[180:183], v143 offset:34816
	ds_read_b128 v[184:187], v143 offset:35840
	ds_read_b128 v[188:191], v143 offset:36864
	ds_read_b128 v[192:195], v143 offset:37888
	ds_read_b128 v[196:199], v143 offset:38912
	ds_read_b128 v[200:203], v143 offset:39936
	global_load_lds_dwordx4 v[234:235], off
	v_lshl_add_u64 v[234:235], s[24:25], 0, v[132:133]
	s_mov_b32 m0, s34
	s_nop 0
	global_load_lds_dwordx4 v[234:235], off
	s_waitcnt lgkmcnt(8)
	s_barrier
	s_waitcnt lgkmcnt(0)
	s_waitcnt lgkmcnt(0)
	v_mfma_f32_16x16x32_bf16 v[126:129], v[144:147], v[172:175], v[126:129]
	v_mfma_f32_16x16x32_bf16 v[122:125], v[164:167], v[172:175], v[122:125]
	v_mfma_f32_16x16x32_bf16 v[118:121], v[144:147], v[180:183], v[118:121]
	v_mfma_f32_16x16x32_bf16 v[114:117], v[164:167], v[180:183], v[114:117]
	v_mfma_f32_16x16x32_bf16 v[102:105], v[144:147], v[188:191], v[102:105]
	v_mfma_f32_16x16x32_bf16 v[98:101], v[164:167], v[188:191], v[98:101]
	v_mfma_f32_16x16x32_bf16 v[86:89], v[144:147], v[196:199], v[86:89]
	v_mfma_f32_16x16x32_bf16 v[82:85], v[164:167], v[196:199], v[82:85]
	v_mfma_f32_16x16x32_bf16 v[126:129], v[160:163], v[176:179], v[126:129]
	v_mfma_f32_16x16x32_bf16 v[122:125], v[168:171], v[176:179], v[122:125]
	v_mfma_f32_16x16x32_bf16 v[118:121], v[160:163], v[184:187], v[118:121]
	v_mfma_f32_16x16x32_bf16 v[114:117], v[168:171], v[184:187], v[114:117]
	v_mfma_f32_16x16x32_bf16 v[102:105], v[160:163], v[192:195], v[102:105]
	v_mfma_f32_16x16x32_bf16 v[98:101], v[168:171], v[192:195], v[98:101]
	v_mfma_f32_16x16x32_bf16 v[86:89], v[160:163], v[200:203], v[86:89]
	v_mfma_f32_16x16x32_bf16 v[82:85], v[168:171], v[200:203], v[82:85]
	s_barrier
	s_add_i32 s24, 0, 0x1c000
	s_add_i32 s25, s53, s28
	v_add_u32_e32 v159, s24, v141
	v_lshl_add_u64 v[148:149], v[148:149], 0, s[20:21]
	s_mov_b32 m0, s25
	ds_read_b128 v[234:237], v159
	ds_read_b128 v[238:241], v159 offset:1024
	ds_read_b128 v[242:245], v159 offset:2048
	ds_read_b128 v[246:249], v159 offset:3072
	global_load_lds_dwordx4 v[148:149], off
	v_lshl_add_u64 v[148:149], v[204:205], 0, s[20:21]
	s_add_i32 m0, s25, 0x2000
	s_nop 0
	global_load_lds_dwordx4 v[148:149], off
	s_barrier
	s_waitcnt lgkmcnt(0)
	s_waitcnt lgkmcnt(0)
	v_mfma_f32_16x16x32_bf16 v[110:113], v[234:237], v[172:175], v[110:113]
	v_mfma_f32_16x16x32_bf16 v[106:109], v[242:245], v[172:175], v[106:109]
	v_mfma_f32_16x16x32_bf16 v[94:97], v[234:237], v[180:183], v[94:97]
	v_mfma_f32_16x16x32_bf16 v[90:93], v[242:245], v[180:183], v[90:93]
	v_mfma_f32_16x16x32_bf16 v[78:81], v[234:237], v[188:191], v[78:81]
	v_mfma_f32_16x16x32_bf16 v[74:77], v[242:245], v[188:191], v[74:77]
	v_mfma_f32_16x16x32_bf16 v[70:73], v[234:237], v[196:199], v[70:73]
	v_mfma_f32_16x16x32_bf16 v[66:69], v[242:245], v[196:199], v[66:69]
	v_mfma_f32_16x16x32_bf16 v[110:113], v[238:241], v[176:179], v[110:113]
	v_mfma_f32_16x16x32_bf16 v[106:109], v[246:249], v[176:179], v[106:109]
	v_mfma_f32_16x16x32_bf16 v[94:97], v[238:241], v[184:187], v[94:97]
	v_mfma_f32_16x16x32_bf16 v[90:93], v[246:249], v[184:187], v[90:93]
	v_mfma_f32_16x16x32_bf16 v[78:81], v[238:241], v[192:195], v[78:81]
	v_mfma_f32_16x16x32_bf16 v[74:77], v[246:249], v[192:195], v[74:77]
	v_mfma_f32_16x16x32_bf16 v[70:73], v[238:241], v[200:203], v[70:73]
	v_mfma_f32_16x16x32_bf16 v[66:69], v[246:249], v[200:203], v[66:69]
	s_mov_b32 m0, s35
	v_lshl_add_u64 v[148:149], v[250:251], 0, s[20:21]
	s_barrier
	ds_read_b128 v[172:175], v143 offset:49152
	ds_read_b128 v[176:179], v143 offset:50176
	ds_read_b128 v[180:183], v143 offset:51200
	ds_read_b128 v[184:187], v143 offset:52224
	ds_read_b128 v[188:191], v143 offset:53248
	ds_read_b128 v[192:195], v143 offset:54272
	ds_read_b128 v[196:199], v143 offset:55296
	ds_read_b128 v[200:203], v143 offset:56320
	global_load_lds_dwordx4 v[148:149], off
	v_lshl_add_u64 v[148:149], v[252:253], 0, s[20:21]
	s_mov_b32 m0, s38
	s_nop 0
	global_load_lds_dwordx4 v[148:149], off
	s_barrier
	s_waitcnt lgkmcnt(0)
	s_waitcnt lgkmcnt(0)
	v_mfma_f32_16x16x32_bf16 v[62:65], v[144:147], v[172:175], v[62:65]
	v_mfma_f32_16x16x32_bf16 v[58:61], v[164:167], v[172:175], v[58:61]
	v_mfma_f32_16x16x32_bf16 v[54:57], v[144:147], v[180:183], v[54:57]
	v_mfma_f32_16x16x32_bf16 v[50:53], v[164:167], v[180:183], v[50:53]
	v_mfma_f32_16x16x32_bf16 v[38:41], v[144:147], v[188:191], v[38:41]
	v_mfma_f32_16x16x32_bf16 v[34:37], v[164:167], v[188:191], v[34:37]
	v_mfma_f32_16x16x32_bf16 v[22:25], v[144:147], v[196:199], v[22:25]
	v_mfma_f32_16x16x32_bf16 v[18:21], v[164:167], v[196:199], v[18:21]
	v_mfma_f32_16x16x32_bf16 v[62:65], v[160:163], v[176:179], v[62:65]
	v_mfma_f32_16x16x32_bf16 v[58:61], v[168:171], v[176:179], v[58:61]
	v_mfma_f32_16x16x32_bf16 v[54:57], v[160:163], v[184:187], v[54:57]
	v_mfma_f32_16x16x32_bf16 v[50:53], v[168:171], v[184:187], v[50:53]
	v_mfma_f32_16x16x32_bf16 v[38:41], v[160:163], v[192:195], v[38:41]
	v_mfma_f32_16x16x32_bf16 v[34:37], v[168:171], v[192:195], v[34:37]
	v_mfma_f32_16x16x32_bf16 v[22:25], v[160:163], v[200:203], v[22:25]
	v_mfma_f32_16x16x32_bf16 v[18:21], v[168:171], v[200:203], v[18:21]
	s_barrier
	s_add_u32 s22, s22, 0x40080
	s_addc_u32 s23, s23, 0
	s_add_i32 s24, s24, s28
	v_lshl_add_u64 v[144:145], s[22:23], 0, v[0:1]
	s_mov_b32 m0, s24
	s_nop 0
	global_load_lds_dwordx4 v[144:145], off
	v_lshl_add_u64 v[144:145], s[22:23], 0, v[130:131]
	s_add_i32 m0, s24, 0x2000
	s_nop 0
	global_load_lds_dwordx4 v[144:145], off
	s_waitcnt vmcnt(6)
	s_barrier
	v_mfma_f32_16x16x32_bf16 v[46:49], v[234:237], v[172:175], v[46:49]
	v_mfma_f32_16x16x32_bf16 v[42:45], v[242:245], v[172:175], v[42:45]
	v_mfma_f32_16x16x32_bf16 v[30:33], v[234:237], v[180:183], v[30:33]
	v_mfma_f32_16x16x32_bf16 v[26:29], v[242:245], v[180:183], v[26:29]
	v_mfma_f32_16x16x32_bf16 v[14:17], v[234:237], v[188:191], v[14:17]
	v_mfma_f32_16x16x32_bf16 v[10:13], v[242:245], v[188:191], v[10:13]
	v_mfma_f32_16x16x32_bf16 v[6:9], v[234:237], v[196:199], v[6:9]
	v_mfma_f32_16x16x32_bf16 v[2:5], v[242:245], v[196:199], v[2:5]
	v_mfma_f32_16x16x32_bf16 v[46:49], v[238:241], v[176:179], v[46:49]
	v_mfma_f32_16x16x32_bf16 v[42:45], v[246:249], v[176:179], v[42:45]
	v_mfma_f32_16x16x32_bf16 v[30:33], v[238:241], v[184:187], v[30:33]
	v_mfma_f32_16x16x32_bf16 v[26:29], v[246:249], v[184:187], v[26:29]
	v_mfma_f32_16x16x32_bf16 v[14:17], v[238:241], v[192:195], v[14:17]
	v_mfma_f32_16x16x32_bf16 v[10:13], v[246:249], v[192:195], v[10:13]
	v_mfma_f32_16x16x32_bf16 v[6:9], v[238:241], v[200:203], v[6:9]
	v_mfma_f32_16x16x32_bf16 v[2:5], v[246:249], v[200:203], v[2:5]
	s_add_i32 s52, s52, 2
	s_add_u32 s50, s50, 0x100
	s_addc_u32 s51, s51, 0
	s_add_u32 s18, s18, 0x100
	s_addc_u32 s19, s19, 0
	s_cmp_gt_u32 s52, 13
	s_barrier
	s_cbranch_scc0 .LBB0_672
	v_lshl_or_b32 v144, s43, 8, v142
	v_lshl_add_u32 v148, s2, 8, v140
	v_ashrrev_i32_e32 v145, 31, v144
	v_lshl_add_u64 v[144:145], v[144:145], 1, s[46:47]
	v_cvt_pk_bf16_f32 v70, v70, v71
	v_cvt_pk_bf16_f32 v71, v72, v73
	v_cvt_pk_bf16_f32 v72, v66, v67
	v_add_u32_e32 v66, 0x80, v148
	v_mad_i64_i32 v[146:147], s[18:19], v148, s74, v[144:145]
	v_cvt_pk_bf16_f32 v110, v110, v111
	v_cvt_pk_bf16_f32 v111, v112, v113
	v_cvt_pk_bf16_f32 v112, v106, v107
	v_cvt_pk_bf16_f32 v113, v108, v109
	v_or_b32_e32 v106, 16, v148
	v_mad_i64_i32 v[66:67], s[18:19], v66, s74, v[144:145]
	v_cvt_pk_bf16_f32 v46, v46, v47
	v_cvt_pk_bf16_f32 v47, v48, v49
	v_cvt_pk_bf16_f32 v48, v42, v43
	v_cvt_pk_bf16_f32 v49, v44, v45
	v_add_u32_e32 v42, 0x90, v148
	global_store_dwordx4 v[146:147], v[110:113], off offset:256
	v_cvt_pk_bf16_f32 v94, v94, v95
	v_cvt_pk_bf16_f32 v95, v96, v97
	v_mad_i64_i32 v[110:111], s[18:19], v106, s74, v[144:145]
	v_cvt_pk_bf16_f32 v96, v90, v91
	v_cvt_pk_bf16_f32 v97, v92, v93
	v_or_b32_e32 v90, 32, v148
	global_store_dwordx4 v[66:67], v[46:49], off offset:256
	v_cvt_pk_bf16_f32 v30, v30, v31
	v_cvt_pk_bf16_f32 v31, v32, v33
	v_mad_i64_i32 v[46:47], s[18:19], v42, s74, v[144:145]
	v_cvt_pk_bf16_f32 v32, v26, v27
	v_cvt_pk_bf16_f32 v33, v28, v29
	v_add_u32_e32 v26, 0xa0, v148
	global_store_dwordx4 v[110:111], v[94:97], off offset:256
	v_cvt_pk_bf16_f32 v78, v78, v79
	v_cvt_pk_bf16_f32 v79, v80, v81
	v_mad_i64_i32 v[94:95], s[18:19], v90, s74, v[144:145]
	v_cvt_pk_bf16_f32 v80, v74, v75
	v_cvt_pk_bf16_f32 v81, v76, v77
	v_or_b32_e32 v74, 48, v148
	global_store_dwordx4 v[46:47], v[30:33], off offset:256
	v_cvt_pk_bf16_f32 v14, v14, v15
	v_cvt_pk_bf16_f32 v15, v16, v17
	v_mad_i64_i32 v[30:31], s[18:19], v26, s74, v[144:145]
	v_cvt_pk_bf16_f32 v16, v10, v11
	v_cvt_pk_bf16_f32 v17, v12, v13
	v_add_u32_e32 v10, 0xb0, v148
	global_store_dwordx4 v[94:95], v[78:81], off offset:256
	global_store_dwordx4 v[30:31], v[14:17], off offset:256
	v_cvt_pk_bf16_f32 v126, v126, v127
	v_mad_i64_i32 v[78:79], s[18:19], v74, s74, v[144:145]
	v_mad_i64_i32 v[14:15], s[18:19], v10, s74, v[144:145]
	v_cvt_pk_bf16_f32 v127, v128, v129
	v_cvt_pk_bf16_f32 v128, v122, v123
	v_cvt_pk_bf16_f32 v129, v124, v125
	v_cvt_pk_bf16_f32 v106, v118, v119
	v_cvt_pk_bf16_f32 v107, v120, v121
	v_cvt_pk_bf16_f32 v108, v114, v115
	v_cvt_pk_bf16_f32 v109, v116, v117
	v_cvt_pk_bf16_f32 v90, v102, v103
	v_cvt_pk_bf16_f32 v91, v104, v105
	v_cvt_pk_bf16_f32 v92, v98, v99
	v_cvt_pk_bf16_f32 v93, v100, v101
	v_cvt_pk_bf16_f32 v74, v86, v87
	v_cvt_pk_bf16_f32 v75, v88, v89
	v_cvt_pk_bf16_f32 v76, v82, v83
	v_cvt_pk_bf16_f32 v77, v84, v85
	v_cvt_pk_bf16_f32 v73, v68, v69
	v_cvt_pk_bf16_f32 v62, v62, v63
	v_cvt_pk_bf16_f32 v63, v64, v65
	v_cvt_pk_bf16_f32 v64, v58, v59
	v_cvt_pk_bf16_f32 v65, v60, v61
	v_cvt_pk_bf16_f32 v42, v54, v55
	v_cvt_pk_bf16_f32 v43, v56, v57
	v_cvt_pk_bf16_f32 v44, v50, v51
	v_cvt_pk_bf16_f32 v45, v52, v53
	v_cvt_pk_bf16_f32 v26, v38, v39
	v_cvt_pk_bf16_f32 v27, v40, v41
	v_cvt_pk_bf16_f32 v28, v34, v35
	v_cvt_pk_bf16_f32 v29, v36, v37
	v_cvt_pk_bf16_f32 v10, v22, v23
	v_cvt_pk_bf16_f32 v11, v24, v25
	v_cvt_pk_bf16_f32 v12, v18, v19
	v_cvt_pk_bf16_f32 v13, v20, v21
	v_cvt_pk_bf16_f32 v6, v6, v7
	v_cvt_pk_bf16_f32 v7, v8, v9
	v_cvt_pk_bf16_f32 v8, v2, v3
	v_cvt_pk_bf16_f32 v9, v4, v5
	s_and_b64 vcc, exec, s[40:41]
	s_mov_b32 s43, s8
	s_mov_b32 s2, s10
	s_mov_b64 s[18:19], s[14:15]
	s_mov_b64 s[22:23], s[12:13]
	global_store_dwordx4 v[146:147], v[126:129], off
	global_store_dwordx4 v[110:111], v[106:109], off
	global_store_dwordx4 v[94:95], v[90:93], off
	global_store_dwordx4 v[78:79], v[74:77], off
	global_store_dwordx4 v[78:79], v[70:73], off offset:256
	global_store_dwordx4 v[66:67], v[62:65], off
	global_store_dwordx4 v[46:47], v[42:45], off
	global_store_dwordx4 v[30:31], v[26:29], off
	global_store_dwordx4 v[14:15], v[10:13], off
	global_store_dwordx4 v[14:15], v[6:9], off offset:256
	s_cbranch_vccz .LBB0_669
	s_waitcnt vmcnt(0)
	s_setprio 0
	s_cmpk_gt_u32 s1, 0xff
	s_cbranch_scc1 .LBB0_676
	s_barrier
